# GEMM K-loops: per-phase s_setprio flips removed, one static s_setprio 1 for waves 4-7 per unit, reset at phase end
# speedup vs baseline: 1.0372x; 1.0064x over previous
; #define PG8_STAGE(bufoff, gbase, voff) do { _Pragma("unroll") for (int _i = 0; _i < 2; ++_i) \
;         __builtin_amdgcn_global_load_lds((const unsigned*)((const char*)(gbase) + (voff)[_i]), (PG8_LAS unsigned*)(lds + (bufoff) + ldsw + _i * 8192), 16, 0, 0); } while (0)
; #define PG8_LDA(dst, b, h) do { _Pragma("unroll") for (int m = 0; m < 4; ++m) _Pragma("unroll") for (int k = 0; k < 2; ++k) dst[m][k] = *(const PG8_LAS bf16x8*)(lds + PG8_SA(b, h) + aoff + m * 2048 + k * 1024); } while (0)
; #define PG8_LDB(dst, b, h) do { _Pragma("unroll") for (int n = 0; n < 2; ++n) _Pragma("unroll") for (int k = 0; k < 2; ++k) dst[n][k] = *(const PG8_LAS bf16x8*)(lds + PG8_SB(b, h) + boff + n * 2048 + k * 1024); } while (0)
; #define PG8_WAIT_L(n) asm volatile("s_waitcnt lgkmcnt(" #n ")" ::: "memory")
; #define PG8_BAR __builtin_amdgcn_s_barrier()
; #define PG8_SCHED __builtin_amdgcn_sched_barrier(0)
; template <class Epi, class Sched>
; __device__ __forceinline__ void gemm_phase(PG8_LAS unsigned char* lds, const Gemm g, const Sched& S, const Epi& E) {
;     ...
;     for (;;) {
;         const bool has_next = S.next(ui + 1, nxt);
;         const char* nA = has_next ? (const char*)g.A + (size_t)nxt.pm * tstep : cA; const char* nB = has_next ? (const char*)g.Bt + (size_t)nxt.pn * tstep : cB;
;         for (int t = 0; t < nt; t += 2) {
;             const bool last = (t == nt - 2);
;             const char* a1 = cA + (size_t)(t + 1) * kstep;
;             const char* a2 = last ? nA : cA + (size_t)(t + 2) * kstep; const char* b2 = last ? nB : cB + (size_t)(t + 2) * kstep;
;             const char* a3 = a2 + kstep; const char* b3 = b2 + kstep;
;             if (last && has_next) S.a_ready(nxt);
;             PG8_LDB(B0, 0, 0); PG8_SCHED; PG8_LDA(At, 0, 0); PG8_STAGE(PG8_SA(1, 1), a1 + hstep, voffA);
;             PG8_WAIT_L(8); PG8_BAR; PG8_WAIT_L(0); PG8_MMA(0, 0, At, B0); PG8_BAR; PG8_SCHED;
;     ...
; #pragma unroll
;         for (int a = 0; a < 2; ++a)
; #pragma unroll
;             for (int b = 0; b < 2; ++b)
; #pragma unroll
;                 for (int m = 0; m < 4; ++m)
; #pragma unroll
;                     for (int n = 0; n < 2; ++n) acc[a][b][m][n] = (f32x4){0.f, 0.f, 0.f, 0.f};
;         cur = nxt; cA = nA; cB = nB; ++ui;
.LBB0_46:
	v_mov_b64_e32 v[0:1], s[54:55]
	s_ashr_i32 s41, s40, 31
	v_cmp_lt_i64_e32 vcc, s[0:1], v[0:1]
	s_lshl_b64 s[0:1], s[40:41], 21
	v_readlane_b32 s42, v251, 49
	v_readlane_b32 s43, v251, 50
	s_add_u32 s44, s42, s0
	s_addc_u32 s45, s43, s1
	s_and_b64 s[0:1], vcc, exec
	s_cselect_b32 s41, s45, s51
	s_cselect_b32 s68, s44, s50
	s_ashr_i32 s39, s38, 31
	s_lshl_b64 s[0:1], s[38:39], 21
	v_readlane_b32 s42, v251, 9
	v_readlane_b32 s43, v251, 10
	s_add_u32 s46, s42, s0
	s_addc_u32 s47, s43, s1
	s_and_b64 s[0:1], vcc, exec
	s_cselect_b32 s39, s47, s53
	s_cselect_b32 s69, s46, s52
	s_add_u32 s70, s52, 0x100
	v_mov_b32_e32 v0, 0
	s_addc_u32 s71, s53, 0
	s_mov_b32 s94, -2
	v_mov_b32_e32 v1, v0
	v_mov_b32_e32 v2, v0
	v_mov_b32_e32 v3, v0
	v_mov_b32_e32 v4, v0
	v_mov_b32_e32 v5, v0
	v_mov_b32_e32 v6, v0
	v_mov_b32_e32 v7, v0
	v_mov_b32_e32 v8, v0
	v_mov_b32_e32 v9, v0
	v_mov_b32_e32 v10, v0
	v_mov_b32_e32 v11, v0
	v_mov_b32_e32 v16, v0
	v_mov_b32_e32 v17, v0
	v_mov_b32_e32 v18, v0
	v_mov_b32_e32 v19, v0
	v_mov_b32_e32 v24, v0
	v_mov_b32_e32 v25, v0
	v_mov_b32_e32 v26, v0
	v_mov_b32_e32 v27, v0
	v_mov_b32_e32 v32, v0
	v_mov_b32_e32 v33, v0
	v_mov_b32_e32 v34, v0
	v_mov_b32_e32 v35, v0
	v_mov_b32_e32 v40, v0
	v_mov_b32_e32 v41, v0
	v_mov_b32_e32 v42, v0
	v_mov_b32_e32 v43, v0
	v_mov_b32_e32 v48, v0
	v_mov_b32_e32 v49, v0
	v_mov_b32_e32 v50, v0
	v_mov_b32_e32 v51, v0
	v_mov_b32_e32 v12, v0
	v_mov_b32_e32 v13, v0
	v_mov_b32_e32 v14, v0
	v_mov_b32_e32 v15, v0
	v_mov_b32_e32 v20, v0
	v_mov_b32_e32 v21, v0
	v_mov_b32_e32 v22, v0
	v_mov_b32_e32 v23, v0
	v_mov_b32_e32 v28, v0
	v_mov_b32_e32 v29, v0
	v_mov_b32_e32 v30, v0
	v_mov_b32_e32 v31, v0
	v_mov_b32_e32 v36, v0
	v_mov_b32_e32 v37, v0
	v_mov_b32_e32 v38, v0
	v_mov_b32_e32 v39, v0
	v_mov_b32_e32 v44, v0
	v_mov_b32_e32 v45, v0
	v_mov_b32_e32 v46, v0
	v_mov_b32_e32 v47, v0
	v_mov_b32_e32 v52, v0
	v_mov_b32_e32 v53, v0
	v_mov_b32_e32 v54, v0
	v_mov_b32_e32 v55, v0
	v_mov_b32_e32 v56, v0
	v_mov_b32_e32 v57, v0
	v_mov_b32_e32 v58, v0
	v_mov_b32_e32 v59, v0
	v_mov_b32_e32 v60, v0
	v_mov_b32_e32 v61, v0
	v_mov_b32_e32 v62, v0
	v_mov_b32_e32 v63, v0
	v_mov_b32_e32 v64, v0
	v_mov_b32_e32 v65, v0
	v_mov_b32_e32 v66, v0
	v_mov_b32_e32 v67, v0
	v_mov_b32_e32 v68, v0
	v_mov_b32_e32 v69, v0
	v_mov_b32_e32 v70, v0
	v_mov_b32_e32 v71, v0
	v_mov_b32_e32 v72, v0
	v_mov_b32_e32 v73, v0
	v_mov_b32_e32 v74, v0
	v_mov_b32_e32 v75, v0
	v_mov_b32_e32 v80, v0
	v_mov_b32_e32 v81, v0
	v_mov_b32_e32 v82, v0
	v_mov_b32_e32 v83, v0
	v_mov_b32_e32 v88, v0
	v_mov_b32_e32 v89, v0
	v_mov_b32_e32 v90, v0
	v_mov_b32_e32 v91, v0
	v_mov_b32_e32 v98, v0
	v_mov_b32_e32 v99, v0
	v_mov_b32_e32 v100, v0
	v_mov_b32_e32 v101, v0
	v_mov_b32_e32 v110, v0
	v_mov_b32_e32 v111, v0
	v_mov_b32_e32 v112, v0
	v_mov_b32_e32 v113, v0
	v_mov_b32_e32 v122, v0
	v_mov_b32_e32 v123, v0
	v_mov_b32_e32 v124, v0
	v_mov_b32_e32 v125, v0
	v_mov_b32_e32 v76, v0
	v_mov_b32_e32 v77, v0
	v_mov_b32_e32 v78, v0
	v_mov_b32_e32 v79, v0
	v_mov_b32_e32 v84, v0
	v_mov_b32_e32 v85, v0
	v_mov_b32_e32 v86, v0
	v_mov_b32_e32 v87, v0
	v_mov_b32_e32 v92, v0
	v_mov_b32_e32 v93, v0
	v_mov_b32_e32 v94, v0
	v_mov_b32_e32 v95, v0
	v_mov_b32_e32 v102, v0
	v_mov_b32_e32 v103, v0
	v_mov_b32_e32 v104, v0
	v_mov_b32_e32 v105, v0
	v_mov_b32_e32 v106, v0
	v_mov_b32_e32 v107, v0
	v_mov_b32_e32 v108, v0
	v_mov_b32_e32 v109, v0
	v_mov_b32_e32 v114, v0
	v_mov_b32_e32 v115, v0
	v_mov_b32_e32 v116, v0
	v_mov_b32_e32 v117, v0
	v_mov_b32_e32 v138, v0
	v_mov_b32_e32 v139, v0
	v_mov_b32_e32 v140, v0
	v_mov_b32_e32 v141, v0
	v_mov_b32_e32 v142, v0
	v_mov_b32_e32 v143, v0
	v_mov_b32_e32 v144, v0
	v_mov_b32_e32 v145, v0
	v_readfirstlane_b32 s100, v226
	s_nop 3
	s_lshr_b32 s100, s100, 8
	s_cmp_eq_u32 s100, 0
	s_cbranch_scc1 .Lgp_1873
	s_setprio 1
.Lgp_1873:
.LBB0_47:
	s_add_u32 s52, s50, 0x100
	s_addc_u32 s53, s51, 0
	s_add_i32 s42, 0, 0x10000
	v_add_u32_e32 v134, s42, v225
	ds_read_b128 v[118:121], v134
	ds_read_b128 v[126:129], v134 offset:1024
	ds_read_b128 v[130:133], v134 offset:2048
	ds_read_b128 v[134:137], v134 offset:3072
	s_cmp_eq_u32 s94, 60
	s_cselect_b32 s1, s41, s53
	s_cselect_b32 s0, s68, s52
	s_cselect_b32 vcc_hi, s39, s71
	s_cselect_b32 vcc_lo, s69, s70
	v_lshl_add_u64 v[178:179], s[50:51], 0, v[210:211]
	s_add_i32 m0, s49, 0xc000
	ds_read_b128 v[146:149], v240
	ds_read_b128 v[150:153], v240 offset:1024
	ds_read_b128 v[154:157], v240 offset:2048
	ds_read_b128 v[158:161], v240 offset:3072
	ds_read_b128 v[162:165], v240 offset:4096
	ds_read_b128 v[166:169], v240 offset:5120
	ds_read_b128 v[170:173], v240 offset:6144
	ds_read_b128 v[174:177], v240 offset:7168
	global_load_lds_dwordx4 v[178:179], off
	v_lshl_add_u64 v[178:179], s[50:51], 0, v[212:213]
	s_add_i32 m0, s49, 0xe000
	s_nop 0
	global_load_lds_dwordx4 v[178:179], off
	s_waitcnt lgkmcnt(8)
	s_barrier
	s_waitcnt lgkmcnt(0)
	s_waitcnt lgkmcnt(0)
	v_mfma_f32_16x16x32_bf16 v[142:145], v[118:121], v[146:149], v[142:145]
	v_mfma_f32_16x16x32_bf16 v[138:141], v[130:133], v[146:149], v[138:141]
	v_mfma_f32_16x16x32_bf16 v[114:117], v[118:121], v[154:157], v[114:117]
	v_mfma_f32_16x16x32_bf16 v[106:109], v[130:133], v[154:157], v[106:109]
	v_mfma_f32_16x16x32_bf16 v[102:105], v[118:121], v[162:165], v[102:105]
	v_mfma_f32_16x16x32_bf16 v[92:95], v[130:133], v[162:165], v[92:95]
	v_mfma_f32_16x16x32_bf16 v[84:87], v[118:121], v[170:173], v[84:87]
	v_mfma_f32_16x16x32_bf16 v[76:79], v[130:133], v[170:173], v[76:79]
	v_mfma_f32_16x16x32_bf16 v[142:145], v[126:129], v[150:153], v[142:145]
	v_mfma_f32_16x16x32_bf16 v[138:141], v[134:137], v[150:153], v[138:141]
	v_mfma_f32_16x16x32_bf16 v[114:117], v[126:129], v[158:161], v[114:117]
	v_mfma_f32_16x16x32_bf16 v[106:109], v[134:137], v[158:161], v[106:109]
	v_mfma_f32_16x16x32_bf16 v[102:105], v[126:129], v[166:169], v[102:105]
	v_mfma_f32_16x16x32_bf16 v[92:95], v[134:137], v[166:169], v[92:95]
	v_mfma_f32_16x16x32_bf16 v[84:87], v[126:129], v[174:177], v[84:87]
	v_mfma_f32_16x16x32_bf16 v[76:79], v[134:137], v[174:177], v[76:79]
	s_barrier
; #define PG8_STAGE(bufoff, gbase, voff) do { _Pragma("unroll") for (int _i = 0; _i < 2; ++_i) \
;         __builtin_amdgcn_global_load_lds((const unsigned*)((const char*)(gbase) + (voff)[_i]), (PG8_LAS unsigned*)(lds + (bufoff) + ldsw + _i * 8192), 16, 0, 0); } while (0)
; #define PG8_LDA(dst, b, h) do { _Pragma("unroll") for (int m = 0; m < 4; ++m) _Pragma("unroll") for (int k = 0; k < 2; ++k) dst[m][k] = *(const PG8_LAS bf16x8*)(lds + PG8_SA(b, h) + aoff + m * 2048 + k * 1024); } while (0)
; #define PG8_LDB(dst, b, h) do { _Pragma("unroll") for (int n = 0; n < 2; ++n) _Pragma("unroll") for (int k = 0; k < 2; ++k) dst[n][k] = *(const PG8_LAS bf16x8*)(lds + PG8_SB(b, h) + boff + n * 2048 + k * 1024); } while (0)
; #define PG8_MMA(ai, bj, At, Bt) do { __builtin_amdgcn_s_setprio(1); _Pragma("unroll") for (int m = 0; m < 4; ++m) _Pragma("unroll") for (int n = 0; n < 2; ++n) _Pragma("unroll") for (int k = 0; k < 2; ++k) \
;         acc[ai][bj][m][n] = __builtin_amdgcn_mfma_f32_16x16x32_bf16(Bt[n][k], At[m][k], acc[ai][bj][m][n], 0, 0, 0); __builtin_amdgcn_s_setprio(0); } while (0)
; #define PG8_WAIT_V(n) asm volatile("s_waitcnt vmcnt(" #n ")" ::: "memory")
; #define PG8_WAIT_L(n) asm volatile("s_waitcnt lgkmcnt(" #n ")" ::: "memory")
; #define PG8_BAR __builtin_amdgcn_s_barrier()
; #define PG8_SCHED __builtin_amdgcn_sched_barrier(0)
; template <class Epi, class Sched>
; __device__ __forceinline__ void gemm_phase(PG8_LAS unsigned char* lds, const Gemm g, const Sched& S, const Epi& E) {
;     ...
;             PG8_LDB(B1, 0, 1); PG8_STAGE(PG8_SB(0, 0), b2, voffB);
;             PG8_BAR; PG8_WAIT_L(0); PG8_MMA(0, 1, At, B1); PG8_BAR;
;             PG8_LDA(At, 0, 1); PG8_STAGE(PG8_SA(0, 0), a2, voffA);
;             PG8_BAR; PG8_WAIT_L(0); PG8_MMA(1, 0, At, B0); PG8_BAR; PG8_SCHED;
;             PG8_STAGE(PG8_SB(0, 1), b2 + hstep, voffB);
;             PG8_WAIT_V(6); PG8_BAR; PG8_MMA(1, 1, At, B1); PG8_BAR;
;             PG8_LDB(B0, 1, 0); PG8_SCHED; PG8_LDA(At, 1, 0); PG8_STAGE(PG8_SA(0, 1), a2 + hstep, voffA);
;             PG8_WAIT_L(8); PG8_BAR; PG8_WAIT_L(0); PG8_MMA(0, 0, At, B0); PG8_BAR; PG8_SCHED;
	s_add_i32 s43, 0, 0x14000
	s_add_i32 s42, s42, s58
	v_add_u32_e32 v190, s43, v225
	v_lshl_add_u64 v[194:195], vcc, 0, v[96:97]
	s_mov_b32 m0, s42
	ds_read_b128 v[178:181], v190
	ds_read_b128 v[182:185], v190 offset:1024
	ds_read_b128 v[186:189], v190 offset:2048
	ds_read_b128 v[190:193], v190 offset:3072
	global_load_lds_dwordx4 v[194:195], off
	v_lshl_add_u64 v[196:197], vcc, 0, v[208:209]
	s_add_i32 m0, s42, 0x2000
	s_nop 0
	global_load_lds_dwordx4 v[196:197], off
	s_barrier
	s_waitcnt lgkmcnt(0)
	s_waitcnt lgkmcnt(0)
	v_mfma_f32_16x16x32_bf16 v[122:125], v[178:181], v[146:149], v[122:125]
	v_mfma_f32_16x16x32_bf16 v[110:113], v[186:189], v[146:149], v[110:113]
	v_mfma_f32_16x16x32_bf16 v[98:101], v[178:181], v[154:157], v[98:101]
	v_mfma_f32_16x16x32_bf16 v[88:91], v[186:189], v[154:157], v[88:91]
	v_mfma_f32_16x16x32_bf16 v[80:83], v[178:181], v[162:165], v[80:83]
	v_mfma_f32_16x16x32_bf16 v[72:75], v[186:189], v[162:165], v[72:75]
	v_mfma_f32_16x16x32_bf16 v[68:71], v[178:181], v[170:173], v[68:71]
	v_mfma_f32_16x16x32_bf16 v[64:67], v[186:189], v[170:173], v[64:67]
	v_mfma_f32_16x16x32_bf16 v[122:125], v[182:185], v[150:153], v[122:125]
	v_mfma_f32_16x16x32_bf16 v[110:113], v[190:193], v[150:153], v[110:113]
	v_mfma_f32_16x16x32_bf16 v[98:101], v[182:185], v[158:161], v[98:101]
	v_mfma_f32_16x16x32_bf16 v[88:91], v[190:193], v[158:161], v[88:91]
	v_mfma_f32_16x16x32_bf16 v[80:83], v[182:185], v[166:169], v[80:83]
	v_mfma_f32_16x16x32_bf16 v[72:75], v[190:193], v[166:169], v[72:75]
	v_mfma_f32_16x16x32_bf16 v[68:71], v[182:185], v[174:177], v[68:71]
	v_mfma_f32_16x16x32_bf16 v[64:67], v[190:193], v[174:177], v[64:67]
	s_mov_b32 m0, s49
	v_lshl_add_u64 v[198:199], s[0:1], 0, v[96:97]
	s_barrier
	ds_read_b128 v[146:149], v240 offset:16384
	ds_read_b128 v[150:153], v240 offset:17408
	ds_read_b128 v[154:157], v240 offset:18432
	ds_read_b128 v[158:161], v240 offset:19456
	ds_read_b128 v[162:165], v240 offset:20480
	ds_read_b128 v[166:169], v240 offset:21504
	ds_read_b128 v[170:173], v240 offset:22528
	ds_read_b128 v[174:177], v240 offset:23552
	global_load_lds_dwordx4 v[198:199], off
	v_lshl_add_u64 v[200:201], s[0:1], 0, v[208:209]
	s_mov_b32 m0, s61
	s_nop 0
	global_load_lds_dwordx4 v[200:201], off
	s_barrier
	s_waitcnt lgkmcnt(0)
	s_waitcnt lgkmcnt(0)
	v_mfma_f32_16x16x32_bf16 v[60:63], v[118:121], v[146:149], v[60:63]
	v_mfma_f32_16x16x32_bf16 v[56:59], v[130:133], v[146:149], v[56:59]
	v_mfma_f32_16x16x32_bf16 v[52:55], v[118:121], v[154:157], v[52:55]
	v_mfma_f32_16x16x32_bf16 v[44:47], v[130:133], v[154:157], v[44:47]
	v_mfma_f32_16x16x32_bf16 v[36:39], v[118:121], v[162:165], v[36:39]
	v_mfma_f32_16x16x32_bf16 v[28:31], v[130:133], v[162:165], v[28:31]
	v_mfma_f32_16x16x32_bf16 v[20:23], v[118:121], v[170:173], v[20:23]
	v_mfma_f32_16x16x32_bf16 v[12:15], v[130:133], v[170:173], v[12:15]
	v_mfma_f32_16x16x32_bf16 v[60:63], v[126:129], v[150:153], v[60:63]
	v_mfma_f32_16x16x32_bf16 v[56:59], v[134:137], v[150:153], v[56:59]
	v_mfma_f32_16x16x32_bf16 v[52:55], v[126:129], v[158:161], v[52:55]
	v_mfma_f32_16x16x32_bf16 v[44:47], v[134:137], v[158:161], v[44:47]
	v_mfma_f32_16x16x32_bf16 v[36:39], v[126:129], v[166:169], v[36:39]
	v_mfma_f32_16x16x32_bf16 v[28:31], v[134:137], v[166:169], v[28:31]
	v_mfma_f32_16x16x32_bf16 v[20:23], v[126:129], v[174:177], v[20:23]
	v_mfma_f32_16x16x32_bf16 v[12:15], v[134:137], v[174:177], v[12:15]
	s_barrier
	s_add_u32 s50, vcc_lo, 0x100000
	s_addc_u32 s51, vcc_hi, 0
	s_add_i32 s42, s43, s58
	v_lshl_add_u64 v[118:119], s[50:51], 0, v[96:97]
	s_mov_b32 m0, s42
	s_nop 0
	global_load_lds_dwordx4 v[118:119], off
	v_lshl_add_u64 v[118:119], s[50:51], 0, v[208:209]
	s_add_i32 m0, s42, 0x2000
	s_nop 0
	global_load_lds_dwordx4 v[118:119], off
	s_waitcnt vmcnt(6)
	s_barrier
	v_mfma_f32_16x16x32_bf16 v[48:51], v[178:181], v[146:149], v[48:51]
	v_mfma_f32_16x16x32_bf16 v[40:43], v[186:189], v[146:149], v[40:43]
	v_mfma_f32_16x16x32_bf16 v[32:35], v[178:181], v[154:157], v[32:35]
	v_mfma_f32_16x16x32_bf16 v[24:27], v[186:189], v[154:157], v[24:27]
	v_mfma_f32_16x16x32_bf16 v[16:19], v[178:181], v[162:165], v[16:19]
	v_mfma_f32_16x16x32_bf16 v[8:11], v[186:189], v[162:165], v[8:11]
	v_mfma_f32_16x16x32_bf16 v[4:7], v[178:181], v[170:173], v[4:7]
	v_mfma_f32_16x16x32_bf16 v[0:3], v[186:189], v[170:173], v[0:3]
	v_mfma_f32_16x16x32_bf16 v[48:51], v[182:185], v[150:153], v[48:51]
	v_mfma_f32_16x16x32_bf16 v[40:43], v[190:193], v[150:153], v[40:43]
	v_mfma_f32_16x16x32_bf16 v[32:35], v[182:185], v[158:161], v[32:35]
	v_mfma_f32_16x16x32_bf16 v[24:27], v[190:193], v[158:161], v[24:27]
	v_mfma_f32_16x16x32_bf16 v[16:19], v[182:185], v[166:169], v[16:19]
	v_mfma_f32_16x16x32_bf16 v[8:11], v[190:193], v[166:169], v[8:11]
	v_mfma_f32_16x16x32_bf16 v[4:7], v[182:185], v[174:177], v[4:7]
	v_mfma_f32_16x16x32_bf16 v[0:3], v[190:193], v[174:177], v[0:3]
	s_add_i32 s42, 0, 0x18000
	v_add_u32_e32 v134, s42, v225
	s_barrier
	ds_read_b128 v[118:121], v134
	ds_read_b128 v[126:129], v134 offset:1024
	ds_read_b128 v[130:133], v134 offset:2048
	ds_read_b128 v[134:137], v134 offset:3072
	s_add_u32 s0, s0, 0x100000
	s_addc_u32 s1, s1, 0
	s_mov_b32 m0, s62
	v_lshl_add_u64 v[178:179], s[0:1], 0, v[96:97]
	ds_read_b128 v[146:149], v240 offset:32768
	ds_read_b128 v[150:153], v240 offset:33792
	ds_read_b128 v[154:157], v240 offset:34816
	ds_read_b128 v[158:161], v240 offset:35840
	ds_read_b128 v[162:165], v240 offset:36864
	ds_read_b128 v[166:169], v240 offset:37888
	ds_read_b128 v[170:173], v240 offset:38912
	ds_read_b128 v[174:177], v240 offset:39936
	global_load_lds_dwordx4 v[178:179], off
	v_lshl_add_u64 v[178:179], s[0:1], 0, v[208:209]
	s_mov_b32 m0, s63
	s_nop 0
	global_load_lds_dwordx4 v[178:179], off
	s_waitcnt lgkmcnt(8)
	s_barrier
; #define PG8_STAGE(bufoff, gbase, voff) do { _Pragma("unroll") for (int _i = 0; _i < 2; ++_i) \
;         __builtin_amdgcn_global_load_lds((const unsigned*)((const char*)(gbase) + (voff)[_i]), (PG8_LAS unsigned*)(lds + (bufoff) + ldsw + _i * 8192), 16, 0, 0); } while (0)
; #define PG8_LDA(dst, b, h) do { _Pragma("unroll") for (int m = 0; m < 4; ++m) _Pragma("unroll") for (int k = 0; k < 2; ++k) dst[m][k] = *(const PG8_LAS bf16x8*)(lds + PG8_SA(b, h) + aoff + m * 2048 + k * 1024); } while (0)
; #define PG8_LDB(dst, b, h) do { _Pragma("unroll") for (int n = 0; n < 2; ++n) _Pragma("unroll") for (int k = 0; k < 2; ++k) dst[n][k] = *(const PG8_LAS bf16x8*)(lds + PG8_SB(b, h) + boff + n * 2048 + k * 1024); } while (0)
; #define PG8_MMA(ai, bj, At, Bt) do { __builtin_amdgcn_s_setprio(1); _Pragma("unroll") for (int m = 0; m < 4; ++m) _Pragma("unroll") for (int n = 0; n < 2; ++n) _Pragma("unroll") for (int k = 0; k < 2; ++k) \
;         acc[ai][bj][m][n] = __builtin_amdgcn_mfma_f32_16x16x32_bf16(Bt[n][k], At[m][k], acc[ai][bj][m][n], 0, 0, 0); __builtin_amdgcn_s_setprio(0); } while (0)
; #define PG8_WAIT_V(n) asm volatile("s_waitcnt vmcnt(" #n ")" ::: "memory")
; #define PG8_WAIT_L(n) asm volatile("s_waitcnt lgkmcnt(" #n ")" ::: "memory")
; #define PG8_BAR __builtin_amdgcn_s_barrier()
; #define PG8_SCHED __builtin_amdgcn_sched_barrier(0)
; template <class Epi, class Sched>
; __device__ __forceinline__ void gemm_phase(PG8_LAS unsigned char* lds, const Gemm g, const Sched& S, const Epi& E) {
;     ...
;             PG8_WAIT_L(8); PG8_BAR; PG8_WAIT_L(0); PG8_MMA(0, 0, At, B0); PG8_BAR; PG8_SCHED;
;             PG8_LDB(B1, 1, 1); PG8_STAGE(PG8_SB(1, 0), b3, voffB);
;             PG8_BAR; PG8_WAIT_L(0); PG8_MMA(0, 1, At, B1); PG8_BAR;
;             PG8_LDA(At, 1, 1); PG8_STAGE(PG8_SA(1, 0), a3, voffA);
;             PG8_BAR; PG8_WAIT_L(0); PG8_MMA(1, 0, At, B0); PG8_BAR; PG8_SCHED;
;             PG8_STAGE(PG8_SB(1, 1), b3 + hstep, voffB);
;             PG8_WAIT_V(6); PG8_BAR; PG8_MMA(1, 1, At, B1); PG8_BAR;
;         }
	s_waitcnt lgkmcnt(0)
	s_waitcnt lgkmcnt(0)
	v_mfma_f32_16x16x32_bf16 v[142:145], v[118:121], v[146:149], v[142:145]
	v_mfma_f32_16x16x32_bf16 v[138:141], v[130:133], v[146:149], v[138:141]
	v_mfma_f32_16x16x32_bf16 v[114:117], v[118:121], v[154:157], v[114:117]
	v_mfma_f32_16x16x32_bf16 v[106:109], v[130:133], v[154:157], v[106:109]
	v_mfma_f32_16x16x32_bf16 v[102:105], v[118:121], v[162:165], v[102:105]
	v_mfma_f32_16x16x32_bf16 v[92:95], v[130:133], v[162:165], v[92:95]
	v_mfma_f32_16x16x32_bf16 v[84:87], v[118:121], v[170:173], v[84:87]
	v_mfma_f32_16x16x32_bf16 v[76:79], v[130:133], v[170:173], v[76:79]
	v_mfma_f32_16x16x32_bf16 v[142:145], v[126:129], v[150:153], v[142:145]
	v_mfma_f32_16x16x32_bf16 v[138:141], v[134:137], v[150:153], v[138:141]
	v_mfma_f32_16x16x32_bf16 v[114:117], v[126:129], v[158:161], v[114:117]
	v_mfma_f32_16x16x32_bf16 v[106:109], v[134:137], v[158:161], v[106:109]
	v_mfma_f32_16x16x32_bf16 v[102:105], v[126:129], v[166:169], v[102:105]
	v_mfma_f32_16x16x32_bf16 v[92:95], v[134:137], v[166:169], v[92:95]
	v_mfma_f32_16x16x32_bf16 v[84:87], v[126:129], v[174:177], v[84:87]
	v_mfma_f32_16x16x32_bf16 v[76:79], v[134:137], v[174:177], v[76:79]
	s_barrier
	s_add_i32 s43, 0, 0x1c000
	s_add_i32 s0, s42, s58
	v_add_u32_e32 v190, s43, v225
	v_lshl_add_u64 v[194:195], v[194:195], 0, s[2:3]
	s_mov_b32 m0, s0
	ds_read_b128 v[178:181], v190
	ds_read_b128 v[182:185], v190 offset:1024
	ds_read_b128 v[186:189], v190 offset:2048
	ds_read_b128 v[190:193], v190 offset:3072
	global_load_lds_dwordx4 v[194:195], off
	v_lshl_add_u64 v[194:195], v[196:197], 0, s[2:3]
	s_add_i32 m0, s0, 0x2000
	s_nop 0
	global_load_lds_dwordx4 v[194:195], off
	s_barrier
	s_waitcnt lgkmcnt(0)
	s_waitcnt lgkmcnt(0)
	v_mfma_f32_16x16x32_bf16 v[122:125], v[178:181], v[146:149], v[122:125]
	v_mfma_f32_16x16x32_bf16 v[110:113], v[186:189], v[146:149], v[110:113]
	v_mfma_f32_16x16x32_bf16 v[98:101], v[178:181], v[154:157], v[98:101]
	v_mfma_f32_16x16x32_bf16 v[88:91], v[186:189], v[154:157], v[88:91]
	v_mfma_f32_16x16x32_bf16 v[80:83], v[178:181], v[162:165], v[80:83]
	v_mfma_f32_16x16x32_bf16 v[72:75], v[186:189], v[162:165], v[72:75]
	v_mfma_f32_16x16x32_bf16 v[68:71], v[178:181], v[170:173], v[68:71]
	v_mfma_f32_16x16x32_bf16 v[64:67], v[186:189], v[170:173], v[64:67]
	v_mfma_f32_16x16x32_bf16 v[122:125], v[182:185], v[150:153], v[122:125]
	v_mfma_f32_16x16x32_bf16 v[110:113], v[190:193], v[150:153], v[110:113]
	v_mfma_f32_16x16x32_bf16 v[98:101], v[182:185], v[158:161], v[98:101]
	v_mfma_f32_16x16x32_bf16 v[88:91], v[190:193], v[158:161], v[88:91]
	v_mfma_f32_16x16x32_bf16 v[80:83], v[182:185], v[166:169], v[80:83]
	v_mfma_f32_16x16x32_bf16 v[72:75], v[190:193], v[166:169], v[72:75]
	v_mfma_f32_16x16x32_bf16 v[68:71], v[182:185], v[174:177], v[68:71]
	v_mfma_f32_16x16x32_bf16 v[64:67], v[190:193], v[174:177], v[64:67]
	s_mov_b32 m0, s64
	v_lshl_add_u64 v[194:195], v[198:199], 0, s[2:3]
	s_barrier
	ds_read_b128 v[146:149], v240 offset:49152
	ds_read_b128 v[150:153], v240 offset:50176
	ds_read_b128 v[154:157], v240 offset:51200
	ds_read_b128 v[158:161], v240 offset:52224
	ds_read_b128 v[162:165], v240 offset:53248
	ds_read_b128 v[166:169], v240 offset:54272
	ds_read_b128 v[170:173], v240 offset:55296
	ds_read_b128 v[174:177], v240 offset:56320
	global_load_lds_dwordx4 v[194:195], off
	v_lshl_add_u64 v[194:195], v[200:201], 0, s[2:3]
	s_mov_b32 m0, s65
	s_nop 0
	global_load_lds_dwordx4 v[194:195], off
	s_barrier
	s_waitcnt lgkmcnt(0)
	s_waitcnt lgkmcnt(0)
	v_mfma_f32_16x16x32_bf16 v[60:63], v[118:121], v[146:149], v[60:63]
	v_mfma_f32_16x16x32_bf16 v[56:59], v[130:133], v[146:149], v[56:59]
	v_mfma_f32_16x16x32_bf16 v[52:55], v[118:121], v[154:157], v[52:55]
	v_mfma_f32_16x16x32_bf16 v[44:47], v[130:133], v[154:157], v[44:47]
	v_mfma_f32_16x16x32_bf16 v[36:39], v[118:121], v[162:165], v[36:39]
	v_mfma_f32_16x16x32_bf16 v[28:31], v[130:133], v[162:165], v[28:31]
	v_mfma_f32_16x16x32_bf16 v[20:23], v[118:121], v[170:173], v[20:23]
	v_mfma_f32_16x16x32_bf16 v[12:15], v[130:133], v[170:173], v[12:15]
	v_mfma_f32_16x16x32_bf16 v[60:63], v[126:129], v[150:153], v[60:63]
	v_mfma_f32_16x16x32_bf16 v[56:59], v[134:137], v[150:153], v[56:59]
	v_mfma_f32_16x16x32_bf16 v[52:55], v[126:129], v[158:161], v[52:55]
	v_mfma_f32_16x16x32_bf16 v[44:47], v[134:137], v[158:161], v[44:47]
	v_mfma_f32_16x16x32_bf16 v[36:39], v[126:129], v[166:169], v[36:39]
	v_mfma_f32_16x16x32_bf16 v[28:31], v[134:137], v[166:169], v[28:31]
	v_mfma_f32_16x16x32_bf16 v[20:23], v[126:129], v[174:177], v[20:23]
	v_mfma_f32_16x16x32_bf16 v[12:15], v[134:137], v[174:177], v[12:15]
	s_barrier
	s_add_u32 s0, vcc_lo, 0x100080
	s_addc_u32 s1, vcc_hi, 0
	s_add_i32 s42, s43, s58
	v_lshl_add_u64 v[118:119], s[0:1], 0, v[96:97]
	s_mov_b32 m0, s42
	s_nop 0
	global_load_lds_dwordx4 v[118:119], off
	v_lshl_add_u64 v[118:119], s[0:1], 0, v[208:209]
	s_add_i32 m0, s42, 0x2000
	s_nop 0
	global_load_lds_dwordx4 v[118:119], off
	s_waitcnt vmcnt(6)
	s_barrier
	v_mfma_f32_16x16x32_bf16 v[48:51], v[178:181], v[146:149], v[48:51]
	v_mfma_f32_16x16x32_bf16 v[40:43], v[186:189], v[146:149], v[40:43]
	v_mfma_f32_16x16x32_bf16 v[32:35], v[178:181], v[154:157], v[32:35]
	v_mfma_f32_16x16x32_bf16 v[24:27], v[186:189], v[154:157], v[24:27]
	v_mfma_f32_16x16x32_bf16 v[16:19], v[178:181], v[162:165], v[16:19]
	v_mfma_f32_16x16x32_bf16 v[8:11], v[186:189], v[162:165], v[8:11]
	v_mfma_f32_16x16x32_bf16 v[4:7], v[178:181], v[170:173], v[4:7]
	v_mfma_f32_16x16x32_bf16 v[0:3], v[186:189], v[170:173], v[0:3]
	v_mfma_f32_16x16x32_bf16 v[48:51], v[182:185], v[150:153], v[48:51]
	v_mfma_f32_16x16x32_bf16 v[40:43], v[190:193], v[150:153], v[40:43]
	v_mfma_f32_16x16x32_bf16 v[32:35], v[182:185], v[158:161], v[32:35]
	v_mfma_f32_16x16x32_bf16 v[24:27], v[190:193], v[158:161], v[24:27]
	v_mfma_f32_16x16x32_bf16 v[16:19], v[182:185], v[166:169], v[16:19]
	v_mfma_f32_16x16x32_bf16 v[8:11], v[190:193], v[166:169], v[8:11]
	v_mfma_f32_16x16x32_bf16 v[4:7], v[182:185], v[174:177], v[4:7]
	v_mfma_f32_16x16x32_bf16 v[0:3], v[190:193], v[174:177], v[0:3]
	s_add_i32 s94, s94, 2
	s_add_u32 s70, s70, 0x100
	s_addc_u32 s71, s71, 0
	s_cmp_gt_u32 s94, 61
	s_mov_b64 s[50:51], s[52:53]
	s_barrier
;   DEV void operator()(const f32x4 (&acc)[2][2][4][2], const pg8::Unit& u, int wr, int wc, int fr, int fq) const {
;     const int row0 = u.pm * 256 + wr * 64 + fr, col0 = u.pn * 256 + wc * 32 + 4 * fq;
;     const float* gt = mod + (size_t)modrow(row0) * 6144;
;     f32x4 g4[2][2];
; #pragma unroll
;     for (int bj = 0; bj < 2; ++bj)
; #pragma unroll
;       for (int n = 0; n < 2; ++n) g4[bj][n] = *(const f32x4*)(gt + col0 + bj * 128 + n * 16);
; #pragma unroll
;     for (int ai = 0; ai < 2; ++ai) {
;       f32x4 xv[4][2][2];
; #pragma unroll
;       for (int m = 0; m < 4; ++m) {
;         const int row = row0 + ai * 128 + m * 16;
;         const float* xi = row < T_LAT ? rin_lat + (size_t)row * DM : rin_ctx + (size_t)(row - T_LAT) * DM;
; #pragma unroll
;         for (int bj = 0; bj < 2; ++bj)
; #pragma unroll
;           for (int n = 0; n < 2; ++n) xv[m][bj][n] = *(const f32x4*)(xi + col0 + bj * 128 + n * 16);
;       }
; #pragma unroll
;       for (int m = 0; m < 4; ++m) {
;         const int row = row0 + ai * 128 + m * 16;
;         float* xr = row < T_LAT ? out + (size_t)row * DM : xc + (size_t)(row - T_LAT) * DM;
; #pragma unroll
;         for (int bj = 0; bj < 2; ++bj)
; #pragma unroll
;           for (int n = 0; n < 2; ++n) {
;             const f32x4 r = xv[m][bj][n] + g4[bj][n] * acc[ai][bj][m][n];
;             if (store) *(f32x4*)(xr + col0 + bj * 128 + n * 16) = r;
;           }
;       }
;     }
;   }
	s_cbranch_scc0 .LBB0_47
	v_lshl_add_u32 v238, s48, 8, v224
	s_mov_b32 s71, 0x8000
	v_readlane_b32 s0, v251, 52
	v_min_i32_e32 v119, 0x8000, v238
	v_cmp_gt_i32_e32 vcc, s71, v238
	v_add_u32_e32 v146, 0xffff8000, v238
	v_ashrrev_i32_e32 v147, 31, v238
	v_mov_b32_e32 v241, s0
	v_readlane_b32 s0, v251, 51
	v_lshl_or_b32 v118, s67, 8, v239
	v_ashrrev_i32_e32 v119, 12, v119
	v_cndmask_b32_e32 v147, 0, v147, vcc
	v_cndmask_b32_e32 v146, v146, v238, vcc
	v_mov_b32_e32 v242, s73
	v_mov_b32_e32 v243, s0
	v_mov_b32_e32 v244, s72
	v_mul_hi_i32_i24_e32 v121, 0x6000, v119
	v_mul_i32_i24_e32 v120, 0x6000, v119
	v_ashrrev_i32_e32 v119, 31, v118
	v_cndmask_b32_e32 v149, v241, v242, vcc
	v_cndmask_b32_e32 v148, v243, v244, vcc
	v_lshlrev_b64 v[146:147], 12, v[146:147]
	v_lshlrev_b64 v[214:215], 2, v[118:119]
	v_lshl_add_u64 v[146:147], v[148:149], 0, v[146:147]
	v_lshl_add_u64 v[222:223], v[146:147], 0, v[214:215]
	v_or_b32_e32 v146, 16, v238
	v_cmp_gt_i32_e32 vcc, s71, v146
	v_ashrrev_i32_e32 v147, 31, v146
	v_add_u32_e32 v148, 0xffff8010, v238
	v_cndmask_b32_e32 v147, 0, v147, vcc
	v_cndmask_b32_e32 v146, v148, v146, vcc
	v_cndmask_b32_e32 v149, v241, v242, vcc
	v_cndmask_b32_e32 v148, v243, v244, vcc
	v_lshlrev_b64 v[146:147], 12, v[146:147]
	v_lshl_add_u64 v[146:147], v[148:149], 0, v[146:147]
	v_lshl_add_u64 v[220:221], v[146:147], 0, v[214:215]
	v_or_b32_e32 v146, 32, v238
	v_cmp_gt_i32_e32 vcc, s71, v146
	v_ashrrev_i32_e32 v147, 31, v146
	v_add_u32_e32 v148, 0xffff8020, v238
	v_cndmask_b32_e32 v147, 0, v147, vcc
	v_cndmask_b32_e32 v146, v148, v146, vcc
	v_cndmask_b32_e32 v149, v241, v242, vcc
	v_cndmask_b32_e32 v148, v243, v244, vcc
	v_lshlrev_b64 v[146:147], 12, v[146:147]
	v_lshl_add_u64 v[146:147], v[148:149], 0, v[146:147]
	v_lshl_add_u64 v[218:219], v[146:147], 0, v[214:215]
	v_or_b32_e32 v146, 48, v238
	v_cmp_gt_i32_e32 vcc, s71, v146
	v_ashrrev_i32_e32 v147, 31, v146
	v_add_u32_e32 v148, 0xffff8030, v238
	v_cndmask_b32_e32 v147, 0, v147, vcc
	v_cndmask_b32_e32 v146, v148, v146, vcc
	v_cndmask_b32_e32 v149, v241, v242, vcc
	v_cndmask_b32_e32 v148, v243, v244, vcc
	v_lshlrev_b64 v[146:147], 12, v[146:147]
	v_lshl_add_u64 v[120:121], s[30:31], 0, v[120:121]
	v_lshl_add_u64 v[146:147], v[148:149], 0, v[146:147]
	v_lshl_add_u64 v[118:119], v[120:121], 0, v[214:215]
	v_lshl_add_u64 v[216:217], v[146:147], 0, v[214:215]
	global_load_dwordx4 v[134:137], v[118:119], off
	global_load_dwordx4 v[130:133], v[118:119], off offset:64
	global_load_dwordx4 v[126:129], v[118:119], off offset:512
	s_nop 0
	global_load_dwordx4 v[118:121], v[118:119], off offset:576
	s_nop 0
	global_load_dwordx4 v[202:205], v[222:223], off offset:64
	global_load_dwordx4 v[198:201], v[222:223], off offset:512
	global_load_dwordx4 v[194:197], v[222:223], off offset:576
	global_load_dwordx4 v[190:193], v[220:221], off
	global_load_dwordx4 v[186:189], v[220:221], off offset:64
	global_load_dwordx4 v[182:185], v[220:221], off offset:512
	global_load_dwordx4 v[174:177], v[220:221], off offset:576
	global_load_dwordx4 v[178:181], v[218:219], off
	global_load_dwordx4 v[170:173], v[218:219], off offset:64
	global_load_dwordx4 v[166:169], v[218:219], off offset:512
	global_load_dwordx4 v[158:161], v[218:219], off offset:576
	global_load_dwordx4 v[162:165], v[216:217], off
	global_load_dwordx4 v[154:157], v[216:217], off offset:64
	global_load_dwordx4 v[150:153], v[216:217], off offset:512
	global_load_dwordx4 v[146:149], v[216:217], off offset:576
	global_load_dwordx4 v[228:231], v[222:223], off
	s_movk_i32 s0, 0x7f80
	v_cmp_gt_i32_e32 vcc, s0, v238
	s_movk_i32 s0, 0x7f70
	s_mov_b32 s67, s38
	s_mov_b32 s48, s40
	s_mov_b64 s[52:53], s[46:47]
	s_mov_b64 s[50:51], s[44:45]
	s_waitcnt vmcnt(0)
	v_pk_fma_f32 v[140:141], v[140:141], v[132:133], v[204:205]
	v_pk_fma_f32 v[138:139], v[138:139], v[130:131], v[202:203]
	v_pk_fma_f32 v[124:125], v[124:125], v[128:129], v[200:201]
	v_pk_fma_f32 v[122:123], v[122:123], v[126:127], v[198:199]
	v_pk_fma_f32 v[112:113], v[112:113], v[120:121], v[196:197]
	v_pk_fma_f32 v[144:145], v[144:145], v[136:137], v[230:231]
	v_pk_fma_f32 v[142:143], v[142:143], v[134:135], v[228:229]
	v_pk_fma_f32 v[110:111], v[110:111], v[118:119], v[194:195]
	v_pk_fma_f32 v[90:91], v[90:91], v[120:121], v[176:177]
	v_pk_fma_f32 v[88:89], v[88:89], v[118:119], v[174:175]
	global_store_dwordx4 v[222:223], v[142:145], off
	global_store_dwordx4 v[222:223], v[138:141], off offset:64
	global_store_dwordx4 v[222:223], v[122:125], off offset:512
	global_store_dwordx4 v[222:223], v[110:113], off offset:576
	v_pk_fma_f32 v[108:109], v[108:109], v[132:133], v[188:189]
	v_pk_fma_f32 v[106:107], v[106:107], v[130:131], v[186:187]
	v_pk_fma_f32 v[112:113], v[116:117], v[136:137], v[192:193]
	v_pk_fma_f32 v[110:111], v[114:115], v[134:135], v[190:191]
	v_pk_fma_f32 v[100:101], v[100:101], v[128:129], v[184:185]
	v_pk_fma_f32 v[98:99], v[98:99], v[126:127], v[182:183]
	global_store_dwordx4 v[220:221], v[88:91], off offset:576
	global_store_dwordx4 v[220:221], v[110:113], off
	global_store_dwordx4 v[220:221], v[106:109], off offset:64
	v_pk_fma_f32 v[90:91], v[104:105], v[136:137], v[180:181]
	v_pk_fma_f32 v[88:89], v[102:103], v[134:135], v[178:179]
	global_store_dwordx4 v[220:221], v[98:101], off offset:512
	global_store_dwordx4 v[218:219], v[88:91], off
	v_pk_fma_f32 v[82:83], v[82:83], v[128:129], v[168:169]
	v_pk_fma_f32 v[80:81], v[80:81], v[126:127], v[166:167]
	v_pk_fma_f32 v[90:91], v[94:95], v[132:133], v[172:173]
	v_pk_fma_f32 v[88:89], v[92:93], v[130:131], v[170:171]
	v_pk_fma_f32 v[74:75], v[74:75], v[120:121], v[160:161]
	v_pk_fma_f32 v[72:73], v[72:73], v[118:119], v[158:159]
; #define PG8_WAIT_V(n) asm volatile("s_waitcnt vmcnt(" #n ")" ::: "memory")
; #define PG8_BAR __builtin_amdgcn_s_barrier()
; template <class Epi, class Sched>
; __device__ __forceinline__ void gemm_phase(PG8_LAS unsigned char* lds, const Gemm g, const Sched& S, const Epi& E) {
;     ...
;         if (!has_next) break;
; #pragma unroll
;         for (int a = 0; a < 2; ++a)
; #pragma unroll
;             for (int b = 0; b < 2; ++b)
; #pragma unroll
;                 for (int m = 0; m < 4; ++m)
; #pragma unroll
;                     for (int n = 0; n < 2; ++n) acc[a][b][m][n] = (f32x4){0.f, 0.f, 0.f, 0.f};
;         cur = nxt; cA = nA; cB = nB; ++ui;
;     }
;     PG8_WAIT_V(0);
;     if (wr == 0) PG8_BAR;
;     PG8_BAR;
;   DEV void operator()(const f32x4 (&acc)[2][2][4][2], const pg8::Unit& u, int wr, int wc, int fr, int fq) const {
;     ...
;     for (int ai = 0; ai < 2; ++ai) {
;       f32x4 xv[4][2][2];
; #pragma unroll
;       for (int m = 0; m < 4; ++m) {
;         const int row = row0 + ai * 128 + m * 16;
;         const float* xi = row < T_LAT ? rin_lat + (size_t)row * DM : rin_ctx + (size_t)(row - T_LAT) * DM;
; #pragma unroll
;         for (int bj = 0; bj < 2; ++bj)
; #pragma unroll
;           for (int n = 0; n < 2; ++n) xv[m][bj][n] = *(const f32x4*)(xi + col0 + bj * 128 + n * 16);
;       }
; #pragma unroll
;       for (int m = 0; m < 4; ++m) {
;         const int row = row0 + ai * 128 + m * 16;
;         float* xr = row < T_LAT ? out + (size_t)row * DM : xc + (size_t)(row - T_LAT) * DM;
; #pragma unroll
;         for (int bj = 0; bj < 2; ++bj)
; #pragma unroll
;           for (int n = 0; n < 2; ++n) {
;             const f32x4 r = xv[m][bj][n] + g4[bj][n] * acc[ai][bj][m][n];
;             if (store) *(f32x4*)(xr + col0 + bj * 128 + n * 16) = r;
;           }
;       }
;     }
	v_pk_fma_f32 v[66:67], v[66:67], v[120:121], v[148:149]
	v_pk_fma_f32 v[64:65], v[64:65], v[118:119], v[146:147]
	global_store_dwordx4 v[218:219], v[88:91], off offset:64
	global_store_dwordx4 v[218:219], v[80:83], off offset:512
	global_store_dwordx4 v[218:219], v[72:75], off offset:576
	global_store_dwordx4 v[216:217], v[64:67], off offset:576
	v_pk_fma_f32 v[70:71], v[70:71], v[128:129], v[152:153]
	v_pk_fma_f32 v[74:75], v[86:87], v[136:137], v[164:165]
	v_add_u32_e32 v64, 0x80, v238
	v_ashrrev_i32_e32 v65, 31, v64
	v_add_u32_e32 v66, 0xffff8080, v238
	v_cndmask_b32_e32 v65, 0, v65, vcc
	v_cndmask_b32_e32 v64, v66, v64, vcc
	v_cndmask_b32_e32 v67, v241, v242, vcc
	v_cndmask_b32_e32 v66, v243, v244, vcc
	v_lshlrev_b64 v[64:65], 12, v[64:65]
	v_lshl_add_u64 v[64:65], v[66:67], 0, v[64:65]
	v_lshl_add_u64 v[148:149], v[64:65], 0, v[214:215]
	v_add_u32_e32 v64, 0x90, v238
	v_cmp_gt_i32_e32 vcc, s0, v238
	v_ashrrev_i32_e32 v65, 31, v64
	v_add_u32_e32 v66, 0xffff8090, v238
	v_cndmask_b32_e32 v65, 0, v65, vcc
	v_cndmask_b32_e32 v64, v66, v64, vcc
	v_cndmask_b32_e32 v67, v241, v242, vcc
	v_cndmask_b32_e32 v66, v243, v244, vcc
	v_lshlrev_b64 v[64:65], 12, v[64:65]
	v_lshl_add_u64 v[64:65], v[66:67], 0, v[64:65]
	v_lshl_add_u64 v[146:147], v[64:65], 0, v[214:215]
	v_add_u32_e32 v64, 0xa0, v238
	s_movk_i32 s0, 0x7f60
	v_cmp_gt_i32_e32 vcc, s0, v238
	v_ashrrev_i32_e32 v65, 31, v64
	v_add_u32_e32 v66, 0xffff80a0, v238
	v_cndmask_b32_e32 v65, 0, v65, vcc
	v_cndmask_b32_e32 v64, v66, v64, vcc
	v_cndmask_b32_e32 v67, v241, v242, vcc
	v_cndmask_b32_e32 v66, v243, v244, vcc
	v_lshlrev_b64 v[64:65], 12, v[64:65]
	v_lshl_add_u64 v[64:65], v[66:67], 0, v[64:65]
	v_lshl_add_u64 v[144:145], v[64:65], 0, v[214:215]
	v_add_u32_e32 v64, 0xb0, v238
	s_movk_i32 s0, 0x7f50
	v_cmp_gt_i32_e32 vcc, s0, v238
	v_ashrrev_i32_e32 v65, 31, v64
	v_add_u32_e32 v66, 0xffff80b0, v238
	v_pk_fma_f32 v[72:73], v[84:85], v[134:135], v[162:163]
	v_cndmask_b32_e32 v65, 0, v65, vcc
	v_cndmask_b32_e32 v64, v66, v64, vcc
	global_store_dwordx4 v[216:217], v[72:75], off
	v_pk_fma_f32 v[68:69], v[68:69], v[126:127], v[150:151]
	v_cndmask_b32_e32 v67, v241, v242, vcc
	v_pk_fma_f32 v[74:75], v[78:79], v[132:133], v[156:157]
	v_pk_fma_f32 v[72:73], v[76:77], v[130:131], v[154:155]
	v_cndmask_b32_e32 v66, v243, v244, vcc
	v_lshlrev_b64 v[64:65], 12, v[64:65]
	global_store_dwordx4 v[216:217], v[72:75], off offset:64
	global_store_dwordx4 v[216:217], v[68:71], off offset:512
	v_lshl_add_u64 v[64:65], v[66:67], 0, v[64:65]
	global_load_dwordx4 v[138:141], v[148:149], off offset:64
	global_load_dwordx4 v[122:125], v[148:149], off offset:512
	global_load_dwordx4 v[110:113], v[148:149], off offset:576
	v_lshl_add_u64 v[142:143], v[64:65], 0, v[214:215]
	global_load_dwordx4 v[114:117], v[146:147], off
	global_load_dwordx4 v[106:109], v[146:147], off offset:64
	global_load_dwordx4 v[102:105], v[146:147], off offset:512
	global_load_dwordx4 v[92:95], v[146:147], off offset:576
	global_load_dwordx4 v[98:101], v[144:145], off
	global_load_dwordx4 v[88:91], v[144:145], off offset:64
	global_load_dwordx4 v[84:87], v[144:145], off offset:512
	global_load_dwordx4 v[76:79], v[144:145], off offset:576
	global_load_dwordx4 v[80:83], v[142:143], off
	global_load_dwordx4 v[72:75], v[142:143], off offset:64
	global_load_dwordx4 v[68:71], v[142:143], off offset:512
	global_load_dwordx4 v[64:67], v[142:143], off offset:576
	global_load_dwordx4 v[150:153], v[148:149], off
	s_and_b64 vcc, exec, s[36:37]
	s_waitcnt vmcnt(0)
	v_pk_fma_f32 v[58:59], v[58:59], v[132:133], v[140:141]
	v_pk_fma_f32 v[56:57], v[56:57], v[130:131], v[138:139]
	v_pk_fma_f32 v[42:43], v[42:43], v[120:121], v[112:113]
	v_pk_fma_f32 v[40:41], v[40:41], v[118:119], v[110:111]
	v_pk_fma_f32 v[50:51], v[50:51], v[128:129], v[124:125]
	v_pk_fma_f32 v[48:49], v[48:49], v[126:127], v[122:123]
	v_pk_fma_f32 v[62:63], v[62:63], v[136:137], v[152:153]
	v_pk_fma_f32 v[60:61], v[60:61], v[134:135], v[150:151]
	global_store_dwordx4 v[148:149], v[40:43], off offset:576
	v_pk_fma_f32 v[26:27], v[26:27], v[120:121], v[94:95]
	v_pk_fma_f32 v[24:25], v[24:25], v[118:119], v[92:93]
	v_pk_fma_f32 v[42:43], v[54:55], v[136:137], v[116:117]
	v_pk_fma_f32 v[40:41], v[52:53], v[134:135], v[114:115]
	global_store_dwordx4 v[148:149], v[60:63], off
	global_store_dwordx4 v[148:149], v[56:59], off offset:64
	global_store_dwordx4 v[148:149], v[48:51], off offset:512
	global_store_dwordx4 v[146:147], v[40:43], off
	v_pk_fma_f32 v[34:35], v[34:35], v[128:129], v[104:105]
	v_pk_fma_f32 v[32:33], v[32:33], v[126:127], v[102:103]
	v_pk_fma_f32 v[42:43], v[46:47], v[132:133], v[108:109]
	v_pk_fma_f32 v[40:41], v[44:45], v[130:131], v[106:107]
	global_store_dwordx4 v[146:147], v[24:27], off offset:576
	v_pk_fma_f32 v[10:11], v[10:11], v[120:121], v[78:79]
	v_pk_fma_f32 v[8:9], v[8:9], v[118:119], v[76:77]
	v_pk_fma_f32 v[26:27], v[38:39], v[136:137], v[100:101]
	v_pk_fma_f32 v[24:25], v[36:37], v[134:135], v[98:99]
	global_store_dwordx4 v[146:147], v[40:43], off offset:64
	global_store_dwordx4 v[146:147], v[32:35], off offset:512
	global_store_dwordx4 v[144:145], v[24:27], off
	v_pk_fma_f32 v[18:19], v[18:19], v[128:129], v[86:87]
	v_pk_fma_f32 v[16:17], v[16:17], v[126:127], v[84:85]
	v_pk_fma_f32 v[26:27], v[30:31], v[132:133], v[90:91]
	v_pk_fma_f32 v[24:25], v[28:29], v[130:131], v[88:89]
	global_store_dwordx4 v[144:145], v[8:11], off offset:576
	global_store_dwordx4 v[144:145], v[24:27], off offset:64
	global_store_dwordx4 v[144:145], v[16:19], off offset:512
	v_pk_fma_f32 v[10:11], v[22:23], v[136:137], v[82:83]
	v_pk_fma_f32 v[8:9], v[20:21], v[134:135], v[80:81]
	global_store_dwordx4 v[142:143], v[8:11], off
	v_pk_fma_f32 v[6:7], v[6:7], v[128:129], v[70:71]
	v_pk_fma_f32 v[4:5], v[4:5], v[126:127], v[68:69]
	v_pk_fma_f32 v[10:11], v[14:15], v[132:133], v[74:75]
	v_pk_fma_f32 v[8:9], v[12:13], v[130:131], v[72:73]
	v_pk_fma_f32 v[2:3], v[2:3], v[120:121], v[66:67]
	v_pk_fma_f32 v[0:1], v[0:1], v[118:119], v[64:65]
	global_store_dwordx4 v[142:143], v[8:11], off offset:64
	global_store_dwordx4 v[142:143], v[4:7], off offset:512
	global_store_dwordx4 v[142:143], v[0:3], off offset:576
	s_cbranch_vccz .LBB0_44
	s_waitcnt vmcnt(0)
	v_readlane_b32 s66, v255, 34
	v_readlane_b32 s64, v255, 38
	s_cmpk_gt_u32 s56, 0xff
	v_readlane_b32 s67, v255, 35
	v_readlane_b32 s65, v255, 39
	s_cbranch_scc1 .LBB0_51
	s_barrier

; #define PG8_BAR __builtin_amdgcn_s_barrier()
; template <class Epi, class Sched>
; __device__ __forceinline__ void gemm_phase(PG8_LAS unsigned char* lds, const Gemm g, const Sched& S, const Epi& E) {
;     ...
;         const bool has_next = S.next(ui + 1, nxt);
;         const char* nA = has_next ? (const char*)g.A + (size_t)nxt.pm * tstep : cA; const char* nB = has_next ? (const char*)g.Bt + (size_t)nxt.pn * tstep : cB;
;         for (int t = 0; t < nt; t += 2) {
;             const bool last = (t == nt - 2);
;             const char* a1 = cA + (size_t)(t + 1) * kstep;
;             const char* a2 = last ? nA : cA + (size_t)(t + 2) * kstep; const char* b2 = last ? nB : cB + (size_t)(t + 2) * kstep;
;             const char* a3 = a2 + kstep; const char* b3 = b2 + kstep;
;             if (last && has_next) S.a_ready(nxt);
;             PG8_LDB(B0, 0, 0); PG8_SCHED; PG8_LDA(At, 0, 0); PG8_STAGE(PG8_SA(1, 1), a1 + hstep, voffA);
;             PG8_WAIT_L(8); PG8_BAR; PG8_WAIT_L(0); PG8_MMA(0, 0, At, B0); PG8_BAR; PG8_SCHED;
;             PG8_LDB(B1, 0, 1); PG8_STAGE(PG8_SB(0, 0), b2, voffB);
;             PG8_BAR; PG8_WAIT_L(0); PG8_MMA(0, 1, At, B1); PG8_BAR;
;             PG8_LDA(At, 0, 1); PG8_STAGE(PG8_SA(0, 0), a2, voffA);
;             PG8_BAR; PG8_WAIT_L(0); PG8_MMA(1, 0, At, B0); PG8_BAR; PG8_SCHED;
;             PG8_STAGE(PG8_SB(0, 1), b2 + hstep, voffB);
;             PG8_WAIT_V(6); PG8_BAR; PG8_MMA(1, 1, At, B1); PG8_BAR;
;             PG8_LDB(B0, 1, 0); PG8_SCHED; PG8_LDA(At, 1, 0); PG8_STAGE(PG8_SA(0, 1), a2 + hstep, voffA);
;             PG8_WAIT_L(8); PG8_BAR; PG8_WAIT_L(0); PG8_MMA(0, 0, At, B0); PG8_BAR; PG8_SCHED;
;             PG8_LDB(B1, 1, 1); PG8_STAGE(PG8_SB(1, 0), b3, voffB);
;             PG8_BAR; PG8_WAIT_L(0); PG8_MMA(0, 1, At, B1); PG8_BAR;
;             PG8_LDA(At, 1, 1); PG8_STAGE(PG8_SA(1, 0), a3, voffA);
;             PG8_BAR; PG8_WAIT_L(0); PG8_MMA(1, 0, At, B0); PG8_BAR; PG8_SCHED;
;             PG8_STAGE(PG8_SB(1, 1), b3 + hstep, voffB);
;             PG8_WAIT_V(6); PG8_BAR; PG8_MMA(1, 1, At, B1); PG8_BAR;
;         }
;         if constexpr (!Epi::AFTER_DRAIN) { E(acc, cur, wr, wc, fr, fq); S.done(cur); }
;         if (!has_next) break;
; #pragma unroll
;         for (int a = 0; a < 2; ++a)
; #pragma unroll
;             for (int b = 0; b < 2; ++b)
; #pragma unroll
;                 for (int m = 0; m < 4; ++m)
; #pragma unroll
.LBB0_64:
	v_mov_b64_e32 v[0:1], s[54:55]
	s_ashr_i32 s31, s30, 31
	v_cmp_lt_i64_e32 vcc, s[38:39], v[0:1]
	s_lshl_b64 s[38:39], s[30:31], 19
	s_add_u32 s38, s74, s38
	s_addc_u32 s39, s75, s39
	s_and_b64 s[40:41], vcc, exec
	s_cselect_b32 s31, s39, s47
	s_cselect_b32 s66, s38, s46
	s_ashr_i32 s1, s0, 31
	s_lshl_b64 s[40:41], s[0:1], 19
	v_readlane_b32 s42, v251, 7
	v_readlane_b32 s43, v251, 8
	s_add_u32 s40, s42, s40
	s_addc_u32 s41, s43, s41
	s_and_b64 s[50:51], vcc, exec
	s_cselect_b32 s1, s41, s49
	s_cselect_b32 s67, s40, s48
	s_add_u32 s46, s46, 0x40080
	s_addc_u32 s47, s47, 0
	s_add_u32 s68, s48, 0x100
	v_mov_b32_e32 v0, 0
	s_addc_u32 s69, s49, 0
	s_mov_b32 s70, -2
	v_mov_b32_e32 v1, v0
	v_mov_b32_e32 v2, v0
	v_mov_b32_e32 v3, v0
	v_mov_b32_e32 v4, v0
	v_mov_b32_e32 v5, v0
	v_mov_b32_e32 v6, v0
	v_mov_b32_e32 v7, v0
	v_mov_b32_e32 v16, v0
	v_mov_b32_e32 v17, v0
	v_mov_b32_e32 v18, v0
	v_mov_b32_e32 v19, v0
	v_mov_b32_e32 v20, v0
	v_mov_b32_e32 v21, v0
	v_mov_b32_e32 v22, v0
	v_mov_b32_e32 v23, v0
	v_mov_b32_e32 v32, v0
	v_mov_b32_e32 v33, v0
	v_mov_b32_e32 v34, v0
	v_mov_b32_e32 v35, v0
	v_mov_b32_e32 v36, v0
	v_mov_b32_e32 v37, v0
	v_mov_b32_e32 v38, v0
	v_mov_b32_e32 v39, v0
	v_mov_b32_e32 v48, v0
	v_mov_b32_e32 v49, v0
	v_mov_b32_e32 v50, v0
	v_mov_b32_e32 v51, v0
	v_mov_b32_e32 v52, v0
	v_mov_b32_e32 v53, v0
	v_mov_b32_e32 v54, v0
	v_mov_b32_e32 v55, v0
	v_mov_b32_e32 v8, v0
	v_mov_b32_e32 v9, v0
	v_mov_b32_e32 v10, v0
	v_mov_b32_e32 v11, v0
	v_mov_b32_e32 v12, v0
	v_mov_b32_e32 v13, v0
	v_mov_b32_e32 v14, v0
	v_mov_b32_e32 v15, v0
	v_mov_b32_e32 v24, v0
	v_mov_b32_e32 v25, v0
	v_mov_b32_e32 v26, v0
	v_mov_b32_e32 v27, v0
	v_mov_b32_e32 v28, v0
	v_mov_b32_e32 v29, v0
	v_mov_b32_e32 v30, v0
	v_mov_b32_e32 v31, v0
	v_mov_b32_e32 v40, v0
	v_mov_b32_e32 v41, v0
	v_mov_b32_e32 v42, v0
	v_mov_b32_e32 v43, v0
	v_mov_b32_e32 v44, v0
	v_mov_b32_e32 v45, v0
	v_mov_b32_e32 v46, v0
	v_mov_b32_e32 v47, v0
	v_mov_b32_e32 v56, v0
	v_mov_b32_e32 v57, v0
	v_mov_b32_e32 v58, v0
	v_mov_b32_e32 v59, v0
	v_mov_b32_e32 v60, v0
	v_mov_b32_e32 v61, v0
	v_mov_b32_e32 v62, v0
	v_mov_b32_e32 v63, v0
	v_mov_b32_e32 v64, v0
	v_mov_b32_e32 v65, v0
	v_mov_b32_e32 v66, v0
	v_mov_b32_e32 v67, v0
	v_mov_b32_e32 v68, v0
	v_mov_b32_e32 v69, v0
	v_mov_b32_e32 v70, v0
	v_mov_b32_e32 v71, v0
	v_mov_b32_e32 v80, v0
	v_mov_b32_e32 v81, v0
	v_mov_b32_e32 v82, v0
	v_mov_b32_e32 v83, v0
	v_mov_b32_e32 v84, v0
	v_mov_b32_e32 v85, v0
	v_mov_b32_e32 v86, v0
	v_mov_b32_e32 v87, v0
	v_mov_b32_e32 v98, v0
	v_mov_b32_e32 v99, v0
	v_mov_b32_e32 v100, v0
	v_mov_b32_e32 v101, v0
	v_mov_b32_e32 v102, v0
	v_mov_b32_e32 v103, v0
	v_mov_b32_e32 v104, v0
	v_mov_b32_e32 v105, v0
	v_mov_b32_e32 v114, v0
	v_mov_b32_e32 v115, v0
	v_mov_b32_e32 v116, v0
	v_mov_b32_e32 v117, v0
	v_mov_b32_e32 v118, v0
	v_mov_b32_e32 v119, v0
	v_mov_b32_e32 v120, v0
	v_mov_b32_e32 v121, v0
	v_mov_b32_e32 v72, v0
	v_mov_b32_e32 v73, v0
	v_mov_b32_e32 v74, v0
	v_mov_b32_e32 v75, v0
	v_mov_b32_e32 v76, v0
	v_mov_b32_e32 v77, v0
	v_mov_b32_e32 v78, v0
	v_mov_b32_e32 v79, v0
	v_mov_b32_e32 v88, v0
	v_mov_b32_e32 v89, v0
	v_mov_b32_e32 v90, v0
	v_mov_b32_e32 v91, v0
	v_mov_b32_e32 v92, v0
	v_mov_b32_e32 v93, v0
	v_mov_b32_e32 v94, v0
	v_mov_b32_e32 v95, v0
	v_mov_b32_e32 v106, v0
	v_mov_b32_e32 v107, v0
	v_mov_b32_e32 v108, v0
	v_mov_b32_e32 v109, v0
	v_mov_b32_e32 v110, v0
	v_mov_b32_e32 v111, v0
	v_mov_b32_e32 v112, v0
	v_mov_b32_e32 v113, v0
	v_mov_b32_e32 v122, v0
	v_mov_b32_e32 v123, v0
	v_mov_b32_e32 v124, v0
	v_mov_b32_e32 v125, v0
	v_mov_b32_e32 v126, v0
	v_mov_b32_e32 v127, v0
	v_mov_b32_e32 v128, v0
	v_mov_b32_e32 v129, v0
	v_readfirstlane_b32 s100, v226
	s_nop 3
	s_lshr_b32 s100, s100, 8
	s_cmp_eq_u32 s100, 0
	s_cbranch_scc1 .Lgp_2972
	s_setprio 1
.Lgp_2972:
.LBB0_65:
	s_add_u32 s42, s46, 0xfffc0080
	s_addc_u32 s43, s47, -1
	s_add_i32 s71, 0, 0x10000
	v_add_u32_e32 v156, s71, v141
	ds_read_b128 v[144:147], v156
	ds_read_b128 v[148:151], v156 offset:1024
	ds_read_b128 v[152:155], v156 offset:2048
	ds_read_b128 v[156:159], v156 offset:3072
	s_cmp_eq_u32 s70, 12
	s_cselect_b32 s51, s31, s43
	s_cselect_b32 s50, s66, s42
	s_cselect_b32 s49, s1, s69
	s_cselect_b32 s48, s67, s68
	v_lshl_add_u64 v[192:193], s[46:47], 0, v[136:137]
	s_add_i32 m0, s45, 0xc000
	ds_read_b128 v[160:163], v143
	ds_read_b128 v[164:167], v143 offset:1024
	ds_read_b128 v[168:171], v143 offset:2048
	ds_read_b128 v[172:175], v143 offset:3072
	ds_read_b128 v[176:179], v143 offset:4096
	ds_read_b128 v[180:183], v143 offset:5120
	ds_read_b128 v[184:187], v143 offset:6144
	ds_read_b128 v[188:191], v143 offset:7168
	global_load_lds_dwordx4 v[192:193], off
	v_lshl_add_u64 v[192:193], s[46:47], 0, v[138:139]
	s_add_i32 m0, s45, 0xe000
	s_nop 0
	global_load_lds_dwordx4 v[192:193], off
	s_waitcnt lgkmcnt(8)
	s_barrier
	s_waitcnt lgkmcnt(0)
	s_waitcnt lgkmcnt(0)
	v_mfma_f32_16x16x32_bf16 v[126:129], v[144:147], v[160:163], v[126:129]
	v_mfma_f32_16x16x32_bf16 v[122:125], v[152:155], v[160:163], v[122:125]
	v_mfma_f32_16x16x32_bf16 v[110:113], v[144:147], v[168:171], v[110:113]
	v_mfma_f32_16x16x32_bf16 v[106:109], v[152:155], v[168:171], v[106:109]
	v_mfma_f32_16x16x32_bf16 v[92:95], v[144:147], v[176:179], v[92:95]
	v_mfma_f32_16x16x32_bf16 v[88:91], v[152:155], v[176:179], v[88:91]
	v_mfma_f32_16x16x32_bf16 v[76:79], v[144:147], v[184:187], v[76:79]
	v_mfma_f32_16x16x32_bf16 v[72:75], v[152:155], v[184:187], v[72:75]
	v_mfma_f32_16x16x32_bf16 v[126:129], v[148:151], v[164:167], v[126:129]
	v_mfma_f32_16x16x32_bf16 v[122:125], v[156:159], v[164:167], v[122:125]
	v_mfma_f32_16x16x32_bf16 v[110:113], v[148:151], v[172:175], v[110:113]
	v_mfma_f32_16x16x32_bf16 v[106:109], v[156:159], v[172:175], v[106:109]
	v_mfma_f32_16x16x32_bf16 v[92:95], v[148:151], v[180:183], v[92:95]
	v_mfma_f32_16x16x32_bf16 v[88:91], v[156:159], v[180:183], v[88:91]
	v_mfma_f32_16x16x32_bf16 v[76:79], v[148:151], v[188:191], v[76:79]
	v_mfma_f32_16x16x32_bf16 v[72:75], v[156:159], v[188:191], v[72:75]
	s_barrier
; #define PG8_STAGE(bufoff, gbase, voff) do { _Pragma("unroll") for (int _i = 0; _i < 2; ++_i) \
;         __builtin_amdgcn_global_load_lds((const unsigned*)((const char*)(gbase) + (voff)[_i]), (PG8_LAS unsigned*)(lds + (bufoff) + ldsw + _i * 8192), 16, 0, 0); } while (0)
; #define PG8_LDA(dst, b, h) do { _Pragma("unroll") for (int m = 0; m < 4; ++m) _Pragma("unroll") for (int k = 0; k < 2; ++k) dst[m][k] = *(const PG8_LAS bf16x8*)(lds + PG8_SA(b, h) + aoff + m * 2048 + k * 1024); } while (0)
; #define PG8_LDB(dst, b, h) do { _Pragma("unroll") for (int n = 0; n < 2; ++n) _Pragma("unroll") for (int k = 0; k < 2; ++k) dst[n][k] = *(const PG8_LAS bf16x8*)(lds + PG8_SB(b, h) + boff + n * 2048 + k * 1024); } while (0)
; #define PG8_MMA(ai, bj, At, Bt) do { __builtin_amdgcn_s_setprio(1); _Pragma("unroll") for (int m = 0; m < 4; ++m) _Pragma("unroll") for (int n = 0; n < 2; ++n) _Pragma("unroll") for (int k = 0; k < 2; ++k) \
;         acc[ai][bj][m][n] = __builtin_amdgcn_mfma_f32_16x16x32_bf16(Bt[n][k], At[m][k], acc[ai][bj][m][n], 0, 0, 0); __builtin_amdgcn_s_setprio(0); } while (0)
; #define PG8_WAIT_V(n) asm volatile("s_waitcnt vmcnt(" #n ")" ::: "memory")
; #define PG8_WAIT_L(n) asm volatile("s_waitcnt lgkmcnt(" #n ")" ::: "memory")
; #define PG8_BAR __builtin_amdgcn_s_barrier()
; #define PG8_SCHED __builtin_amdgcn_sched_barrier(0)
; template <class Epi, class Sched>
; __device__ __forceinline__ void gemm_phase(PG8_LAS unsigned char* lds, const Gemm g, const Sched& S, const Epi& E) {
;     ...
;             PG8_LDB(B1, 0, 1); PG8_STAGE(PG8_SB(0, 0), b2, voffB);
;             PG8_BAR; PG8_WAIT_L(0); PG8_MMA(0, 1, At, B1); PG8_BAR;
;             PG8_LDA(At, 0, 1); PG8_STAGE(PG8_SA(0, 0), a2, voffA);
;             PG8_BAR; PG8_WAIT_L(0); PG8_MMA(1, 0, At, B0); PG8_BAR; PG8_SCHED;
;             PG8_STAGE(PG8_SB(0, 1), b2 + hstep, voffB);
;             PG8_WAIT_V(6); PG8_BAR; PG8_MMA(1, 1, At, B1); PG8_BAR;
;             PG8_LDB(B0, 1, 0); PG8_SCHED; PG8_LDA(At, 1, 0); PG8_STAGE(PG8_SA(0, 1), a2 + hstep, voffA);
;             PG8_WAIT_L(8); PG8_BAR; PG8_WAIT_L(0); PG8_MMA(0, 0, At, B0); PG8_BAR; PG8_SCHED;
	s_add_i32 s42, 0, 0x14000
	v_add_u32_e32 v204, s42, v141
	s_add_i32 s43, s71, s56
	ds_read_b128 v[192:195], v204
	ds_read_b128 v[196:199], v204 offset:1024
	ds_read_b128 v[200:203], v204 offset:2048
	ds_read_b128 v[208:211], v204 offset:3072
	v_lshl_add_u64 v[204:205], s[48:49], 0, v[96:97]
	s_mov_b32 m0, s43
	v_lshl_add_u64 v[212:213], s[48:49], 0, v[130:131]
	global_load_lds_dwordx4 v[204:205], off
	s_add_i32 m0, s43, 0x2000
	s_nop 0
	global_load_lds_dwordx4 v[212:213], off
	s_barrier
	s_waitcnt lgkmcnt(0)
	s_waitcnt lgkmcnt(0)
	v_mfma_f32_16x16x32_bf16 v[118:121], v[192:195], v[160:163], v[118:121]
	v_mfma_f32_16x16x32_bf16 v[114:117], v[200:203], v[160:163], v[114:117]
	v_mfma_f32_16x16x32_bf16 v[102:105], v[192:195], v[168:171], v[102:105]
	v_mfma_f32_16x16x32_bf16 v[98:101], v[200:203], v[168:171], v[98:101]
	v_mfma_f32_16x16x32_bf16 v[84:87], v[192:195], v[176:179], v[84:87]
	v_mfma_f32_16x16x32_bf16 v[80:83], v[200:203], v[176:179], v[80:83]
	v_mfma_f32_16x16x32_bf16 v[68:71], v[192:195], v[184:187], v[68:71]
	v_mfma_f32_16x16x32_bf16 v[64:67], v[200:203], v[184:187], v[64:67]
	v_mfma_f32_16x16x32_bf16 v[118:121], v[196:199], v[164:167], v[118:121]
	v_mfma_f32_16x16x32_bf16 v[114:117], v[208:211], v[164:167], v[114:117]
	v_mfma_f32_16x16x32_bf16 v[102:105], v[196:199], v[172:175], v[102:105]
	v_mfma_f32_16x16x32_bf16 v[98:101], v[208:211], v[172:175], v[98:101]
	v_mfma_f32_16x16x32_bf16 v[84:87], v[196:199], v[180:183], v[84:87]
	v_mfma_f32_16x16x32_bf16 v[80:83], v[208:211], v[180:183], v[80:83]
	v_mfma_f32_16x16x32_bf16 v[68:71], v[196:199], v[188:191], v[68:71]
	v_mfma_f32_16x16x32_bf16 v[64:67], v[208:211], v[188:191], v[64:67]
	s_mov_b32 m0, s45
	v_lshl_add_u64 v[214:215], s[50:51], 0, v[134:135]
	s_barrier
	ds_read_b128 v[160:163], v143 offset:16384
	ds_read_b128 v[164:167], v143 offset:17408
	ds_read_b128 v[168:171], v143 offset:18432
	ds_read_b128 v[172:175], v143 offset:19456
	ds_read_b128 v[176:179], v143 offset:20480
	ds_read_b128 v[180:183], v143 offset:21504
	ds_read_b128 v[184:187], v143 offset:22528
	ds_read_b128 v[188:191], v143 offset:23552
	global_load_lds_dwordx4 v[214:215], off
	v_lshl_add_u64 v[216:217], s[50:51], 0, v[132:133]
	s_mov_b32 m0, s59
	s_nop 0
	global_load_lds_dwordx4 v[216:217], off
	s_barrier
	s_waitcnt lgkmcnt(0)
	s_waitcnt lgkmcnt(0)
	v_mfma_f32_16x16x32_bf16 v[60:63], v[144:147], v[160:163], v[60:63]
	v_mfma_f32_16x16x32_bf16 v[56:59], v[152:155], v[160:163], v[56:59]
	v_mfma_f32_16x16x32_bf16 v[44:47], v[144:147], v[168:171], v[44:47]
	v_mfma_f32_16x16x32_bf16 v[40:43], v[152:155], v[168:171], v[40:43]
	v_mfma_f32_16x16x32_bf16 v[28:31], v[144:147], v[176:179], v[28:31]
	v_mfma_f32_16x16x32_bf16 v[24:27], v[152:155], v[176:179], v[24:27]
	v_mfma_f32_16x16x32_bf16 v[12:15], v[144:147], v[184:187], v[12:15]
	v_mfma_f32_16x16x32_bf16 v[8:11], v[152:155], v[184:187], v[8:11]
	v_mfma_f32_16x16x32_bf16 v[60:63], v[148:151], v[164:167], v[60:63]
	v_mfma_f32_16x16x32_bf16 v[56:59], v[156:159], v[164:167], v[56:59]
	v_mfma_f32_16x16x32_bf16 v[44:47], v[148:151], v[172:175], v[44:47]
	v_mfma_f32_16x16x32_bf16 v[40:43], v[156:159], v[172:175], v[40:43]
	v_mfma_f32_16x16x32_bf16 v[28:31], v[148:151], v[180:183], v[28:31]
	v_mfma_f32_16x16x32_bf16 v[24:27], v[156:159], v[180:183], v[24:27]
	v_mfma_f32_16x16x32_bf16 v[12:15], v[148:151], v[188:191], v[12:15]
	v_mfma_f32_16x16x32_bf16 v[8:11], v[156:159], v[188:191], v[8:11]
	s_barrier
	s_add_u32 vcc_lo, s48, 0x40000
	s_addc_u32 vcc_hi, s49, 0
	s_add_i32 s42, s42, s56
	v_lshl_add_u64 v[144:145], vcc, 0, v[96:97]
	s_mov_b32 m0, s42
	s_nop 0
	global_load_lds_dwordx4 v[144:145], off
	v_lshl_add_u64 v[144:145], vcc, 0, v[130:131]
	s_add_i32 m0, s42, 0x2000
	s_nop 0
	global_load_lds_dwordx4 v[144:145], off
	s_waitcnt vmcnt(6)
	s_barrier
	v_mfma_f32_16x16x32_bf16 v[52:55], v[192:195], v[160:163], v[52:55]
	v_mfma_f32_16x16x32_bf16 v[48:51], v[200:203], v[160:163], v[48:51]
	v_mfma_f32_16x16x32_bf16 v[36:39], v[192:195], v[168:171], v[36:39]
	v_mfma_f32_16x16x32_bf16 v[32:35], v[200:203], v[168:171], v[32:35]
	v_mfma_f32_16x16x32_bf16 v[20:23], v[192:195], v[176:179], v[20:23]
	v_mfma_f32_16x16x32_bf16 v[16:19], v[200:203], v[176:179], v[16:19]
	v_mfma_f32_16x16x32_bf16 v[4:7], v[192:195], v[184:187], v[4:7]
	v_mfma_f32_16x16x32_bf16 v[0:3], v[200:203], v[184:187], v[0:3]
	v_mfma_f32_16x16x32_bf16 v[52:55], v[196:199], v[164:167], v[52:55]
	v_mfma_f32_16x16x32_bf16 v[48:51], v[208:211], v[164:167], v[48:51]
	v_mfma_f32_16x16x32_bf16 v[36:39], v[196:199], v[172:175], v[36:39]
	v_mfma_f32_16x16x32_bf16 v[32:35], v[208:211], v[172:175], v[32:35]
	v_mfma_f32_16x16x32_bf16 v[20:23], v[196:199], v[180:183], v[20:23]
	v_mfma_f32_16x16x32_bf16 v[16:19], v[208:211], v[180:183], v[16:19]
	v_mfma_f32_16x16x32_bf16 v[4:7], v[196:199], v[188:191], v[4:7]
	v_mfma_f32_16x16x32_bf16 v[0:3], v[208:211], v[188:191], v[0:3]
	s_add_i32 s42, 0, 0x18000
	v_add_u32_e32 v156, s42, v141
	s_barrier
	ds_read_b128 v[144:147], v156
	ds_read_b128 v[148:151], v156 offset:1024
	ds_read_b128 v[152:155], v156 offset:2048
	ds_read_b128 v[156:159], v156 offset:3072
	s_add_u32 s50, s50, 0x40000
	s_addc_u32 s51, s51, 0
	s_mov_b32 m0, s60
	v_lshl_add_u64 v[192:193], s[50:51], 0, v[134:135]
	ds_read_b128 v[160:163], v143 offset:32768
	ds_read_b128 v[164:167], v143 offset:33792
	ds_read_b128 v[168:171], v143 offset:34816
	ds_read_b128 v[172:175], v143 offset:35840
	ds_read_b128 v[176:179], v143 offset:36864
	ds_read_b128 v[180:183], v143 offset:37888
	ds_read_b128 v[184:187], v143 offset:38912
	ds_read_b128 v[188:191], v143 offset:39936
	global_load_lds_dwordx4 v[192:193], off
	v_lshl_add_u64 v[192:193], s[50:51], 0, v[132:133]
	s_mov_b32 m0, s61
	s_nop 0
	global_load_lds_dwordx4 v[192:193], off
	s_waitcnt lgkmcnt(8)
	s_barrier
; #define PG8_STAGE(bufoff, gbase, voff) do { _Pragma("unroll") for (int _i = 0; _i < 2; ++_i) \
;         __builtin_amdgcn_global_load_lds((const unsigned*)((const char*)(gbase) + (voff)[_i]), (PG8_LAS unsigned*)(lds + (bufoff) + ldsw + _i * 8192), 16, 0, 0); } while (0)
; #define PG8_LDA(dst, b, h) do { _Pragma("unroll") for (int m = 0; m < 4; ++m) _Pragma("unroll") for (int k = 0; k < 2; ++k) dst[m][k] = *(const PG8_LAS bf16x8*)(lds + PG8_SA(b, h) + aoff + m * 2048 + k * 1024); } while (0)
; #define PG8_LDB(dst, b, h) do { _Pragma("unroll") for (int n = 0; n < 2; ++n) _Pragma("unroll") for (int k = 0; k < 2; ++k) dst[n][k] = *(const PG8_LAS bf16x8*)(lds + PG8_SB(b, h) + boff + n * 2048 + k * 1024); } while (0)
; #define PG8_MMA(ai, bj, At, Bt) do { __builtin_amdgcn_s_setprio(1); _Pragma("unroll") for (int m = 0; m < 4; ++m) _Pragma("unroll") for (int n = 0; n < 2; ++n) _Pragma("unroll") for (int k = 0; k < 2; ++k) \
;         acc[ai][bj][m][n] = __builtin_amdgcn_mfma_f32_16x16x32_bf16(Bt[n][k], At[m][k], acc[ai][bj][m][n], 0, 0, 0); __builtin_amdgcn_s_setprio(0); } while (0)
; #define PG8_WAIT_V(n) asm volatile("s_waitcnt vmcnt(" #n ")" ::: "memory")
; #define PG8_WAIT_L(n) asm volatile("s_waitcnt lgkmcnt(" #n ")" ::: "memory")
; #define PG8_BAR __builtin_amdgcn_s_barrier()
; #define PG8_SCHED __builtin_amdgcn_sched_barrier(0)
; template <class Epi, class Sched>
; __device__ __forceinline__ void gemm_phase(PG8_LAS unsigned char* lds, const Gemm g, const Sched& S, const Epi& E) {
;     ...
;             PG8_WAIT_L(8); PG8_BAR; PG8_WAIT_L(0); PG8_MMA(0, 0, At, B0); PG8_BAR; PG8_SCHED;
;             PG8_LDB(B1, 1, 1); PG8_STAGE(PG8_SB(1, 0), b3, voffB);
;             PG8_BAR; PG8_WAIT_L(0); PG8_MMA(0, 1, At, B1); PG8_BAR;
;             PG8_LDA(At, 1, 1); PG8_STAGE(PG8_SA(1, 0), a3, voffA);
;             PG8_BAR; PG8_WAIT_L(0); PG8_MMA(1, 0, At, B0); PG8_BAR; PG8_SCHED;
;             PG8_STAGE(PG8_SB(1, 1), b3 + hstep, voffB);
;             PG8_WAIT_V(6); PG8_BAR; PG8_MMA(1, 1, At, B1); PG8_BAR;
;         }
	s_waitcnt lgkmcnt(0)
	s_waitcnt lgkmcnt(0)
	v_mfma_f32_16x16x32_bf16 v[126:129], v[144:147], v[160:163], v[126:129]
	v_mfma_f32_16x16x32_bf16 v[122:125], v[152:155], v[160:163], v[122:125]
	v_mfma_f32_16x16x32_bf16 v[110:113], v[144:147], v[168:171], v[110:113]
	v_mfma_f32_16x16x32_bf16 v[106:109], v[152:155], v[168:171], v[106:109]
	v_mfma_f32_16x16x32_bf16 v[92:95], v[144:147], v[176:179], v[92:95]
	v_mfma_f32_16x16x32_bf16 v[88:91], v[152:155], v[176:179], v[88:91]
	v_mfma_f32_16x16x32_bf16 v[76:79], v[144:147], v[184:187], v[76:79]
	v_mfma_f32_16x16x32_bf16 v[72:75], v[152:155], v[184:187], v[72:75]
	v_mfma_f32_16x16x32_bf16 v[126:129], v[148:151], v[164:167], v[126:129]
	v_mfma_f32_16x16x32_bf16 v[122:125], v[156:159], v[164:167], v[122:125]
	v_mfma_f32_16x16x32_bf16 v[110:113], v[148:151], v[172:175], v[110:113]
	v_mfma_f32_16x16x32_bf16 v[106:109], v[156:159], v[172:175], v[106:109]
	v_mfma_f32_16x16x32_bf16 v[92:95], v[148:151], v[180:183], v[92:95]
	v_mfma_f32_16x16x32_bf16 v[88:91], v[156:159], v[180:183], v[88:91]
	v_mfma_f32_16x16x32_bf16 v[76:79], v[148:151], v[188:191], v[76:79]
	v_mfma_f32_16x16x32_bf16 v[72:75], v[156:159], v[188:191], v[72:75]
	s_barrier
	s_add_i32 s43, 0, 0x1c000
	s_add_i32 s42, s42, s56
	v_add_u32_e32 v208, s43, v141
	v_lshl_add_u64 v[204:205], v[204:205], 0, s[2:3]
	s_mov_b32 m0, s42
	ds_read_b128 v[192:195], v208
	ds_read_b128 v[196:199], v208 offset:1024
	ds_read_b128 v[200:203], v208 offset:2048
	ds_read_b128 v[208:211], v208 offset:3072
	global_load_lds_dwordx4 v[204:205], off
	v_lshl_add_u64 v[204:205], v[212:213], 0, s[2:3]
	s_add_i32 m0, s42, 0x2000
	s_nop 0
	global_load_lds_dwordx4 v[204:205], off
	s_barrier
	s_waitcnt lgkmcnt(0)
	s_waitcnt lgkmcnt(0)
	v_mfma_f32_16x16x32_bf16 v[118:121], v[192:195], v[160:163], v[118:121]
	v_mfma_f32_16x16x32_bf16 v[114:117], v[200:203], v[160:163], v[114:117]
	v_mfma_f32_16x16x32_bf16 v[102:105], v[192:195], v[168:171], v[102:105]
	v_mfma_f32_16x16x32_bf16 v[98:101], v[200:203], v[168:171], v[98:101]
	v_mfma_f32_16x16x32_bf16 v[84:87], v[192:195], v[176:179], v[84:87]
	v_mfma_f32_16x16x32_bf16 v[80:83], v[200:203], v[176:179], v[80:83]
	v_mfma_f32_16x16x32_bf16 v[68:71], v[192:195], v[184:187], v[68:71]
	v_mfma_f32_16x16x32_bf16 v[64:67], v[200:203], v[184:187], v[64:67]
	v_mfma_f32_16x16x32_bf16 v[118:121], v[196:199], v[164:167], v[118:121]
	v_mfma_f32_16x16x32_bf16 v[114:117], v[208:211], v[164:167], v[114:117]
	v_mfma_f32_16x16x32_bf16 v[102:105], v[196:199], v[172:175], v[102:105]
	v_mfma_f32_16x16x32_bf16 v[98:101], v[208:211], v[172:175], v[98:101]
	v_mfma_f32_16x16x32_bf16 v[84:87], v[196:199], v[180:183], v[84:87]
	v_mfma_f32_16x16x32_bf16 v[80:83], v[208:211], v[180:183], v[80:83]
	v_mfma_f32_16x16x32_bf16 v[68:71], v[196:199], v[188:191], v[68:71]
	v_mfma_f32_16x16x32_bf16 v[64:67], v[208:211], v[188:191], v[64:67]
	s_mov_b32 m0, s62
	v_lshl_add_u64 v[204:205], v[214:215], 0, s[2:3]
	s_barrier
	ds_read_b128 v[160:163], v143 offset:49152
	ds_read_b128 v[164:167], v143 offset:50176
	ds_read_b128 v[168:171], v143 offset:51200
	ds_read_b128 v[172:175], v143 offset:52224
	ds_read_b128 v[176:179], v143 offset:53248
	ds_read_b128 v[180:183], v143 offset:54272
	ds_read_b128 v[184:187], v143 offset:55296
	ds_read_b128 v[188:191], v143 offset:56320
	global_load_lds_dwordx4 v[204:205], off
	v_lshl_add_u64 v[204:205], v[216:217], 0, s[2:3]
	s_mov_b32 m0, s63
	s_nop 0
	global_load_lds_dwordx4 v[204:205], off
	s_barrier
	s_waitcnt lgkmcnt(0)
	s_waitcnt lgkmcnt(0)
	v_mfma_f32_16x16x32_bf16 v[60:63], v[144:147], v[160:163], v[60:63]
	v_mfma_f32_16x16x32_bf16 v[56:59], v[152:155], v[160:163], v[56:59]
	v_mfma_f32_16x16x32_bf16 v[44:47], v[144:147], v[168:171], v[44:47]
	v_mfma_f32_16x16x32_bf16 v[40:43], v[152:155], v[168:171], v[40:43]
	v_mfma_f32_16x16x32_bf16 v[28:31], v[144:147], v[176:179], v[28:31]
	v_mfma_f32_16x16x32_bf16 v[24:27], v[152:155], v[176:179], v[24:27]
	v_mfma_f32_16x16x32_bf16 v[12:15], v[144:147], v[184:187], v[12:15]
	v_mfma_f32_16x16x32_bf16 v[8:11], v[152:155], v[184:187], v[8:11]
	v_mfma_f32_16x16x32_bf16 v[60:63], v[148:151], v[164:167], v[60:63]
	v_mfma_f32_16x16x32_bf16 v[56:59], v[156:159], v[164:167], v[56:59]
	v_mfma_f32_16x16x32_bf16 v[44:47], v[148:151], v[172:175], v[44:47]
	v_mfma_f32_16x16x32_bf16 v[40:43], v[156:159], v[172:175], v[40:43]
	v_mfma_f32_16x16x32_bf16 v[28:31], v[148:151], v[180:183], v[28:31]
	v_mfma_f32_16x16x32_bf16 v[24:27], v[156:159], v[180:183], v[24:27]
	v_mfma_f32_16x16x32_bf16 v[12:15], v[148:151], v[188:191], v[12:15]
	v_mfma_f32_16x16x32_bf16 v[8:11], v[156:159], v[188:191], v[8:11]
	s_barrier
	s_add_u32 s48, s48, 0x40080
	s_addc_u32 s49, s49, 0
	s_add_i32 s42, s43, s56
	v_lshl_add_u64 v[144:145], s[48:49], 0, v[96:97]
	s_mov_b32 m0, s42
	s_nop 0
	global_load_lds_dwordx4 v[144:145], off
	v_lshl_add_u64 v[144:145], s[48:49], 0, v[130:131]
	s_add_i32 m0, s42, 0x2000
	s_nop 0
	global_load_lds_dwordx4 v[144:145], off
	s_waitcnt vmcnt(6)
	s_barrier
	v_mfma_f32_16x16x32_bf16 v[52:55], v[192:195], v[160:163], v[52:55]
	v_mfma_f32_16x16x32_bf16 v[48:51], v[200:203], v[160:163], v[48:51]
	v_mfma_f32_16x16x32_bf16 v[36:39], v[192:195], v[168:171], v[36:39]
	v_mfma_f32_16x16x32_bf16 v[32:35], v[200:203], v[168:171], v[32:35]
	v_mfma_f32_16x16x32_bf16 v[20:23], v[192:195], v[176:179], v[20:23]
	v_mfma_f32_16x16x32_bf16 v[16:19], v[200:203], v[176:179], v[16:19]
	v_mfma_f32_16x16x32_bf16 v[4:7], v[192:195], v[184:187], v[4:7]
	v_mfma_f32_16x16x32_bf16 v[0:3], v[200:203], v[184:187], v[0:3]
	v_mfma_f32_16x16x32_bf16 v[52:55], v[196:199], v[164:167], v[52:55]
	v_mfma_f32_16x16x32_bf16 v[48:51], v[208:211], v[164:167], v[48:51]
	v_mfma_f32_16x16x32_bf16 v[36:39], v[196:199], v[172:175], v[36:39]
	v_mfma_f32_16x16x32_bf16 v[32:35], v[208:211], v[172:175], v[32:35]
	v_mfma_f32_16x16x32_bf16 v[20:23], v[196:199], v[180:183], v[20:23]
	v_mfma_f32_16x16x32_bf16 v[16:19], v[208:211], v[180:183], v[16:19]
	v_mfma_f32_16x16x32_bf16 v[4:7], v[196:199], v[188:191], v[4:7]
	v_mfma_f32_16x16x32_bf16 v[0:3], v[208:211], v[188:191], v[0:3]
	s_add_i32 s70, s70, 2
	s_add_u32 s46, s46, 0x100
	s_addc_u32 s47, s47, 0
	s_add_u32 s68, s68, 0x100
	s_addc_u32 s69, s69, 0
	s_cmp_gt_u32 s70, 13
	s_barrier
;   DEV void operator()(const f32x4 (&acc)[2][2][4][2], const pg8::Unit& u, int wr, int wc, int fr, int fq) const {
;     const int row0 = u.pm * 256 + wr * 64 + fr, col0 = u.pn * 256 + wc * 32 + 8 * fq;
; #pragma unroll
;     for (int ai = 0; ai < 2; ++ai)
; #pragma unroll
;       for (int m = 0; m < 4; ++m) {
;         const int row = row0 + ai * 128 + m * 16;
; #pragma unroll
;         for (int bj = 0; bj < 2; ++bj) {
;           float v[8];
; #pragma unroll
;           for (int j = 0; j < 4; ++j) {
;             const float r0 = fmaxf(acc[ai][bj][m][0][j], 0.f), r1 = fmaxf(acc[ai][bj][m][1][j], 0.f);
;             v[j] = r0 * r0; v[4 + j] = r1 * r1;
;           }
;           u32x4 o;
;           o[0] = pk2(v[0], v[1]); o[1] = pk2(v[2], v[3]); o[2] = pk2(v[4], v[5]); o[3] = pk2(v[6], v[7]);
;           *(u32x4*)(HID + (size_t)row * 4096 + col0 + bj * 128) = o;
;         }
;       }
	s_cbranch_scc0 .LBB0_65
	v_lshl_add_u32 v144, s44, 8, v140
	v_max_f32_e32 v126, v126, v126
	v_max_f32_e32 v122, v122, v122
	v_max_f32_e32 v127, v127, v127
	v_max_f32_e32 v123, v123, v123
	v_max_f32_e32 v128, v128, v128
	v_max_f32_e32 v129, v129, v129
	v_lshl_or_b32 v146, s65, 8, v142
	v_ashrrev_i32_e32 v145, 31, v144
	v_max_f32_e32 v126, 0, v126
	v_max_f32_e32 v122, 0, v122
	v_max_f32_e32 v127, 0, v127
	v_max_f32_e32 v123, 0, v123
	v_max_f32_e32 v128, 0, v128
	v_max_f32_e32 v124, v124, v124
	v_max_f32_e32 v129, 0, v129
	v_max_f32_e32 v125, v125, v125
	v_readlane_b32 s42, v251, 49
	v_ashrrev_i32_e32 v147, 31, v146
	v_lshlrev_b64 v[148:149], 13, v[144:145]
	v_pk_mul_f32 v[126:127], v[126:127], v[126:127]
	v_pk_mul_f32 v[122:123], v[122:123], v[122:123]
	v_max_f32_e32 v124, 0, v124
	v_max_f32_e32 v125, 0, v125
	v_pk_mul_f32 v[128:129], v[128:129], v[128:129]
	v_readlane_b32 s43, v251, 50
	v_pk_mul_f32 v[150:151], v[124:125], v[124:125]
	v_cvt_pk_bf16_f32 v124, v126, v127
	v_cvt_pk_bf16_f32 v125, v128, v129
	v_cvt_pk_bf16_f32 v126, v122, v123
	v_lshl_add_u64 v[122:123], s[42:43], 0, v[148:149]
	v_lshlrev_b64 v[128:129], 1, v[146:147]
	v_max_f32_e32 v114, v114, v114
	v_max_f32_e32 v115, v115, v115
	v_cvt_pk_bf16_f32 v127, v150, v151
	v_lshl_add_u64 v[122:123], v[122:123], 0, v[128:129]
	v_max_f32_e32 v114, 0, v114
	v_max_f32_e32 v115, 0, v115
	global_store_dwordx4 v[122:123], v[124:127], off
	v_max_f32_e32 v118, v118, v118
	v_max_f32_e32 v119, v119, v119
	v_pk_mul_f32 v[124:125], v[114:115], v[114:115]
	v_max_f32_e32 v115, v116, v116
	v_max_f32_e32 v114, v120, v120
	v_max_f32_e32 v116, 0, v115
	v_max_f32_e32 v115, v121, v121
	v_max_f32_e32 v117, v117, v117
	v_max_f32_e32 v118, 0, v118
	v_max_f32_e32 v119, 0, v119
	v_max_f32_e32 v114, 0, v114
	v_max_f32_e32 v115, 0, v115
	v_max_f32_e32 v117, 0, v117
	v_pk_mul_f32 v[118:119], v[118:119], v[118:119]
	v_pk_mul_f32 v[120:121], v[114:115], v[114:115]
	v_pk_mul_f32 v[126:127], v[116:117], v[116:117]
	v_max_f32_e32 v106, v106, v106
	v_max_f32_e32 v107, v107, v107
	v_cvt_pk_bf16_f32 v114, v118, v119
	v_cvt_pk_bf16_f32 v115, v120, v121
	v_cvt_pk_bf16_f32 v116, v124, v125
	v_cvt_pk_bf16_f32 v117, v126, v127
	v_max_f32_e32 v106, 0, v106
	v_max_f32_e32 v107, 0, v107
	global_store_dwordx4 v[122:123], v[114:117], off offset:256
	v_max_f32_e32 v110, v110, v110
	v_max_f32_e32 v111, v111, v111
	v_or_b32_e32 v114, 16, v144
	v_pk_mul_f32 v[116:117], v[106:107], v[106:107]
	v_max_f32_e32 v107, v108, v108
	v_ashrrev_i32_e32 v115, 31, v114
	v_max_f32_e32 v110, 0, v110
	v_max_f32_e32 v111, 0, v111
	v_max_f32_e32 v106, v112, v112
	v_max_f32_e32 v108, 0, v107
	v_max_f32_e32 v107, v113, v113
	v_max_f32_e32 v109, v109, v109
	v_lshlrev_b64 v[114:115], 13, v[114:115]
	v_pk_mul_f32 v[110:111], v[110:111], v[110:111]
	v_max_f32_e32 v106, 0, v106
	v_max_f32_e32 v107, 0, v107
	v_max_f32_e32 v109, 0, v109
	v_pk_mul_f32 v[112:113], v[106:107], v[106:107]
	v_pk_mul_f32 v[118:119], v[108:109], v[108:109]
	v_cvt_pk_bf16_f32 v106, v110, v111
	v_lshl_add_u64 v[110:111], s[42:43], 0, v[114:115]
	v_max_f32_e32 v98, v98, v98
	v_max_f32_e32 v99, v99, v99
	v_cvt_pk_bf16_f32 v107, v112, v113
	v_cvt_pk_bf16_f32 v108, v116, v117
	v_cvt_pk_bf16_f32 v109, v118, v119
	v_lshl_add_u64 v[110:111], v[110:111], 0, v[128:129]
	v_max_f32_e32 v98, 0, v98
	v_max_f32_e32 v99, 0, v99
	global_store_dwordx4 v[110:111], v[106:109], off
	v_max_f32_e32 v102, v102, v102
	v_max_f32_e32 v103, v103, v103
	v_pk_mul_f32 v[106:107], v[98:99], v[98:99]
	v_max_f32_e32 v99, v100, v100
	v_max_f32_e32 v98, v104, v104
	v_max_f32_e32 v100, 0, v99
	v_max_f32_e32 v99, v105, v105
	v_max_f32_e32 v101, v101, v101
	v_max_f32_e32 v102, 0, v102
	v_max_f32_e32 v103, 0, v103
	v_max_f32_e32 v98, 0, v98
	v_max_f32_e32 v99, 0, v99
	v_max_f32_e32 v101, 0, v101
	v_pk_mul_f32 v[102:103], v[102:103], v[102:103]
	v_pk_mul_f32 v[104:105], v[98:99], v[98:99]
	v_pk_mul_f32 v[108:109], v[100:101], v[100:101]
	v_max_f32_e32 v88, v88, v88
	v_max_f32_e32 v89, v89, v89
	v_cvt_pk_bf16_f32 v98, v102, v103
	v_cvt_pk_bf16_f32 v99, v104, v105
	v_cvt_pk_bf16_f32 v100, v106, v107
	v_cvt_pk_bf16_f32 v101, v108, v109
	v_max_f32_e32 v88, 0, v88
	v_max_f32_e32 v89, 0, v89
	global_store_dwordx4 v[110:111], v[98:101], off offset:256
	v_max_f32_e32 v92, v92, v92
	v_max_f32_e32 v93, v93, v93
	v_or_b32_e32 v98, 32, v144
	v_pk_mul_f32 v[100:101], v[88:89], v[88:89]
	v_max_f32_e32 v89, v90, v90
	v_ashrrev_i32_e32 v99, 31, v98
	v_max_f32_e32 v92, 0, v92
	v_max_f32_e32 v93, 0, v93
	v_max_f32_e32 v88, v94, v94
	v_max_f32_e32 v90, 0, v89
	v_max_f32_e32 v89, v95, v95
	v_max_f32_e32 v91, v91, v91
	v_lshlrev_b64 v[98:99], 13, v[98:99]
	v_pk_mul_f32 v[92:93], v[92:93], v[92:93]
	v_max_f32_e32 v88, 0, v88
	v_max_f32_e32 v89, 0, v89
	v_max_f32_e32 v91, 0, v91
	v_pk_mul_f32 v[94:95], v[88:89], v[88:89]
	v_pk_mul_f32 v[102:103], v[90:91], v[90:91]
	v_cvt_pk_bf16_f32 v88, v92, v93
	v_lshl_add_u64 v[92:93], s[42:43], 0, v[98:99]
	v_max_f32_e32 v80, v80, v80
	v_max_f32_e32 v81, v81, v81
	v_cvt_pk_bf16_f32 v89, v94, v95
	v_cvt_pk_bf16_f32 v90, v100, v101
	v_cvt_pk_bf16_f32 v91, v102, v103
	v_lshl_add_u64 v[92:93], v[92:93], 0, v[128:129]
	v_max_f32_e32 v80, 0, v80
	v_max_f32_e32 v81, 0, v81
	global_store_dwordx4 v[92:93], v[88:91], off
	v_max_f32_e32 v84, v84, v84
	v_max_f32_e32 v85, v85, v85
	v_pk_mul_f32 v[88:89], v[80:81], v[80:81]
	v_max_f32_e32 v81, v82, v82
	v_max_f32_e32 v80, v86, v86
	v_max_f32_e32 v82, 0, v81
	v_max_f32_e32 v81, v87, v87
	v_max_f32_e32 v83, v83, v83
	v_max_f32_e32 v84, 0, v84
	v_max_f32_e32 v85, 0, v85
	v_max_f32_e32 v80, 0, v80
	v_max_f32_e32 v81, 0, v81
	v_max_f32_e32 v83, 0, v83
;   DEV void operator()(const f32x4 (&acc)[2][2][4][2], const pg8::Unit& u, int wr, int wc, int fr, int fq) const {
;     ...
;     for (int ai = 0; ai < 2; ++ai)
; #pragma unroll
;       for (int m = 0; m < 4; ++m) {
;         const int row = row0 + ai * 128 + m * 16;
; #pragma unroll
;         for (int bj = 0; bj < 2; ++bj) {
;           float v[8];
; #pragma unroll
;           for (int j = 0; j < 4; ++j) {
;             const float r0 = fmaxf(acc[ai][bj][m][0][j], 0.f), r1 = fmaxf(acc[ai][bj][m][1][j], 0.f);
;             v[j] = r0 * r0; v[4 + j] = r1 * r1;
;           }
;           u32x4 o;
;           o[0] = pk2(v[0], v[1]); o[1] = pk2(v[2], v[3]); o[2] = pk2(v[4], v[5]); o[3] = pk2(v[6], v[7]);
;           *(u32x4*)(HID + (size_t)row * 4096 + col0 + bj * 128) = o;
;         }
;       }
	v_pk_mul_f32 v[84:85], v[84:85], v[84:85]
	v_pk_mul_f32 v[86:87], v[80:81], v[80:81]
	v_pk_mul_f32 v[90:91], v[82:83], v[82:83]
	v_max_f32_e32 v72, v72, v72
	v_max_f32_e32 v73, v73, v73
	v_cvt_pk_bf16_f32 v80, v84, v85
	v_cvt_pk_bf16_f32 v81, v86, v87
	v_cvt_pk_bf16_f32 v82, v88, v89
	v_cvt_pk_bf16_f32 v83, v90, v91
	v_max_f32_e32 v72, 0, v72
	v_max_f32_e32 v73, 0, v73
	global_store_dwordx4 v[92:93], v[80:83], off offset:256
	v_max_f32_e32 v76, v76, v76
	v_max_f32_e32 v77, v77, v77
	v_or_b32_e32 v80, 48, v144
	v_pk_mul_f32 v[82:83], v[72:73], v[72:73]
	v_max_f32_e32 v73, v74, v74
	v_ashrrev_i32_e32 v81, 31, v80
	v_max_f32_e32 v76, 0, v76
	v_max_f32_e32 v77, 0, v77
	v_max_f32_e32 v72, v78, v78
	v_max_f32_e32 v74, 0, v73
	v_max_f32_e32 v73, v79, v79
	v_max_f32_e32 v75, v75, v75
	v_lshlrev_b64 v[80:81], 13, v[80:81]
	v_pk_mul_f32 v[76:77], v[76:77], v[76:77]
	v_max_f32_e32 v72, 0, v72
	v_max_f32_e32 v73, 0, v73
	v_max_f32_e32 v75, 0, v75
	v_pk_mul_f32 v[78:79], v[72:73], v[72:73]
	v_pk_mul_f32 v[84:85], v[74:75], v[74:75]
	v_cvt_pk_bf16_f32 v72, v76, v77
	v_lshl_add_u64 v[76:77], s[42:43], 0, v[80:81]
	v_max_f32_e32 v64, v64, v64
	v_max_f32_e32 v65, v65, v65
	v_cvt_pk_bf16_f32 v73, v78, v79
	v_cvt_pk_bf16_f32 v74, v82, v83
	v_cvt_pk_bf16_f32 v75, v84, v85
	v_lshl_add_u64 v[76:77], v[76:77], 0, v[128:129]
	v_max_f32_e32 v64, 0, v64
	v_max_f32_e32 v65, 0, v65
	global_store_dwordx4 v[76:77], v[72:75], off
	v_max_f32_e32 v68, v68, v68
	v_max_f32_e32 v69, v69, v69
	v_pk_mul_f32 v[72:73], v[64:65], v[64:65]
	v_max_f32_e32 v65, v66, v66
	v_max_f32_e32 v64, v70, v70
	v_max_f32_e32 v66, 0, v65
	v_max_f32_e32 v65, v71, v71
	v_max_f32_e32 v67, v67, v67
	v_max_f32_e32 v68, 0, v68
	v_max_f32_e32 v69, 0, v69
	v_max_f32_e32 v64, 0, v64
	v_max_f32_e32 v65, 0, v65
	v_max_f32_e32 v67, 0, v67
	v_pk_mul_f32 v[68:69], v[68:69], v[68:69]
	v_pk_mul_f32 v[70:71], v[64:65], v[64:65]
	v_pk_mul_f32 v[74:75], v[66:67], v[66:67]
	v_max_f32_e32 v56, v56, v56
	v_max_f32_e32 v57, v57, v57
	v_cvt_pk_bf16_f32 v64, v68, v69
	v_cvt_pk_bf16_f32 v65, v70, v71
	v_cvt_pk_bf16_f32 v66, v72, v73
	v_cvt_pk_bf16_f32 v67, v74, v75
	v_max_f32_e32 v56, 0, v56
	v_max_f32_e32 v57, 0, v57
	global_store_dwordx4 v[76:77], v[64:67], off offset:256
	v_max_f32_e32 v60, v60, v60
	v_max_f32_e32 v61, v61, v61
	v_pk_mul_f32 v[64:65], v[56:57], v[56:57]
	v_max_f32_e32 v57, v58, v58
	v_max_f32_e32 v56, v62, v62
	v_max_f32_e32 v58, 0, v57
	v_max_f32_e32 v57, v63, v63
	v_max_f32_e32 v56, 0, v56
	v_max_f32_e32 v57, 0, v57
	v_max_f32_e32 v59, v59, v59
	v_max_f32_e32 v60, 0, v60
	v_max_f32_e32 v61, 0, v61
	v_max_f32_e32 v59, 0, v59
	v_pk_mul_f32 v[62:63], v[56:57], v[56:57]
	s_mov_b32 s1, 0x100000
	v_pk_mul_f32 v[60:61], v[60:61], v[60:61]
	v_pk_mul_f32 v[66:67], v[58:59], v[58:59]
	v_cvt_pk_bf16_f32 v57, v62, v63
	v_add_co_u32_e32 v62, vcc, s1, v122
	v_max_f32_e32 v48, v48, v48
	v_max_f32_e32 v49, v49, v49
	v_cvt_pk_bf16_f32 v56, v60, v61
	v_cvt_pk_bf16_f32 v58, v64, v65
	v_cvt_pk_bf16_f32 v59, v66, v67
	v_addc_co_u32_e32 v63, vcc, 0, v123, vcc
	v_max_f32_e32 v48, 0, v48
	v_max_f32_e32 v49, 0, v49
	global_store_dwordx4 v[62:63], v[56:59], off
	v_max_f32_e32 v52, v52, v52
	v_max_f32_e32 v53, v53, v53
	v_pk_mul_f32 v[56:57], v[48:49], v[48:49]
	v_max_f32_e32 v49, v50, v50
	v_max_f32_e32 v48, v54, v54
	v_max_f32_e32 v50, 0, v49
	v_max_f32_e32 v49, v55, v55
	v_max_f32_e32 v51, v51, v51
	v_max_f32_e32 v52, 0, v52
	v_max_f32_e32 v53, 0, v53
	v_max_f32_e32 v48, 0, v48
	v_max_f32_e32 v49, 0, v49
	v_max_f32_e32 v51, 0, v51
	s_mov_b64 s[46:47], 0x100000
	v_pk_mul_f32 v[52:53], v[52:53], v[52:53]
	v_pk_mul_f32 v[54:55], v[48:49], v[48:49]
	v_pk_mul_f32 v[58:59], v[50:51], v[50:51]
	v_max_f32_e32 v40, v40, v40
	v_max_f32_e32 v41, v41, v41
	v_lshl_add_u64 v[60:61], v[122:123], 0, s[46:47]
	v_cvt_pk_bf16_f32 v48, v52, v53
	v_cvt_pk_bf16_f32 v49, v54, v55
	v_cvt_pk_bf16_f32 v50, v56, v57
	v_cvt_pk_bf16_f32 v51, v58, v59
	v_max_f32_e32 v40, 0, v40
	v_max_f32_e32 v41, 0, v41
	global_store_dwordx4 v[60:61], v[48:51], off offset:256
	v_max_f32_e32 v44, v44, v44
	v_max_f32_e32 v45, v45, v45
	v_pk_mul_f32 v[48:49], v[40:41], v[40:41]
	v_max_f32_e32 v41, v42, v42
	v_max_f32_e32 v40, v46, v46
	v_max_f32_e32 v42, 0, v41
	v_max_f32_e32 v41, v47, v47
	v_max_f32_e32 v40, 0, v40
	v_max_f32_e32 v41, 0, v41
	v_max_f32_e32 v43, v43, v43
	v_max_f32_e32 v44, 0, v44
	v_max_f32_e32 v45, 0, v45
	v_max_f32_e32 v43, 0, v43
	v_pk_mul_f32 v[46:47], v[40:41], v[40:41]
	s_mov_b32 s1, 0x120000
	v_pk_mul_f32 v[44:45], v[44:45], v[44:45]
	v_pk_mul_f32 v[50:51], v[42:43], v[42:43]
	v_cvt_pk_bf16_f32 v41, v46, v47
	v_add_co_u32_e32 v46, vcc, s1, v122
	v_max_f32_e32 v32, v32, v32
	v_max_f32_e32 v33, v33, v33
	v_cvt_pk_bf16_f32 v40, v44, v45
	v_cvt_pk_bf16_f32 v42, v48, v49
; #define PG8_WAIT_V(n) asm volatile("s_waitcnt vmcnt(" #n ")" ::: "memory")
; #define PG8_BAR __builtin_amdgcn_s_barrier()
; template <class Epi, class Sched>
; __device__ __forceinline__ void gemm_phase(PG8_LAS unsigned char* lds, const Gemm g, const Sched& S, const Epi& E) {
;     ...
;         if (!has_next) break;
; #pragma unroll
;         for (int a = 0; a < 2; ++a)
; #pragma unroll
;             for (int b = 0; b < 2; ++b)
; #pragma unroll
;                 for (int m = 0; m < 4; ++m)
; #pragma unroll
;                     for (int n = 0; n < 2; ++n) acc[a][b][m][n] = (f32x4){0.f, 0.f, 0.f, 0.f};
;         cur = nxt; cA = nA; cB = nB; ++ui;
;     }
;     PG8_WAIT_V(0);
;     if (wr == 0) PG8_BAR;
;     PG8_BAR;
;   DEV void operator()(const f32x4 (&acc)[2][2][4][2], const pg8::Unit& u, int wr, int wc, int fr, int fq) const {
;     ...
;     for (int ai = 0; ai < 2; ++ai)
; #pragma unroll
;       for (int m = 0; m < 4; ++m) {
;         const int row = row0 + ai * 128 + m * 16;
; #pragma unroll
;         for (int bj = 0; bj < 2; ++bj) {
;           float v[8];
; #pragma unroll
;           for (int j = 0; j < 4; ++j) {
;             const float r0 = fmaxf(acc[ai][bj][m][0][j], 0.f), r1 = fmaxf(acc[ai][bj][m][1][j], 0.f);
;             v[j] = r0 * r0; v[4 + j] = r1 * r1;
;           }
;           u32x4 o;
;           o[0] = pk2(v[0], v[1]); o[1] = pk2(v[2], v[3]); o[2] = pk2(v[4], v[5]); o[3] = pk2(v[6], v[7]);
;           *(u32x4*)(HID + (size_t)row * 4096 + col0 + bj * 128) = o;
;         }
;       }
	v_cvt_pk_bf16_f32 v43, v50, v51
	v_addc_co_u32_e32 v47, vcc, 0, v123, vcc
	v_max_f32_e32 v32, 0, v32
	v_max_f32_e32 v33, 0, v33
	global_store_dwordx4 v[46:47], v[40:43], off
	v_max_f32_e32 v36, v36, v36
	v_max_f32_e32 v37, v37, v37
	v_pk_mul_f32 v[40:41], v[32:33], v[32:33]
	v_max_f32_e32 v33, v34, v34
	v_max_f32_e32 v32, v38, v38
	v_max_f32_e32 v34, 0, v33
	v_max_f32_e32 v33, v39, v39
	v_max_f32_e32 v35, v35, v35
	v_max_f32_e32 v36, 0, v36
	v_max_f32_e32 v37, 0, v37
	v_max_f32_e32 v32, 0, v32
	v_max_f32_e32 v33, 0, v33
	v_max_f32_e32 v35, 0, v35
	s_mov_b64 s[46:47], 0x120000
	v_pk_mul_f32 v[36:37], v[36:37], v[36:37]
	v_pk_mul_f32 v[38:39], v[32:33], v[32:33]
	v_pk_mul_f32 v[42:43], v[34:35], v[34:35]
	v_max_f32_e32 v24, v24, v24
	v_max_f32_e32 v25, v25, v25
	v_lshl_add_u64 v[44:45], v[122:123], 0, s[46:47]
	v_cvt_pk_bf16_f32 v32, v36, v37
	v_cvt_pk_bf16_f32 v33, v38, v39
	v_cvt_pk_bf16_f32 v34, v40, v41
	v_cvt_pk_bf16_f32 v35, v42, v43
	v_max_f32_e32 v24, 0, v24
	v_max_f32_e32 v25, 0, v25
	global_store_dwordx4 v[44:45], v[32:35], off offset:256
	v_max_f32_e32 v28, v28, v28
	v_max_f32_e32 v29, v29, v29
	v_pk_mul_f32 v[32:33], v[24:25], v[24:25]
	v_max_f32_e32 v25, v26, v26
	v_max_f32_e32 v24, v30, v30
	v_max_f32_e32 v26, 0, v25
	v_max_f32_e32 v25, v31, v31
	v_max_f32_e32 v24, 0, v24
	v_max_f32_e32 v25, 0, v25
	v_max_f32_e32 v27, v27, v27
	v_max_f32_e32 v28, 0, v28
	v_max_f32_e32 v29, 0, v29
	v_max_f32_e32 v27, 0, v27
	v_pk_mul_f32 v[30:31], v[24:25], v[24:25]
	s_mov_b32 s1, 0x140000
	v_pk_mul_f32 v[28:29], v[28:29], v[28:29]
	v_pk_mul_f32 v[34:35], v[26:27], v[26:27]
	v_cvt_pk_bf16_f32 v25, v30, v31
	v_add_co_u32_e32 v30, vcc, s1, v122
	v_max_f32_e32 v16, v16, v16
	v_max_f32_e32 v17, v17, v17
	v_cvt_pk_bf16_f32 v24, v28, v29
	v_cvt_pk_bf16_f32 v26, v32, v33
	v_cvt_pk_bf16_f32 v27, v34, v35
	v_addc_co_u32_e32 v31, vcc, 0, v123, vcc
	v_max_f32_e32 v16, 0, v16
	v_max_f32_e32 v17, 0, v17
	global_store_dwordx4 v[30:31], v[24:27], off
	v_max_f32_e32 v20, v20, v20
	v_max_f32_e32 v21, v21, v21
	v_pk_mul_f32 v[24:25], v[16:17], v[16:17]
	v_max_f32_e32 v17, v18, v18
	v_max_f32_e32 v16, v22, v22
	v_max_f32_e32 v18, 0, v17
	v_max_f32_e32 v17, v23, v23
	v_max_f32_e32 v19, v19, v19
	v_max_f32_e32 v20, 0, v20
	v_max_f32_e32 v21, 0, v21
	v_max_f32_e32 v16, 0, v16
	v_max_f32_e32 v17, 0, v17
	v_max_f32_e32 v19, 0, v19
	s_mov_b64 s[46:47], 0x140000
	v_pk_mul_f32 v[20:21], v[20:21], v[20:21]
	v_pk_mul_f32 v[22:23], v[16:17], v[16:17]
	v_pk_mul_f32 v[26:27], v[18:19], v[18:19]
	v_max_f32_e32 v8, v8, v8
	v_max_f32_e32 v9, v9, v9
	v_lshl_add_u64 v[28:29], v[122:123], 0, s[46:47]
	v_cvt_pk_bf16_f32 v16, v20, v21
	v_cvt_pk_bf16_f32 v17, v22, v23
	v_cvt_pk_bf16_f32 v18, v24, v25
	v_cvt_pk_bf16_f32 v19, v26, v27
	v_max_f32_e32 v8, 0, v8
	v_max_f32_e32 v9, 0, v9
	global_store_dwordx4 v[28:29], v[16:19], off offset:256
	v_max_f32_e32 v12, v12, v12
	v_max_f32_e32 v13, v13, v13
	v_pk_mul_f32 v[16:17], v[8:9], v[8:9]
	v_max_f32_e32 v9, v10, v10
	v_max_f32_e32 v8, v14, v14
	v_max_f32_e32 v10, 0, v9
	v_max_f32_e32 v9, v15, v15
	v_max_f32_e32 v8, 0, v8
	v_max_f32_e32 v9, 0, v9
	v_max_f32_e32 v11, v11, v11
	v_max_f32_e32 v12, 0, v12
	v_max_f32_e32 v13, 0, v13
	v_max_f32_e32 v11, 0, v11
	v_pk_mul_f32 v[14:15], v[8:9], v[8:9]
	s_mov_b32 s1, 0x160000
	v_pk_mul_f32 v[12:13], v[12:13], v[12:13]
	v_pk_mul_f32 v[18:19], v[10:11], v[10:11]
	v_cvt_pk_bf16_f32 v9, v14, v15
	v_add_co_u32_e32 v14, vcc, s1, v122
	v_max_f32_e32 v0, v0, v0
	v_max_f32_e32 v1, v1, v1
	v_cvt_pk_bf16_f32 v8, v12, v13
	v_cvt_pk_bf16_f32 v10, v16, v17
	v_cvt_pk_bf16_f32 v11, v18, v19
	v_addc_co_u32_e32 v15, vcc, 0, v123, vcc
	v_max_f32_e32 v0, 0, v0
	v_max_f32_e32 v1, 0, v1
	global_store_dwordx4 v[14:15], v[8:11], off
	v_max_f32_e32 v4, v4, v4
	v_max_f32_e32 v5, v5, v5
	v_pk_mul_f32 v[8:9], v[0:1], v[0:1]
	v_max_f32_e32 v1, v2, v2
	v_max_f32_e32 v0, v6, v6
	v_max_f32_e32 v2, 0, v1
	v_max_f32_e32 v1, v7, v7
	v_max_f32_e32 v3, v3, v3
	v_max_f32_e32 v4, 0, v4
	v_max_f32_e32 v5, 0, v5
	v_max_f32_e32 v0, 0, v0
	v_max_f32_e32 v1, 0, v1
	v_max_f32_e32 v3, 0, v3
	s_mov_b64 s[46:47], 0x160000
	v_pk_mul_f32 v[4:5], v[4:5], v[4:5]
	v_pk_mul_f32 v[6:7], v[0:1], v[0:1]
	v_pk_mul_f32 v[10:11], v[2:3], v[2:3]
	v_lshl_add_u64 v[12:13], v[122:123], 0, s[46:47]
	v_cvt_pk_bf16_f32 v0, v4, v5
	v_cvt_pk_bf16_f32 v1, v6, v7
	v_cvt_pk_bf16_f32 v2, v8, v9
	v_cvt_pk_bf16_f32 v3, v10, v11
	s_and_b64 vcc, exec, s[36:37]
	s_mov_b32 s65, s0
	s_mov_b32 s44, s30
	s_mov_b64 s[48:49], s[40:41]
	s_mov_b64 s[46:47], s[38:39]
	global_store_dwordx4 v[12:13], v[0:3], off offset:256
	s_cbranch_vccz .LBB0_62
	s_waitcnt vmcnt(0)
	v_readlane_b32 s64, v255, 38
	s_cmpk_gt_u32 s52, 0xff
	v_readlane_b32 s65, v255, 39
	s_cbranch_scc1 .LBB0_69
	s_barrier

; #define PG8_BAR __builtin_amdgcn_s_barrier()
; template <class Epi, class Sched>
; __device__ __forceinline__ void gemm_phase(PG8_LAS unsigned char* lds, const Gemm g, const Sched& S, const Epi& E) {
;     ...
;         const bool has_next = S.next(ui + 1, nxt);
;         const char* nA = has_next ? (const char*)g.A + (size_t)nxt.pm * tstep : cA; const char* nB = has_next ? (const char*)g.Bt + (size_t)nxt.pn * tstep : cB;
;         for (int t = 0; t < nt; t += 2) {
;             const bool last = (t == nt - 2);
;             const char* a1 = cA + (size_t)(t + 1) * kstep;
;             const char* a2 = last ? nA : cA + (size_t)(t + 2) * kstep; const char* b2 = last ? nB : cB + (size_t)(t + 2) * kstep;
;             const char* a3 = a2 + kstep; const char* b3 = b2 + kstep;
;             if (last && has_next) S.a_ready(nxt);
;             PG8_LDB(B0, 0, 0); PG8_SCHED; PG8_LDA(At, 0, 0); PG8_STAGE(PG8_SA(1, 1), a1 + hstep, voffA);
;             PG8_WAIT_L(8); PG8_BAR; PG8_WAIT_L(0); PG8_MMA(0, 0, At, B0); PG8_BAR; PG8_SCHED;
;             PG8_LDB(B1, 0, 1); PG8_STAGE(PG8_SB(0, 0), b2, voffB);
;             PG8_BAR; PG8_WAIT_L(0); PG8_MMA(0, 1, At, B1); PG8_BAR;
;             PG8_LDA(At, 0, 1); PG8_STAGE(PG8_SA(0, 0), a2, voffA);
;             PG8_BAR; PG8_WAIT_L(0); PG8_MMA(1, 0, At, B0); PG8_BAR; PG8_SCHED;
;             PG8_STAGE(PG8_SB(0, 1), b2 + hstep, voffB);
;             PG8_WAIT_V(6); PG8_BAR; PG8_MMA(1, 1, At, B1); PG8_BAR;
;             PG8_LDB(B0, 1, 0); PG8_SCHED; PG8_LDA(At, 1, 0); PG8_STAGE(PG8_SA(0, 1), a2 + hstep, voffA);
;             PG8_WAIT_L(8); PG8_BAR; PG8_WAIT_L(0); PG8_MMA(0, 0, At, B0); PG8_BAR; PG8_SCHED;
;             PG8_LDB(B1, 1, 1); PG8_STAGE(PG8_SB(1, 0), b3, voffB);
;             PG8_BAR; PG8_WAIT_L(0); PG8_MMA(0, 1, At, B1); PG8_BAR;
;             PG8_LDA(At, 1, 1); PG8_STAGE(PG8_SA(1, 0), a3, voffA);
;             PG8_BAR; PG8_WAIT_L(0); PG8_MMA(1, 0, At, B0); PG8_BAR; PG8_SCHED;
;             PG8_STAGE(PG8_SB(1, 1), b3 + hstep, voffB);
;             PG8_WAIT_V(6); PG8_BAR; PG8_MMA(1, 1, At, B1); PG8_BAR;
;         }
;         if constexpr (!Epi::AFTER_DRAIN) { E(acc, cur, wr, wc, fr, fq); S.done(cur); }
;         if (!has_next) break;
; #pragma unroll
;         for (int a = 0; a < 2; ++a)
; #pragma unroll
;             for (int b = 0; b < 2; ++b)
; #pragma unroll
;                 for (int m = 0; m < 4; ++m)
; #pragma unroll
.LBB0_86:
	v_mov_b64_e32 v[0:1], s[54:55]
	s_ashr_i32 s47, s46, 31
	v_cmp_lt_i64_e32 vcc, s[48:49], v[0:1]
	s_lshl_b64 s[48:49], s[46:47], 19
	s_add_u32 s48, s74, s48
	s_addc_u32 s49, s75, s49
	s_and_b64 s[50:51], vcc, exec
	s_cselect_b32 s47, s49, s39
	s_cselect_b32 s94, s48, s38
	s_ashr_i32 s45, s44, 31
	s_lshl_b64 s[50:51], s[44:45], 19
	v_readlane_b32 s42, v251, 11
	v_readlane_b32 s43, v251, 12
	s_add_u32 s50, s42, s50
	s_addc_u32 s51, s43, s51
	s_and_b64 s[52:53], vcc, exec
	s_cselect_b32 s45, s51, s41
	s_cselect_b32 s97, s50, s40
	s_add_u32 s56, s40, 0x100
	v_mov_b32_e32 v0, 0
	s_addc_u32 s57, s41, 0
	s_mov_b32 s60, -2
	v_mov_b32_e32 v1, v0
	v_mov_b32_e32 v2, v0
	v_mov_b32_e32 v3, v0
	v_mov_b32_e32 v4, v0
	v_mov_b32_e32 v5, v0
	v_mov_b32_e32 v6, v0
	v_mov_b32_e32 v7, v0
	v_mov_b32_e32 v12, v0
	v_mov_b32_e32 v13, v0
	v_mov_b32_e32 v14, v0
	v_mov_b32_e32 v15, v0
	v_mov_b32_e32 v20, v0
	v_mov_b32_e32 v21, v0
	v_mov_b32_e32 v22, v0
	v_mov_b32_e32 v23, v0
	v_mov_b32_e32 v28, v0
	v_mov_b32_e32 v29, v0
	v_mov_b32_e32 v30, v0
	v_mov_b32_e32 v31, v0
	v_mov_b32_e32 v36, v0
	v_mov_b32_e32 v37, v0
	v_mov_b32_e32 v38, v0
	v_mov_b32_e32 v39, v0
	v_mov_b32_e32 v44, v0
	v_mov_b32_e32 v45, v0
	v_mov_b32_e32 v46, v0
	v_mov_b32_e32 v47, v0
	v_mov_b32_e32 v52, v0
	v_mov_b32_e32 v53, v0
	v_mov_b32_e32 v54, v0
	v_mov_b32_e32 v55, v0
	v_mov_b32_e32 v8, v0
	v_mov_b32_e32 v9, v0
	v_mov_b32_e32 v10, v0
	v_mov_b32_e32 v11, v0
	v_mov_b32_e32 v16, v0
	v_mov_b32_e32 v17, v0
	v_mov_b32_e32 v18, v0
	v_mov_b32_e32 v19, v0
	v_mov_b32_e32 v24, v0
	v_mov_b32_e32 v25, v0
	v_mov_b32_e32 v26, v0
	v_mov_b32_e32 v27, v0
	v_mov_b32_e32 v32, v0
	v_mov_b32_e32 v33, v0
	v_mov_b32_e32 v34, v0
	v_mov_b32_e32 v35, v0
	v_mov_b32_e32 v40, v0
	v_mov_b32_e32 v41, v0
	v_mov_b32_e32 v42, v0
	v_mov_b32_e32 v43, v0
	v_mov_b32_e32 v48, v0
	v_mov_b32_e32 v49, v0
	v_mov_b32_e32 v50, v0
	v_mov_b32_e32 v51, v0
	v_mov_b32_e32 v56, v0
	v_mov_b32_e32 v57, v0
	v_mov_b32_e32 v58, v0
	v_mov_b32_e32 v59, v0
	v_mov_b32_e32 v60, v0
	v_mov_b32_e32 v61, v0
	v_mov_b32_e32 v62, v0
	v_mov_b32_e32 v63, v0
	v_mov_b32_e32 v64, v0
	v_mov_b32_e32 v65, v0
	v_mov_b32_e32 v66, v0
	v_mov_b32_e32 v67, v0
	v_mov_b32_e32 v68, v0
	v_mov_b32_e32 v69, v0
	v_mov_b32_e32 v70, v0
	v_mov_b32_e32 v71, v0
	v_mov_b32_e32 v76, v0
	v_mov_b32_e32 v77, v0
	v_mov_b32_e32 v78, v0
	v_mov_b32_e32 v79, v0
	v_mov_b32_e32 v88, v0
	v_mov_b32_e32 v89, v0
	v_mov_b32_e32 v90, v0
	v_mov_b32_e32 v91, v0
	v_mov_b32_e32 v110, v0
	v_mov_b32_e32 v111, v0
	v_mov_b32_e32 v112, v0
	v_mov_b32_e32 v113, v0
	v_mov_b32_e32 v118, v0
	v_mov_b32_e32 v119, v0
	v_mov_b32_e32 v120, v0
	v_mov_b32_e32 v121, v0
	v_mov_b32_e32 v126, v0
	v_mov_b32_e32 v127, v0
	v_mov_b32_e32 v128, v0
	v_mov_b32_e32 v129, v0
	v_mov_b32_e32 v134, v0
	v_mov_b32_e32 v135, v0
	v_mov_b32_e32 v136, v0
	v_mov_b32_e32 v137, v0
	v_mov_b32_e32 v72, v0
	v_mov_b32_e32 v73, v0
	v_mov_b32_e32 v74, v0
	v_mov_b32_e32 v75, v0
	v_mov_b32_e32 v80, v0
	v_mov_b32_e32 v81, v0
	v_mov_b32_e32 v82, v0
	v_mov_b32_e32 v83, v0
	v_mov_b32_e32 v106, v0
	v_mov_b32_e32 v107, v0
	v_mov_b32_e32 v108, v0
	v_mov_b32_e32 v109, v0
	v_mov_b32_e32 v114, v0
	v_mov_b32_e32 v115, v0
	v_mov_b32_e32 v116, v0
	v_mov_b32_e32 v117, v0
	v_mov_b32_e32 v122, v0
	v_mov_b32_e32 v123, v0
	v_mov_b32_e32 v124, v0
	v_mov_b32_e32 v125, v0
	v_mov_b32_e32 v130, v0
	v_mov_b32_e32 v131, v0
	v_mov_b32_e32 v132, v0
	v_mov_b32_e32 v133, v0
	v_mov_b32_e32 v138, v0
	v_mov_b32_e32 v139, v0
	v_mov_b32_e32 v140, v0
	v_mov_b32_e32 v141, v0
	v_mov_b32_e32 v142, v0
	v_mov_b32_e32 v143, v0
	v_mov_b32_e32 v144, v0
	v_mov_b32_e32 v145, v0
	v_readfirstlane_b32 s100, v226
	s_nop 3
	s_lshr_b32 s100, s100, 8
	s_cmp_eq_u32 s100, 0
	s_cbranch_scc1 .Lgp_4525
	s_setprio 1
.Lgp_4525:
.LBB0_87:
	s_add_u32 s40, s38, 0x100
	s_addc_u32 s41, s39, 0
	s_add_i32 s59, 0, 0x10000
	v_add_u32_e32 v102, s59, v240
	ds_read_b128 v[84:87], v102
	ds_read_b128 v[92:95], v102 offset:1024
	ds_read_b128 v[98:101], v102 offset:2048
	ds_read_b128 v[102:105], v102 offset:3072
	s_cmp_eq_u32 s60, 12
	s_cselect_b32 vcc_hi, s47, s41
	s_cselect_b32 vcc_lo, s94, s40
	s_cselect_b32 s53, s45, s57
	s_cselect_b32 s52, s97, s56
	v_lshl_add_u64 v[178:179], s[38:39], 0, v[210:211]
	s_add_i32 m0, s61, 0xc000
	ds_read_b128 v[146:149], v242
	ds_read_b128 v[150:153], v242 offset:1024
	ds_read_b128 v[154:157], v242 offset:2048
	ds_read_b128 v[158:161], v242 offset:3072
	ds_read_b128 v[162:165], v242 offset:4096
	ds_read_b128 v[166:169], v242 offset:5120
	ds_read_b128 v[170:173], v242 offset:6144
	ds_read_b128 v[174:177], v242 offset:7168
	global_load_lds_dwordx4 v[178:179], off
	v_lshl_add_u64 v[178:179], s[38:39], 0, v[212:213]
	s_add_i32 m0, s61, 0xe000
	s_nop 0
	global_load_lds_dwordx4 v[178:179], off
	s_waitcnt lgkmcnt(8)
	s_barrier
	s_waitcnt lgkmcnt(0)
	s_waitcnt lgkmcnt(0)
	v_mfma_f32_16x16x32_bf16 v[142:145], v[84:87], v[146:149], v[142:145]
	v_mfma_f32_16x16x32_bf16 v[138:141], v[98:101], v[146:149], v[138:141]
	v_mfma_f32_16x16x32_bf16 v[130:133], v[84:87], v[154:157], v[130:133]
	v_mfma_f32_16x16x32_bf16 v[122:125], v[98:101], v[154:157], v[122:125]
	v_mfma_f32_16x16x32_bf16 v[114:117], v[84:87], v[162:165], v[114:117]
	v_mfma_f32_16x16x32_bf16 v[106:109], v[98:101], v[162:165], v[106:109]
	v_mfma_f32_16x16x32_bf16 v[80:83], v[84:87], v[170:173], v[80:83]
	v_mfma_f32_16x16x32_bf16 v[72:75], v[98:101], v[170:173], v[72:75]
	v_mfma_f32_16x16x32_bf16 v[142:145], v[92:95], v[150:153], v[142:145]
	v_mfma_f32_16x16x32_bf16 v[138:141], v[102:105], v[150:153], v[138:141]
	v_mfma_f32_16x16x32_bf16 v[130:133], v[92:95], v[158:161], v[130:133]
	v_mfma_f32_16x16x32_bf16 v[122:125], v[102:105], v[158:161], v[122:125]
	v_mfma_f32_16x16x32_bf16 v[114:117], v[92:95], v[166:169], v[114:117]
	v_mfma_f32_16x16x32_bf16 v[106:109], v[102:105], v[166:169], v[106:109]
	v_mfma_f32_16x16x32_bf16 v[80:83], v[92:95], v[174:177], v[80:83]
	v_mfma_f32_16x16x32_bf16 v[72:75], v[102:105], v[174:177], v[72:75]
	s_barrier
; #define PG8_STAGE(bufoff, gbase, voff) do { _Pragma("unroll") for (int _i = 0; _i < 2; ++_i) \
;         __builtin_amdgcn_global_load_lds((const unsigned*)((const char*)(gbase) + (voff)[_i]), (PG8_LAS unsigned*)(lds + (bufoff) + ldsw + _i * 8192), 16, 0, 0); } while (0)
; #define PG8_LDA(dst, b, h) do { _Pragma("unroll") for (int m = 0; m < 4; ++m) _Pragma("unroll") for (int k = 0; k < 2; ++k) dst[m][k] = *(const PG8_LAS bf16x8*)(lds + PG8_SA(b, h) + aoff + m * 2048 + k * 1024); } while (0)
; #define PG8_LDB(dst, b, h) do { _Pragma("unroll") for (int n = 0; n < 2; ++n) _Pragma("unroll") for (int k = 0; k < 2; ++k) dst[n][k] = *(const PG8_LAS bf16x8*)(lds + PG8_SB(b, h) + boff + n * 2048 + k * 1024); } while (0)
; #define PG8_MMA(ai, bj, At, Bt) do { __builtin_amdgcn_s_setprio(1); _Pragma("unroll") for (int m = 0; m < 4; ++m) _Pragma("unroll") for (int n = 0; n < 2; ++n) _Pragma("unroll") for (int k = 0; k < 2; ++k) \
;         acc[ai][bj][m][n] = __builtin_amdgcn_mfma_f32_16x16x32_bf16(Bt[n][k], At[m][k], acc[ai][bj][m][n], 0, 0, 0); __builtin_amdgcn_s_setprio(0); } while (0)
; #define PG8_WAIT_V(n) asm volatile("s_waitcnt vmcnt(" #n ")" ::: "memory")
; #define PG8_WAIT_L(n) asm volatile("s_waitcnt lgkmcnt(" #n ")" ::: "memory")
; #define PG8_BAR __builtin_amdgcn_s_barrier()
; #define PG8_SCHED __builtin_amdgcn_sched_barrier(0)
; template <class Epi, class Sched>
; __device__ __forceinline__ void gemm_phase(PG8_LAS unsigned char* lds, const Gemm g, const Sched& S, const Epi& E) {
;     ...
;             PG8_LDB(B1, 0, 1); PG8_STAGE(PG8_SB(0, 0), b2, voffB);
;             PG8_BAR; PG8_WAIT_L(0); PG8_MMA(0, 1, At, B1); PG8_BAR;
;             PG8_LDA(At, 0, 1); PG8_STAGE(PG8_SA(0, 0), a2, voffA);
;             PG8_BAR; PG8_WAIT_L(0); PG8_MMA(1, 0, At, B0); PG8_BAR; PG8_SCHED;
;             PG8_STAGE(PG8_SB(0, 1), b2 + hstep, voffB);
;             PG8_WAIT_V(6); PG8_BAR; PG8_MMA(1, 1, At, B1); PG8_BAR;
;             PG8_LDB(B0, 1, 0); PG8_SCHED; PG8_LDA(At, 1, 0); PG8_STAGE(PG8_SA(0, 1), a2 + hstep, voffA);
;             PG8_WAIT_L(8); PG8_BAR; PG8_WAIT_L(0); PG8_MMA(0, 0, At, B0); PG8_BAR; PG8_SCHED;
	s_add_i32 s42, 0, 0x14000
	s_add_i32 s38, s59, s58
	v_add_u32_e32 v190, s42, v240
	v_lshl_add_u64 v[194:195], s[52:53], 0, v[96:97]
	s_mov_b32 m0, s38
	ds_read_b128 v[178:181], v190
	ds_read_b128 v[182:185], v190 offset:1024
	ds_read_b128 v[186:189], v190 offset:2048
	ds_read_b128 v[190:193], v190 offset:3072
	global_load_lds_dwordx4 v[194:195], off
	v_lshl_add_u64 v[196:197], s[52:53], 0, v[208:209]
	s_add_i32 m0, s38, 0x2000
	s_nop 0
	global_load_lds_dwordx4 v[196:197], off
	s_barrier
	s_waitcnt lgkmcnt(0)
	s_waitcnt lgkmcnt(0)
	v_mfma_f32_16x16x32_bf16 v[134:137], v[178:181], v[146:149], v[134:137]
	v_mfma_f32_16x16x32_bf16 v[126:129], v[186:189], v[146:149], v[126:129]
	v_mfma_f32_16x16x32_bf16 v[118:121], v[178:181], v[154:157], v[118:121]
	v_mfma_f32_16x16x32_bf16 v[110:113], v[186:189], v[154:157], v[110:113]
	v_mfma_f32_16x16x32_bf16 v[88:91], v[178:181], v[162:165], v[88:91]
	v_mfma_f32_16x16x32_bf16 v[76:79], v[186:189], v[162:165], v[76:79]
	v_mfma_f32_16x16x32_bf16 v[68:71], v[178:181], v[170:173], v[68:71]
	v_mfma_f32_16x16x32_bf16 v[64:67], v[186:189], v[170:173], v[64:67]
	v_mfma_f32_16x16x32_bf16 v[134:137], v[182:185], v[150:153], v[134:137]
	v_mfma_f32_16x16x32_bf16 v[126:129], v[190:193], v[150:153], v[126:129]
	v_mfma_f32_16x16x32_bf16 v[118:121], v[182:185], v[158:161], v[118:121]
	v_mfma_f32_16x16x32_bf16 v[110:113], v[190:193], v[158:161], v[110:113]
	v_mfma_f32_16x16x32_bf16 v[88:91], v[182:185], v[166:169], v[88:91]
	v_mfma_f32_16x16x32_bf16 v[76:79], v[190:193], v[166:169], v[76:79]
	v_mfma_f32_16x16x32_bf16 v[68:71], v[182:185], v[174:177], v[68:71]
	v_mfma_f32_16x16x32_bf16 v[64:67], v[190:193], v[174:177], v[64:67]
	s_mov_b32 m0, s61
	v_lshl_add_u64 v[198:199], vcc, 0, v[96:97]
	s_barrier
	ds_read_b128 v[146:149], v242 offset:16384
	ds_read_b128 v[150:153], v242 offset:17408
	ds_read_b128 v[154:157], v242 offset:18432
	ds_read_b128 v[158:161], v242 offset:19456
	ds_read_b128 v[162:165], v242 offset:20480
	ds_read_b128 v[166:169], v242 offset:21504
	ds_read_b128 v[170:173], v242 offset:22528
	ds_read_b128 v[174:177], v242 offset:23552
	global_load_lds_dwordx4 v[198:199], off
	v_lshl_add_u64 v[200:201], vcc, 0, v[208:209]
	s_mov_b32 m0, s62
	s_nop 0
	global_load_lds_dwordx4 v[200:201], off
	s_barrier
	s_waitcnt lgkmcnt(0)
	s_waitcnt lgkmcnt(0)
	v_mfma_f32_16x16x32_bf16 v[60:63], v[84:87], v[146:149], v[60:63]
	v_mfma_f32_16x16x32_bf16 v[56:59], v[98:101], v[146:149], v[56:59]
	v_mfma_f32_16x16x32_bf16 v[48:51], v[84:87], v[154:157], v[48:51]
	v_mfma_f32_16x16x32_bf16 v[40:43], v[98:101], v[154:157], v[40:43]
	v_mfma_f32_16x16x32_bf16 v[32:35], v[84:87], v[162:165], v[32:35]
	v_mfma_f32_16x16x32_bf16 v[24:27], v[98:101], v[162:165], v[24:27]
	v_mfma_f32_16x16x32_bf16 v[16:19], v[84:87], v[170:173], v[16:19]
	v_mfma_f32_16x16x32_bf16 v[8:11], v[98:101], v[170:173], v[8:11]
	v_mfma_f32_16x16x32_bf16 v[60:63], v[92:95], v[150:153], v[60:63]
	v_mfma_f32_16x16x32_bf16 v[56:59], v[102:105], v[150:153], v[56:59]
	v_mfma_f32_16x16x32_bf16 v[48:51], v[92:95], v[158:161], v[48:51]
	v_mfma_f32_16x16x32_bf16 v[40:43], v[102:105], v[158:161], v[40:43]
	v_mfma_f32_16x16x32_bf16 v[32:35], v[92:95], v[166:169], v[32:35]
	v_mfma_f32_16x16x32_bf16 v[24:27], v[102:105], v[166:169], v[24:27]
	v_mfma_f32_16x16x32_bf16 v[16:19], v[92:95], v[174:177], v[16:19]
	v_mfma_f32_16x16x32_bf16 v[8:11], v[102:105], v[174:177], v[8:11]
	s_barrier
	s_add_u32 s38, s52, 0x40000
	s_addc_u32 s39, s53, 0
	s_add_i32 s42, s42, s58
	v_lshl_add_u64 v[84:85], s[38:39], 0, v[96:97]
	s_mov_b32 m0, s42
	s_nop 0
	global_load_lds_dwordx4 v[84:85], off
	v_lshl_add_u64 v[84:85], s[38:39], 0, v[208:209]
	s_add_i32 m0, s42, 0x2000
	s_nop 0
	global_load_lds_dwordx4 v[84:85], off
	s_waitcnt vmcnt(6)
	s_barrier
	v_mfma_f32_16x16x32_bf16 v[52:55], v[178:181], v[146:149], v[52:55]
	v_mfma_f32_16x16x32_bf16 v[44:47], v[186:189], v[146:149], v[44:47]
	v_mfma_f32_16x16x32_bf16 v[36:39], v[178:181], v[154:157], v[36:39]
	v_mfma_f32_16x16x32_bf16 v[28:31], v[186:189], v[154:157], v[28:31]
	v_mfma_f32_16x16x32_bf16 v[20:23], v[178:181], v[162:165], v[20:23]
	v_mfma_f32_16x16x32_bf16 v[12:15], v[186:189], v[162:165], v[12:15]
	v_mfma_f32_16x16x32_bf16 v[4:7], v[178:181], v[170:173], v[4:7]
	v_mfma_f32_16x16x32_bf16 v[0:3], v[186:189], v[170:173], v[0:3]
	v_mfma_f32_16x16x32_bf16 v[52:55], v[182:185], v[150:153], v[52:55]
	v_mfma_f32_16x16x32_bf16 v[44:47], v[190:193], v[150:153], v[44:47]
	v_mfma_f32_16x16x32_bf16 v[36:39], v[182:185], v[158:161], v[36:39]
	v_mfma_f32_16x16x32_bf16 v[28:31], v[190:193], v[158:161], v[28:31]
	v_mfma_f32_16x16x32_bf16 v[20:23], v[182:185], v[166:169], v[20:23]
	v_mfma_f32_16x16x32_bf16 v[12:15], v[190:193], v[166:169], v[12:15]
	v_mfma_f32_16x16x32_bf16 v[4:7], v[182:185], v[174:177], v[4:7]
	v_mfma_f32_16x16x32_bf16 v[0:3], v[190:193], v[174:177], v[0:3]
	s_add_i32 s42, 0, 0x18000
	v_add_u32_e32 v102, s42, v240
	s_barrier
	ds_read_b128 v[84:87], v102
	ds_read_b128 v[92:95], v102 offset:1024
	ds_read_b128 v[98:101], v102 offset:2048
	ds_read_b128 v[102:105], v102 offset:3072
	s_add_u32 s38, vcc_lo, 0x40000
	s_addc_u32 s39, vcc_hi, 0
	s_mov_b32 m0, s63
	v_lshl_add_u64 v[178:179], s[38:39], 0, v[96:97]
	ds_read_b128 v[146:149], v242 offset:32768
	ds_read_b128 v[150:153], v242 offset:33792
	ds_read_b128 v[154:157], v242 offset:34816
	ds_read_b128 v[158:161], v242 offset:35840
	ds_read_b128 v[162:165], v242 offset:36864
	ds_read_b128 v[166:169], v242 offset:37888
	ds_read_b128 v[170:173], v242 offset:38912
	ds_read_b128 v[174:177], v242 offset:39936
	global_load_lds_dwordx4 v[178:179], off
	v_lshl_add_u64 v[178:179], s[38:39], 0, v[208:209]
	s_mov_b32 m0, s64
	s_nop 0
	global_load_lds_dwordx4 v[178:179], off
	s_waitcnt lgkmcnt(8)
	s_barrier
; #define PG8_STAGE(bufoff, gbase, voff) do { _Pragma("unroll") for (int _i = 0; _i < 2; ++_i) \
;         __builtin_amdgcn_global_load_lds((const unsigned*)((const char*)(gbase) + (voff)[_i]), (PG8_LAS unsigned*)(lds + (bufoff) + ldsw + _i * 8192), 16, 0, 0); } while (0)
; #define PG8_LDA(dst, b, h) do { _Pragma("unroll") for (int m = 0; m < 4; ++m) _Pragma("unroll") for (int k = 0; k < 2; ++k) dst[m][k] = *(const PG8_LAS bf16x8*)(lds + PG8_SA(b, h) + aoff + m * 2048 + k * 1024); } while (0)
; #define PG8_LDB(dst, b, h) do { _Pragma("unroll") for (int n = 0; n < 2; ++n) _Pragma("unroll") for (int k = 0; k < 2; ++k) dst[n][k] = *(const PG8_LAS bf16x8*)(lds + PG8_SB(b, h) + boff + n * 2048 + k * 1024); } while (0)
; #define PG8_MMA(ai, bj, At, Bt) do { __builtin_amdgcn_s_setprio(1); _Pragma("unroll") for (int m = 0; m < 4; ++m) _Pragma("unroll") for (int n = 0; n < 2; ++n) _Pragma("unroll") for (int k = 0; k < 2; ++k) \
;         acc[ai][bj][m][n] = __builtin_amdgcn_mfma_f32_16x16x32_bf16(Bt[n][k], At[m][k], acc[ai][bj][m][n], 0, 0, 0); __builtin_amdgcn_s_setprio(0); } while (0)
; #define PG8_WAIT_V(n) asm volatile("s_waitcnt vmcnt(" #n ")" ::: "memory")
; #define PG8_WAIT_L(n) asm volatile("s_waitcnt lgkmcnt(" #n ")" ::: "memory")
; #define PG8_BAR __builtin_amdgcn_s_barrier()
; #define PG8_SCHED __builtin_amdgcn_sched_barrier(0)
; template <class Epi, class Sched>
; __device__ __forceinline__ void gemm_phase(PG8_LAS unsigned char* lds, const Gemm g, const Sched& S, const Epi& E) {
;     ...
;             PG8_WAIT_L(8); PG8_BAR; PG8_WAIT_L(0); PG8_MMA(0, 0, At, B0); PG8_BAR; PG8_SCHED;
;             PG8_LDB(B1, 1, 1); PG8_STAGE(PG8_SB(1, 0), b3, voffB);
;             PG8_BAR; PG8_WAIT_L(0); PG8_MMA(0, 1, At, B1); PG8_BAR;
;             PG8_LDA(At, 1, 1); PG8_STAGE(PG8_SA(1, 0), a3, voffA);
;             PG8_BAR; PG8_WAIT_L(0); PG8_MMA(1, 0, At, B0); PG8_BAR; PG8_SCHED;
;             PG8_STAGE(PG8_SB(1, 1), b3 + hstep, voffB);
;             PG8_WAIT_V(6); PG8_BAR; PG8_MMA(1, 1, At, B1); PG8_BAR;
;         }
	s_waitcnt lgkmcnt(0)
	s_waitcnt lgkmcnt(0)
	v_mfma_f32_16x16x32_bf16 v[142:145], v[84:87], v[146:149], v[142:145]
	v_mfma_f32_16x16x32_bf16 v[138:141], v[98:101], v[146:149], v[138:141]
	v_mfma_f32_16x16x32_bf16 v[130:133], v[84:87], v[154:157], v[130:133]
	v_mfma_f32_16x16x32_bf16 v[122:125], v[98:101], v[154:157], v[122:125]
	v_mfma_f32_16x16x32_bf16 v[114:117], v[84:87], v[162:165], v[114:117]
	v_mfma_f32_16x16x32_bf16 v[106:109], v[98:101], v[162:165], v[106:109]
	v_mfma_f32_16x16x32_bf16 v[80:83], v[84:87], v[170:173], v[80:83]
	v_mfma_f32_16x16x32_bf16 v[72:75], v[98:101], v[170:173], v[72:75]
	v_mfma_f32_16x16x32_bf16 v[142:145], v[92:95], v[150:153], v[142:145]
	v_mfma_f32_16x16x32_bf16 v[138:141], v[102:105], v[150:153], v[138:141]
	v_mfma_f32_16x16x32_bf16 v[130:133], v[92:95], v[158:161], v[130:133]
	v_mfma_f32_16x16x32_bf16 v[122:125], v[102:105], v[158:161], v[122:125]
	v_mfma_f32_16x16x32_bf16 v[114:117], v[92:95], v[166:169], v[114:117]
	v_mfma_f32_16x16x32_bf16 v[106:109], v[102:105], v[166:169], v[106:109]
	v_mfma_f32_16x16x32_bf16 v[80:83], v[92:95], v[174:177], v[80:83]
	v_mfma_f32_16x16x32_bf16 v[72:75], v[102:105], v[174:177], v[72:75]
	s_barrier
	s_add_i32 s43, 0, 0x1c000
	s_add_i32 s38, s42, s58
	v_add_u32_e32 v190, s43, v240
	v_lshl_add_u64 v[194:195], v[194:195], 0, s[2:3]
	s_mov_b32 m0, s38
	ds_read_b128 v[178:181], v190
	ds_read_b128 v[182:185], v190 offset:1024
	ds_read_b128 v[186:189], v190 offset:2048
	ds_read_b128 v[190:193], v190 offset:3072
	global_load_lds_dwordx4 v[194:195], off
	v_lshl_add_u64 v[194:195], v[196:197], 0, s[2:3]
	s_add_i32 m0, s38, 0x2000
	s_nop 0
	global_load_lds_dwordx4 v[194:195], off
	s_barrier
	s_waitcnt lgkmcnt(0)
	s_waitcnt lgkmcnt(0)
	v_mfma_f32_16x16x32_bf16 v[134:137], v[178:181], v[146:149], v[134:137]
	v_mfma_f32_16x16x32_bf16 v[126:129], v[186:189], v[146:149], v[126:129]
	v_mfma_f32_16x16x32_bf16 v[118:121], v[178:181], v[154:157], v[118:121]
	v_mfma_f32_16x16x32_bf16 v[110:113], v[186:189], v[154:157], v[110:113]
	v_mfma_f32_16x16x32_bf16 v[88:91], v[178:181], v[162:165], v[88:91]
	v_mfma_f32_16x16x32_bf16 v[76:79], v[186:189], v[162:165], v[76:79]
	v_mfma_f32_16x16x32_bf16 v[68:71], v[178:181], v[170:173], v[68:71]
	v_mfma_f32_16x16x32_bf16 v[64:67], v[186:189], v[170:173], v[64:67]
	v_mfma_f32_16x16x32_bf16 v[134:137], v[182:185], v[150:153], v[134:137]
	v_mfma_f32_16x16x32_bf16 v[126:129], v[190:193], v[150:153], v[126:129]
	v_mfma_f32_16x16x32_bf16 v[118:121], v[182:185], v[158:161], v[118:121]
	v_mfma_f32_16x16x32_bf16 v[110:113], v[190:193], v[158:161], v[110:113]
	v_mfma_f32_16x16x32_bf16 v[88:91], v[182:185], v[166:169], v[88:91]
	v_mfma_f32_16x16x32_bf16 v[76:79], v[190:193], v[166:169], v[76:79]
	v_mfma_f32_16x16x32_bf16 v[68:71], v[182:185], v[174:177], v[68:71]
	v_mfma_f32_16x16x32_bf16 v[64:67], v[190:193], v[174:177], v[64:67]
	s_mov_b32 m0, s69
	v_lshl_add_u64 v[194:195], v[198:199], 0, s[2:3]
	s_barrier
	ds_read_b128 v[146:149], v242 offset:49152
	ds_read_b128 v[150:153], v242 offset:50176
	ds_read_b128 v[154:157], v242 offset:51200
	ds_read_b128 v[158:161], v242 offset:52224
	ds_read_b128 v[162:165], v242 offset:53248
	ds_read_b128 v[166:169], v242 offset:54272
	ds_read_b128 v[170:173], v242 offset:55296
	ds_read_b128 v[174:177], v242 offset:56320
	global_load_lds_dwordx4 v[194:195], off
	v_lshl_add_u64 v[194:195], v[200:201], 0, s[2:3]
	s_mov_b32 m0, s70
	s_nop 0
	global_load_lds_dwordx4 v[194:195], off
	s_barrier
	s_waitcnt lgkmcnt(0)
	s_waitcnt lgkmcnt(0)
	v_mfma_f32_16x16x32_bf16 v[60:63], v[84:87], v[146:149], v[60:63]
	v_mfma_f32_16x16x32_bf16 v[56:59], v[98:101], v[146:149], v[56:59]
	v_mfma_f32_16x16x32_bf16 v[48:51], v[84:87], v[154:157], v[48:51]
	v_mfma_f32_16x16x32_bf16 v[40:43], v[98:101], v[154:157], v[40:43]
	v_mfma_f32_16x16x32_bf16 v[32:35], v[84:87], v[162:165], v[32:35]
	v_mfma_f32_16x16x32_bf16 v[24:27], v[98:101], v[162:165], v[24:27]
	v_mfma_f32_16x16x32_bf16 v[16:19], v[84:87], v[170:173], v[16:19]
	v_mfma_f32_16x16x32_bf16 v[8:11], v[98:101], v[170:173], v[8:11]
	v_mfma_f32_16x16x32_bf16 v[60:63], v[92:95], v[150:153], v[60:63]
	v_mfma_f32_16x16x32_bf16 v[56:59], v[102:105], v[150:153], v[56:59]
	v_mfma_f32_16x16x32_bf16 v[48:51], v[92:95], v[158:161], v[48:51]
	v_mfma_f32_16x16x32_bf16 v[40:43], v[102:105], v[158:161], v[40:43]
	v_mfma_f32_16x16x32_bf16 v[32:35], v[92:95], v[166:169], v[32:35]
	v_mfma_f32_16x16x32_bf16 v[24:27], v[102:105], v[166:169], v[24:27]
	v_mfma_f32_16x16x32_bf16 v[16:19], v[92:95], v[174:177], v[16:19]
	v_mfma_f32_16x16x32_bf16 v[8:11], v[102:105], v[174:177], v[8:11]
	s_barrier
	s_add_u32 s38, s52, 0x40080
	s_addc_u32 s39, s53, 0
	s_add_i32 s42, s43, s58
	v_lshl_add_u64 v[84:85], s[38:39], 0, v[96:97]
	s_mov_b32 m0, s42
	s_nop 0
	global_load_lds_dwordx4 v[84:85], off
	v_lshl_add_u64 v[84:85], s[38:39], 0, v[208:209]
	s_add_i32 m0, s42, 0x2000
	s_nop 0
	global_load_lds_dwordx4 v[84:85], off
	s_waitcnt vmcnt(6)
	s_barrier
	v_mfma_f32_16x16x32_bf16 v[52:55], v[178:181], v[146:149], v[52:55]
	v_mfma_f32_16x16x32_bf16 v[44:47], v[186:189], v[146:149], v[44:47]
	v_mfma_f32_16x16x32_bf16 v[36:39], v[178:181], v[154:157], v[36:39]
	v_mfma_f32_16x16x32_bf16 v[28:31], v[186:189], v[154:157], v[28:31]
	v_mfma_f32_16x16x32_bf16 v[20:23], v[178:181], v[162:165], v[20:23]
	v_mfma_f32_16x16x32_bf16 v[12:15], v[186:189], v[162:165], v[12:15]
	v_mfma_f32_16x16x32_bf16 v[4:7], v[178:181], v[170:173], v[4:7]
	v_mfma_f32_16x16x32_bf16 v[0:3], v[186:189], v[170:173], v[0:3]
	v_mfma_f32_16x16x32_bf16 v[52:55], v[182:185], v[150:153], v[52:55]
	v_mfma_f32_16x16x32_bf16 v[44:47], v[190:193], v[150:153], v[44:47]
	v_mfma_f32_16x16x32_bf16 v[36:39], v[182:185], v[158:161], v[36:39]
	v_mfma_f32_16x16x32_bf16 v[28:31], v[190:193], v[158:161], v[28:31]
	v_mfma_f32_16x16x32_bf16 v[20:23], v[182:185], v[166:169], v[20:23]
	v_mfma_f32_16x16x32_bf16 v[12:15], v[190:193], v[166:169], v[12:15]
	v_mfma_f32_16x16x32_bf16 v[4:7], v[182:185], v[174:177], v[4:7]
	v_mfma_f32_16x16x32_bf16 v[0:3], v[190:193], v[174:177], v[0:3]
	s_add_i32 s60, s60, 2
	s_add_u32 s56, s56, 0x100
	s_addc_u32 s57, s57, 0
	s_cmp_gt_u32 s60, 13
	s_mov_b64 s[38:39], s[40:41]
	s_barrier
;   DEV void operator()(const f32x4 (&acc)[2][2][4][2], const pg8::Unit& u, int wr, int wc, int fr, int fq) const {
;     const int row0 = u.pm * 256 + wr * 64 + fr, col0 = u.pn * 256 + wc * 32 + 4 * fq;
;     const float* gt = mod + (size_t)modrow(row0) * 6144;
;     f32x4 g4[2][2];
; #pragma unroll
;     for (int bj = 0; bj < 2; ++bj)
; #pragma unroll
;       for (int n = 0; n < 2; ++n) g4[bj][n] = *(const f32x4*)(gt + col0 + bj * 128 + n * 16);
; #pragma unroll
;     for (int ai = 0; ai < 2; ++ai) {
;       f32x4 xv[4][2][2];
; #pragma unroll
;       for (int m = 0; m < 4; ++m) {
;         const int row = row0 + ai * 128 + m * 16;
;         const float* xi = row < T_LAT ? rin_lat + (size_t)row * DM : rin_ctx + (size_t)(row - T_LAT) * DM;
; #pragma unroll
;         for (int bj = 0; bj < 2; ++bj)
; #pragma unroll
;           for (int n = 0; n < 2; ++n) xv[m][bj][n] = *(const f32x4*)(xi + col0 + bj * 128 + n * 16);
;       }
; #pragma unroll
;       for (int m = 0; m < 4; ++m) {
;         const int row = row0 + ai * 128 + m * 16;
;         float* xr = row < T_LAT ? out + (size_t)row * DM : xc + (size_t)(row - T_LAT) * DM;
; #pragma unroll
;         for (int bj = 0; bj < 2; ++bj)
; #pragma unroll
;           for (int n = 0; n < 2; ++n) {
;             const f32x4 r = xv[m][bj][n] + g4[bj][n] * acc[ai][bj][m][n];
;             if (store) *(f32x4*)(xr + col0 + bj * 128 + n * 16) = r;
;           }
;       }
;     }
;   }
	s_cbranch_scc0 .LBB0_87
	v_lshl_add_u32 v247, s0, 8, v239
	s_mov_b32 s42, 0x8000
	v_min_i32_e32 v85, 0x8000, v247
	v_cmp_gt_i32_e64 s[40:41], s42, v247
	v_add_u32_e32 v146, 0xffff8000, v247
	v_ashrrev_i32_e32 v147, 31, v247
	v_lshl_or_b32 v84, s1, 8, v241
	v_ashrrev_i32_e32 v85, 12, v85
	v_cndmask_b32_e64 v147, 0, v147, s[40:41]
	v_cndmask_b32_e64 v146, v146, v247, s[40:41]
	v_mov_b32_e32 v248, s67
	v_mov_b32_e32 v249, s65
	v_mov_b32_e32 v250, s68
	v_mov_b32_e32 v238, s66
	v_mul_hi_i32_i24_e32 v87, 0x6000, v85
	v_mul_i32_i24_e32 v86, 0x6000, v85
	v_ashrrev_i32_e32 v85, 31, v84
	v_cndmask_b32_e64 v149, v248, v249, s[40:41]
	v_cndmask_b32_e64 v148, v250, v238, s[40:41]
	v_lshlrev_b64 v[222:223], 12, v[146:147]
	v_lshlrev_b64 v[214:215], 2, v[84:85]
	v_lshl_add_u64 v[146:147], v[148:149], 0, v[222:223]
	v_lshl_add_u64 v[224:225], v[146:147], 0, v[214:215]
	v_or_b32_e32 v146, 16, v247
	v_cmp_gt_i32_e64 s[38:39], s42, v146
	v_ashrrev_i32_e32 v147, 31, v146
	v_add_u32_e32 v148, 0xffff8010, v247
	v_cndmask_b32_e64 v147, 0, v147, s[38:39]
	v_cndmask_b32_e64 v146, v148, v146, s[38:39]
	v_cndmask_b32_e64 v149, v248, v249, s[38:39]
	v_cndmask_b32_e64 v148, v250, v238, s[38:39]
	v_lshlrev_b64 v[220:221], 12, v[146:147]
	v_lshl_add_u64 v[86:87], s[30:31], 0, v[86:87]
	v_lshl_add_u64 v[146:147], v[148:149], 0, v[220:221]
	v_lshl_add_u64 v[84:85], v[86:87], 0, v[214:215]
	v_lshl_add_u64 v[146:147], v[146:147], 0, v[214:215]
	global_load_dwordx4 v[102:105], v[84:85], off
	global_load_dwordx4 v[98:101], v[84:85], off offset:64
	global_load_dwordx4 v[92:95], v[84:85], off offset:512
	s_nop 0
	global_load_dwordx4 v[84:87], v[84:85], off offset:576
	s_nop 0
	global_load_dwordx4 v[202:205], v[224:225], off offset:64
	global_load_dwordx4 v[198:201], v[224:225], off offset:512
	global_load_dwordx4 v[194:197], v[224:225], off offset:576
	global_load_dwordx4 v[190:193], v[146:147], off
	global_load_dwordx4 v[186:189], v[146:147], off offset:64
	global_load_dwordx4 v[182:185], v[146:147], off offset:512
	global_load_dwordx4 v[178:181], v[146:147], off offset:576
	v_or_b32_e32 v146, 32, v247
	v_cmp_gt_i32_e64 s[0:1], s42, v146
	v_ashrrev_i32_e32 v147, 31, v146
	v_add_u32_e32 v148, 0xffff8020, v247
	v_cndmask_b32_e64 v147, 0, v147, s[0:1]
	v_cndmask_b32_e64 v146, v148, v146, s[0:1]
	v_cndmask_b32_e64 v149, v248, v249, s[0:1]
	v_cndmask_b32_e64 v148, v250, v238, s[0:1]
	v_lshlrev_b64 v[218:219], 12, v[146:147]
	v_lshl_add_u64 v[146:147], v[148:149], 0, v[218:219]
	v_lshl_add_u64 v[146:147], v[146:147], 0, v[214:215]
	global_load_dwordx4 v[174:177], v[146:147], off
	global_load_dwordx4 v[170:173], v[146:147], off offset:64
	global_load_dwordx4 v[166:169], v[146:147], off offset:512
	global_load_dwordx4 v[162:165], v[146:147], off offset:576
	v_or_b32_e32 v146, 48, v247
	v_cmp_gt_i32_e32 vcc, s42, v146
	v_ashrrev_i32_e32 v147, 31, v146
	v_add_u32_e32 v148, 0xffff8030, v247
	v_cndmask_b32_e32 v147, 0, v147, vcc
	v_cndmask_b32_e32 v146, v148, v146, vcc
	v_readlane_b32 s42, v251, 52
	v_cndmask_b32_e32 v149, v248, v249, vcc
	v_cndmask_b32_e32 v148, v250, v238, vcc
	v_lshlrev_b64 v[216:217], 12, v[146:147]
	v_mov_b32_e32 v243, s42
	v_readlane_b32 s42, v251, 51
	v_lshl_add_u64 v[146:147], v[148:149], 0, v[216:217]
	v_mov_b32_e32 v244, s73
	v_mov_b32_e32 v245, s42
	v_mov_b32_e32 v246, s72
	v_lshl_add_u64 v[146:147], v[146:147], 0, v[214:215]
	v_cndmask_b32_e64 v229, v243, v244, s[40:41]
	v_cndmask_b32_e64 v228, v245, v246, s[40:41]
	global_load_dwordx4 v[158:161], v[146:147], off
	global_load_dwordx4 v[154:157], v[146:147], off offset:64
	global_load_dwordx4 v[150:153], v[146:147], off offset:512
	s_nop 0
	global_load_dwordx4 v[146:149], v[146:147], off offset:576
	v_lshl_add_u64 v[222:223], v[228:229], 0, v[222:223]
	global_load_dwordx4 v[228:231], v[224:225], off
	v_lshl_add_u64 v[222:223], v[222:223], 0, v[214:215]
	s_movk_i32 s42, 0x7f50
	s_waitcnt vmcnt(0)
	v_pk_fma_f32 v[140:141], v[140:141], v[100:101], v[204:205]
	v_pk_fma_f32 v[136:137], v[136:137], v[94:95], v[200:201]
	v_pk_fma_f32 v[128:129], v[128:129], v[86:87], v[196:197]
	v_pk_fma_f32 v[126:127], v[126:127], v[84:85], v[194:195]
	global_store_dwordx4 v[222:223], v[126:129], off offset:576
	v_pk_fma_f32 v[134:135], v[134:135], v[92:93], v[198:199]
	v_pk_fma_f32 v[138:139], v[138:139], v[98:99], v[202:203]
	v_cndmask_b32_e64 v127, v243, v244, s[38:39]
	v_cndmask_b32_e64 v126, v245, v246, s[38:39]
	v_lshl_add_u64 v[126:127], v[126:127], 0, v[220:221]
	global_store_dwordx4 v[222:223], v[134:137], off offset:512
	v_pk_fma_f32 v[112:113], v[112:113], v[86:87], v[180:181]
	v_pk_fma_f32 v[110:111], v[110:111], v[84:85], v[178:179]
	v_lshl_add_u64 v[134:135], v[126:127], 0, v[214:215]
	global_store_dwordx4 v[222:223], v[138:141], off offset:64
	v_pk_fma_f32 v[120:121], v[120:121], v[94:95], v[184:185]
	v_pk_fma_f32 v[118:119], v[118:119], v[92:93], v[182:183]
	v_pk_fma_f32 v[128:129], v[132:133], v[104:105], v[192:193]
	v_pk_fma_f32 v[126:127], v[130:131], v[102:103], v[190:191]
	v_pk_fma_f32 v[124:125], v[124:125], v[100:101], v[188:189]
	v_pk_fma_f32 v[122:123], v[122:123], v[98:99], v[186:187]
	v_pk_fma_f32 v[78:79], v[78:79], v[86:87], v[164:165]
	v_pk_fma_f32 v[76:77], v[76:77], v[84:85], v[162:163]
	v_pk_fma_f32 v[90:91], v[90:91], v[94:95], v[168:169]
	v_pk_fma_f32 v[88:89], v[88:89], v[92:93], v[166:167]
	v_pk_fma_f32 v[108:109], v[108:109], v[100:101], v[172:173]
	v_pk_fma_f32 v[106:107], v[106:107], v[98:99], v[170:171]
	v_pk_fma_f32 v[74:75], v[74:75], v[100:101], v[156:157]
	v_pk_fma_f32 v[68:69], v[68:69], v[92:93], v[150:151]
	v_pk_fma_f32 v[66:67], v[66:67], v[86:87], v[148:149]
;   DEV void operator()(const f32x4 (&acc)[2][2][4][2], const pg8::Unit& u, int wr, int wc, int fr, int fq) const {
;     ...
;     for (int ai = 0; ai < 2; ++ai) {
;       f32x4 xv[4][2][2];
; #pragma unroll
;       for (int m = 0; m < 4; ++m) {
;         const int row = row0 + ai * 128 + m * 16;
;         const float* xi = row < T_LAT ? rin_lat + (size_t)row * DM : rin_ctx + (size_t)(row - T_LAT) * DM;
; #pragma unroll
;         for (int bj = 0; bj < 2; ++bj)
; #pragma unroll
;           for (int n = 0; n < 2; ++n) xv[m][bj][n] = *(const f32x4*)(xi + col0 + bj * 128 + n * 16);
;       }
; #pragma unroll
;       for (int m = 0; m < 4; ++m) {
;         const int row = row0 + ai * 128 + m * 16;
;         float* xr = row < T_LAT ? out + (size_t)row * DM : xc + (size_t)(row - T_LAT) * DM;
; #pragma unroll
;         for (int bj = 0; bj < 2; ++bj)
; #pragma unroll
;           for (int n = 0; n < 2; ++n) {
;             const f32x4 r = xv[m][bj][n] + g4[bj][n] * acc[ai][bj][m][n];
;             if (store) *(f32x4*)(xr + col0 + bj * 128 + n * 16) = r;
;           }
;       }
;     }
	v_pk_fma_f32 v[64:65], v[64:65], v[84:85], v[146:147]
	v_pk_fma_f32 v[144:145], v[144:145], v[104:105], v[230:231]
	v_pk_fma_f32 v[142:143], v[142:143], v[102:103], v[228:229]
	global_store_dwordx4 v[222:223], v[142:145], off
	global_store_dwordx4 v[134:135], v[110:113], off offset:576
	global_store_dwordx4 v[134:135], v[118:121], off offset:512
	global_store_dwordx4 v[134:135], v[126:129], off
	v_cndmask_b32_e64 v111, v243, v244, s[0:1]
	v_cndmask_b32_e64 v110, v245, v246, s[0:1]
	v_lshl_add_u64 v[110:111], v[110:111], 0, v[218:219]
	v_lshl_add_u64 v[118:119], v[110:111], 0, v[214:215]
	global_store_dwordx4 v[134:135], v[122:125], off offset:64
	global_store_dwordx4 v[118:119], v[76:79], off offset:576
	v_pk_fma_f32 v[112:113], v[116:117], v[104:105], v[176:177]
	v_pk_fma_f32 v[110:111], v[114:115], v[102:103], v[174:175]
	v_cndmask_b32_e32 v77, v243, v244, vcc
	v_cndmask_b32_e32 v76, v245, v246, vcc
	v_lshl_add_u64 v[76:77], v[76:77], 0, v[216:217]
	global_store_dwordx4 v[118:119], v[88:91], off offset:512
	global_store_dwordx4 v[118:119], v[110:113], off
	global_store_dwordx4 v[118:119], v[106:109], off offset:64
	v_lshl_add_u64 v[88:89], v[76:77], 0, v[214:215]
	global_store_dwordx4 v[88:89], v[64:67], off offset:576
	s_movk_i32 s0, 0x7f80
	v_cmp_gt_i32_e64 s[40:41], s0, v247
	v_add_u32_e32 v64, 0x80, v247
	v_ashrrev_i32_e32 v65, 31, v64
	v_add_u32_e32 v66, 0xffff8080, v247
	v_cndmask_b32_e64 v65, 0, v65, s[40:41]
	v_cndmask_b32_e64 v64, v66, v64, s[40:41]
	v_cndmask_b32_e64 v67, v248, v249, s[40:41]
	v_cndmask_b32_e64 v66, v250, v238, s[40:41]
	v_lshlrev_b64 v[148:149], 12, v[64:65]
	v_lshl_add_u64 v[64:65], v[66:67], 0, v[148:149]
	v_lshl_add_u64 v[150:151], v[64:65], 0, v[214:215]
	v_add_u32_e32 v64, 0x90, v247
	s_movk_i32 s0, 0x7f70
	v_cmp_gt_i32_e64 s[38:39], s0, v247
	v_ashrrev_i32_e32 v65, 31, v64
	v_add_u32_e32 v66, 0xffff8090, v247
	v_cndmask_b32_e64 v65, 0, v65, s[38:39]
	v_cndmask_b32_e64 v64, v66, v64, s[38:39]
	v_cndmask_b32_e64 v67, v248, v249, s[38:39]
	v_cndmask_b32_e64 v66, v250, v238, s[38:39]
	v_lshlrev_b64 v[146:147], 12, v[64:65]
	v_pk_fma_f32 v[78:79], v[82:83], v[104:105], v[160:161]
	v_pk_fma_f32 v[76:77], v[80:81], v[102:103], v[158:159]
	v_pk_fma_f32 v[72:73], v[72:73], v[98:99], v[154:155]
	v_pk_fma_f32 v[70:71], v[70:71], v[94:95], v[152:153]
	v_lshl_add_u64 v[64:65], v[66:67], 0, v[146:147]
	global_store_dwordx4 v[88:89], v[76:79], off
	global_store_dwordx4 v[88:89], v[72:75], off offset:64
	global_store_dwordx4 v[88:89], v[68:71], off offset:512
	v_lshl_add_u64 v[64:65], v[64:65], 0, v[214:215]
	global_load_dwordx4 v[138:141], v[150:151], off offset:64
	global_load_dwordx4 v[134:137], v[150:151], off offset:512
	global_load_dwordx4 v[130:133], v[150:151], off offset:576
	global_load_dwordx4 v[126:129], v[64:65], off
	global_load_dwordx4 v[122:125], v[64:65], off offset:64
	global_load_dwordx4 v[118:121], v[64:65], off offset:512
	global_load_dwordx4 v[114:117], v[64:65], off offset:576
	v_add_u32_e32 v64, 0xa0, v247
	s_movk_i32 s0, 0x7f60
	v_cmp_gt_i32_e64 s[0:1], s0, v247
	v_ashrrev_i32_e32 v65, 31, v64
	v_add_u32_e32 v66, 0xffff80a0, v247
	v_cndmask_b32_e64 v65, 0, v65, s[0:1]
	v_cndmask_b32_e64 v64, v66, v64, s[0:1]
	v_cndmask_b32_e64 v67, v248, v249, s[0:1]
	v_cndmask_b32_e64 v66, v250, v238, s[0:1]
	v_lshlrev_b64 v[144:145], 12, v[64:65]
	v_lshl_add_u64 v[64:65], v[66:67], 0, v[144:145]
	v_lshl_add_u64 v[64:65], v[64:65], 0, v[214:215]
	global_load_dwordx4 v[110:113], v[64:65], off
	global_load_dwordx4 v[106:109], v[64:65], off offset:64
	global_load_dwordx4 v[88:91], v[64:65], off offset:512
	global_load_dwordx4 v[80:83], v[64:65], off offset:576
	v_add_u32_e32 v64, 0xb0, v247
	v_cmp_gt_i32_e32 vcc, s42, v247
	v_ashrrev_i32_e32 v65, 31, v64
	v_add_u32_e32 v66, 0xffff80b0, v247
	v_cndmask_b32_e32 v65, 0, v65, vcc
	v_cndmask_b32_e32 v64, v66, v64, vcc
	v_cndmask_b32_e32 v67, v248, v249, vcc
	v_cndmask_b32_e32 v66, v250, v238, vcc
	v_lshlrev_b64 v[142:143], 12, v[64:65]
	v_lshl_add_u64 v[64:65], v[66:67], 0, v[142:143]
	v_lshl_add_u64 v[64:65], v[64:65], 0, v[214:215]
	v_cndmask_b32_e64 v153, v243, v244, s[40:41]
	v_cndmask_b32_e64 v152, v245, v246, s[40:41]
	global_load_dwordx4 v[76:79], v[64:65], off
	global_load_dwordx4 v[72:75], v[64:65], off offset:64
	global_load_dwordx4 v[68:71], v[64:65], off offset:512
	s_nop 0
	global_load_dwordx4 v[64:67], v[64:65], off offset:576
	v_lshl_add_u64 v[148:149], v[152:153], 0, v[148:149]
	global_load_dwordx4 v[150:153], v[150:151], off
	v_lshl_add_u64 v[148:149], v[148:149], 0, v[214:215]
	s_mov_b64 s[40:41], s[50:51]
	s_waitcnt vmcnt(0)
; #define PG8_WAIT_V(n) asm volatile("s_waitcnt vmcnt(" #n ")" ::: "memory")
; #define PG8_BAR __builtin_amdgcn_s_barrier()
; template <class Epi, class Sched>
; __device__ __forceinline__ void gemm_phase(PG8_LAS unsigned char* lds, const Gemm g, const Sched& S, const Epi& E) {
;     ...
;         if (!has_next) break;
; #pragma unroll
;         for (int a = 0; a < 2; ++a)
; #pragma unroll
;             for (int b = 0; b < 2; ++b)
; #pragma unroll
;                 for (int m = 0; m < 4; ++m)
; #pragma unroll
;                     for (int n = 0; n < 2; ++n) acc[a][b][m][n] = (f32x4){0.f, 0.f, 0.f, 0.f};
;         cur = nxt; cA = nA; cB = nB; ++ui;
;     }
;     PG8_WAIT_V(0);
;     if (wr == 0) PG8_BAR;
;     PG8_BAR;
;   DEV void operator()(const f32x4 (&acc)[2][2][4][2], const pg8::Unit& u, int wr, int wc, int fr, int fq) const {
;     ...
;     for (int ai = 0; ai < 2; ++ai) {
;       f32x4 xv[4][2][2];
; #pragma unroll
;       for (int m = 0; m < 4; ++m) {
;         const int row = row0 + ai * 128 + m * 16;
;         const float* xi = row < T_LAT ? rin_lat + (size_t)row * DM : rin_ctx + (size_t)(row - T_LAT) * DM;
; #pragma unroll
;         for (int bj = 0; bj < 2; ++bj)
; #pragma unroll
;           for (int n = 0; n < 2; ++n) xv[m][bj][n] = *(const f32x4*)(xi + col0 + bj * 128 + n * 16);
;       }
; #pragma unroll
;       for (int m = 0; m < 4; ++m) {
;         const int row = row0 + ai * 128 + m * 16;
;         float* xr = row < T_LAT ? out + (size_t)row * DM : xc + (size_t)(row - T_LAT) * DM;
; #pragma unroll
;         for (int bj = 0; bj < 2; ++bj)
; #pragma unroll
;           for (int n = 0; n < 2; ++n) {
;             const f32x4 r = xv[m][bj][n] + g4[bj][n] * acc[ai][bj][m][n];
;             if (store) *(f32x4*)(xr + col0 + bj * 128 + n * 16) = r;
;           }
;       }
;     }
	v_pk_fma_f32 v[58:59], v[58:59], v[100:101], v[140:141]
	v_pk_fma_f32 v[54:55], v[54:55], v[94:95], v[136:137]
	v_pk_fma_f32 v[46:47], v[46:47], v[86:87], v[132:133]
	v_pk_fma_f32 v[44:45], v[44:45], v[84:85], v[130:131]
	global_store_dwordx4 v[148:149], v[44:47], off offset:576
	v_pk_fma_f32 v[52:53], v[52:53], v[92:93], v[134:135]
	v_pk_fma_f32 v[56:57], v[56:57], v[98:99], v[138:139]
	v_cndmask_b32_e64 v45, v243, v244, s[38:39]
	v_cndmask_b32_e64 v44, v245, v246, s[38:39]
	v_lshl_add_u64 v[44:45], v[44:45], 0, v[146:147]
	global_store_dwordx4 v[148:149], v[52:55], off offset:512
	v_pk_fma_f32 v[30:31], v[30:31], v[86:87], v[116:117]
	v_pk_fma_f32 v[28:29], v[28:29], v[84:85], v[114:115]
	v_lshl_add_u64 v[52:53], v[44:45], 0, v[214:215]
	global_store_dwordx4 v[148:149], v[56:59], off offset:64
	v_pk_fma_f32 v[38:39], v[38:39], v[94:95], v[120:121]
	v_pk_fma_f32 v[36:37], v[36:37], v[92:93], v[118:119]
	v_pk_fma_f32 v[46:47], v[50:51], v[104:105], v[128:129]
	v_pk_fma_f32 v[44:45], v[48:49], v[102:103], v[126:127]
	v_pk_fma_f32 v[42:43], v[42:43], v[100:101], v[124:125]
	v_pk_fma_f32 v[40:41], v[40:41], v[98:99], v[122:123]
	v_pk_fma_f32 v[14:15], v[14:15], v[86:87], v[82:83]
	v_pk_fma_f32 v[12:13], v[12:13], v[84:85], v[80:81]
	v_pk_fma_f32 v[22:23], v[22:23], v[94:95], v[90:91]
	v_pk_fma_f32 v[20:21], v[20:21], v[92:93], v[88:89]
	v_pk_fma_f32 v[26:27], v[26:27], v[100:101], v[108:109]
	v_pk_fma_f32 v[24:25], v[24:25], v[98:99], v[106:107]
	s_mov_b64 s[38:39], s[48:49]
	v_pk_fma_f32 v[10:11], v[10:11], v[100:101], v[74:75]
	v_pk_fma_f32 v[8:9], v[8:9], v[98:99], v[72:73]
	v_pk_fma_f32 v[6:7], v[6:7], v[94:95], v[70:71]
	v_pk_fma_f32 v[4:5], v[4:5], v[92:93], v[68:69]
	v_pk_fma_f32 v[62:63], v[62:63], v[104:105], v[152:153]
	v_pk_fma_f32 v[60:61], v[60:61], v[102:103], v[150:151]
	global_store_dwordx4 v[148:149], v[60:63], off
	global_store_dwordx4 v[52:53], v[28:31], off offset:576
	global_store_dwordx4 v[52:53], v[36:39], off offset:512
	global_store_dwordx4 v[52:53], v[44:47], off
	v_cndmask_b32_e64 v29, v243, v244, s[0:1]
	v_cndmask_b32_e64 v28, v245, v246, s[0:1]
	v_lshl_add_u64 v[28:29], v[28:29], 0, v[144:145]
	v_lshl_add_u64 v[36:37], v[28:29], 0, v[214:215]
	global_store_dwordx4 v[52:53], v[40:43], off offset:64
	global_store_dwordx4 v[36:37], v[12:15], off offset:576
	v_pk_fma_f32 v[30:31], v[34:35], v[104:105], v[112:113]
	v_pk_fma_f32 v[28:29], v[32:33], v[102:103], v[110:111]
	v_cndmask_b32_e32 v13, v243, v244, vcc
	v_cndmask_b32_e32 v12, v245, v246, vcc
	v_lshl_add_u64 v[12:13], v[12:13], 0, v[142:143]
	global_store_dwordx4 v[36:37], v[20:23], off offset:512
	v_pk_fma_f32 v[14:15], v[18:19], v[104:105], v[78:79]
	v_pk_fma_f32 v[2:3], v[2:3], v[86:87], v[66:67]
	v_lshl_add_u64 v[20:21], v[12:13], 0, v[214:215]
	v_pk_fma_f32 v[12:13], v[16:17], v[102:103], v[76:77]
	v_pk_fma_f32 v[0:1], v[0:1], v[84:85], v[64:65]
	s_and_b64 vcc, exec, s[36:37]
	s_mov_b32 s1, s44
	s_mov_b32 s0, s46
	global_store_dwordx4 v[36:37], v[28:31], off
	global_store_dwordx4 v[36:37], v[24:27], off offset:64
	global_store_dwordx4 v[20:21], v[12:15], off
	global_store_dwordx4 v[20:21], v[8:11], off offset:64
	global_store_dwordx4 v[20:21], v[4:7], off offset:512
	global_store_dwordx4 v[20:21], v[0:3], off offset:576
	s_cbranch_vccz .LBB0_84
	s_waitcnt vmcnt(0)
	v_readlane_b32 s0, v255, 48
	v_readlane_b32 s66, v255, 34
	v_readlane_b32 s68, v255, 36
	s_cmpk_gt_u32 s0, 0xff
	v_readlane_b32 s67, v255, 35
	v_readlane_b32 s69, v255, 37
	v_readlane_b32 s70, v255, 41
	s_mov_b64 s[78:79], 0
	s_cbranch_scc1 .LBB0_91
	s_barrier

; #define PG8_BAR __builtin_amdgcn_s_barrier()
; template <class Epi, class Sched>
; __device__ __forceinline__ void gemm_phase(PG8_LAS unsigned char* lds, const Gemm g, const Sched& S, const Epi& E) {
;     ...
;         const bool has_next = S.next(ui + 1, nxt);
;         const char* nA = has_next ? (const char*)g.A + (size_t)nxt.pm * tstep : cA; const char* nB = has_next ? (const char*)g.Bt + (size_t)nxt.pn * tstep : cB;
;         for (int t = 0; t < nt; t += 2) {
;             const bool last = (t == nt - 2);
;             const char* a1 = cA + (size_t)(t + 1) * kstep;
;             const char* a2 = last ? nA : cA + (size_t)(t + 2) * kstep; const char* b2 = last ? nB : cB + (size_t)(t + 2) * kstep;
;             const char* a3 = a2 + kstep; const char* b3 = b2 + kstep;
;             if (last && has_next) S.a_ready(nxt);
;             PG8_LDB(B0, 0, 0); PG8_SCHED; PG8_LDA(At, 0, 0); PG8_STAGE(PG8_SA(1, 1), a1 + hstep, voffA);
;             PG8_WAIT_L(8); PG8_BAR; PG8_WAIT_L(0); PG8_MMA(0, 0, At, B0); PG8_BAR; PG8_SCHED;
;             PG8_LDB(B1, 0, 1); PG8_STAGE(PG8_SB(0, 0), b2, voffB);
;             PG8_BAR; PG8_WAIT_L(0); PG8_MMA(0, 1, At, B1); PG8_BAR;
;             PG8_LDA(At, 0, 1); PG8_STAGE(PG8_SA(0, 0), a2, voffA);
;             PG8_BAR; PG8_WAIT_L(0); PG8_MMA(1, 0, At, B0); PG8_BAR; PG8_SCHED;
;             PG8_STAGE(PG8_SB(0, 1), b2 + hstep, voffB);
;             PG8_WAIT_V(6); PG8_BAR; PG8_MMA(1, 1, At, B1); PG8_BAR;
;             PG8_LDB(B0, 1, 0); PG8_SCHED; PG8_LDA(At, 1, 0); PG8_STAGE(PG8_SA(0, 1), a2 + hstep, voffA);
;             PG8_WAIT_L(8); PG8_BAR; PG8_WAIT_L(0); PG8_MMA(0, 0, At, B0); PG8_BAR; PG8_SCHED;
;             PG8_LDB(B1, 1, 1); PG8_STAGE(PG8_SB(1, 0), b3, voffB);
;             PG8_BAR; PG8_WAIT_L(0); PG8_MMA(0, 1, At, B1); PG8_BAR;
;             PG8_LDA(At, 1, 1); PG8_STAGE(PG8_SA(1, 0), a3, voffA);
;             PG8_BAR; PG8_WAIT_L(0); PG8_MMA(1, 0, At, B0); PG8_BAR; PG8_SCHED;
;             PG8_STAGE(PG8_SB(1, 1), b3 + hstep, voffB);
;             PG8_WAIT_V(6); PG8_BAR; PG8_MMA(1, 1, At, B1); PG8_BAR;
;         }
;         if constexpr (!Epi::AFTER_DRAIN) { E(acc, cur, wr, wc, fr, fq); S.done(cur); }
;         if (!has_next) break;
; #pragma unroll
;         for (int a = 0; a < 2; ++a)
; #pragma unroll
;             for (int b = 0; b < 2; ++b)
; #pragma unroll
;                 for (int m = 0; m < 4; ++m)
; #pragma unroll
.LBB0_104:
	v_mov_b64_e32 v[0:1], s[54:55]
	s_ashr_i32 s39, s38, 31
	v_cmp_lt_i64_e32 vcc, s[40:41], v[0:1]
	s_lshl_b64 s[40:41], s[38:39], 18
	s_add_u32 s40, s74, s40
	s_addc_u32 s41, s75, s41
	s_and_b64 s[44:45], vcc, exec
	s_cselect_b32 s1, s41, s49
	s_cselect_b32 s39, s40, s48
	s_ashr_i32 s31, s30, 31
	s_lshl_b64 s[44:45], s[30:31], 18
	v_readlane_b32 s42, v251, 13
	v_readlane_b32 s43, v251, 14
	s_add_u32 s44, s42, s44
	s_addc_u32 s45, s43, s45
	s_and_b64 s[52:53], vcc, exec
	s_cselect_b32 s31, s45, s51
	s_cselect_b32 s47, s44, s50
	s_add_u32 s48, s48, 0x20080
	s_addc_u32 s49, s49, 0
	s_add_u32 s67, s50, 0x100
	v_mov_b32_e32 v0, 0
	s_addc_u32 s68, s51, 0
	s_mov_b32 s69, -2
	v_mov_b32_e32 v1, v0
	v_mov_b32_e32 v2, v0
	v_mov_b32_e32 v3, v0
	v_mov_b32_e32 v4, v0
	v_mov_b32_e32 v5, v0
	v_mov_b32_e32 v6, v0
	v_mov_b32_e32 v7, v0
	v_mov_b32_e32 v16, v0
	v_mov_b32_e32 v17, v0
	v_mov_b32_e32 v18, v0
	v_mov_b32_e32 v19, v0
	v_mov_b32_e32 v20, v0
	v_mov_b32_e32 v21, v0
	v_mov_b32_e32 v22, v0
	v_mov_b32_e32 v23, v0
	v_mov_b32_e32 v32, v0
	v_mov_b32_e32 v33, v0
	v_mov_b32_e32 v34, v0
	v_mov_b32_e32 v35, v0
	v_mov_b32_e32 v36, v0
	v_mov_b32_e32 v37, v0
	v_mov_b32_e32 v38, v0
	v_mov_b32_e32 v39, v0
	v_mov_b32_e32 v48, v0
	v_mov_b32_e32 v49, v0
	v_mov_b32_e32 v50, v0
	v_mov_b32_e32 v51, v0
	v_mov_b32_e32 v52, v0
	v_mov_b32_e32 v53, v0
	v_mov_b32_e32 v54, v0
	v_mov_b32_e32 v55, v0
	v_mov_b32_e32 v8, v0
	v_mov_b32_e32 v9, v0
	v_mov_b32_e32 v10, v0
	v_mov_b32_e32 v11, v0
	v_mov_b32_e32 v12, v0
	v_mov_b32_e32 v13, v0
	v_mov_b32_e32 v14, v0
	v_mov_b32_e32 v15, v0
	v_mov_b32_e32 v24, v0
	v_mov_b32_e32 v25, v0
	v_mov_b32_e32 v26, v0
	v_mov_b32_e32 v27, v0
	v_mov_b32_e32 v28, v0
	v_mov_b32_e32 v29, v0
	v_mov_b32_e32 v30, v0
	v_mov_b32_e32 v31, v0
	v_mov_b32_e32 v40, v0
	v_mov_b32_e32 v41, v0
	v_mov_b32_e32 v42, v0
	v_mov_b32_e32 v43, v0
	v_mov_b32_e32 v44, v0
	v_mov_b32_e32 v45, v0
	v_mov_b32_e32 v46, v0
	v_mov_b32_e32 v47, v0
	v_mov_b32_e32 v56, v0
	v_mov_b32_e32 v57, v0
	v_mov_b32_e32 v58, v0
	v_mov_b32_e32 v59, v0
	v_mov_b32_e32 v60, v0
	v_mov_b32_e32 v61, v0
	v_mov_b32_e32 v62, v0
	v_mov_b32_e32 v63, v0
	v_mov_b32_e32 v64, v0
	v_mov_b32_e32 v65, v0
	v_mov_b32_e32 v66, v0
	v_mov_b32_e32 v67, v0
	v_mov_b32_e32 v68, v0
	v_mov_b32_e32 v69, v0
	v_mov_b32_e32 v70, v0
	v_mov_b32_e32 v71, v0
	v_mov_b32_e32 v80, v0
	v_mov_b32_e32 v81, v0
	v_mov_b32_e32 v82, v0
	v_mov_b32_e32 v83, v0
	v_mov_b32_e32 v84, v0
	v_mov_b32_e32 v85, v0
	v_mov_b32_e32 v86, v0
	v_mov_b32_e32 v87, v0
	v_mov_b32_e32 v98, v0
	v_mov_b32_e32 v99, v0
	v_mov_b32_e32 v100, v0
	v_mov_b32_e32 v101, v0
	v_mov_b32_e32 v102, v0
	v_mov_b32_e32 v103, v0
	v_mov_b32_e32 v104, v0
	v_mov_b32_e32 v105, v0
	v_mov_b32_e32 v114, v0
	v_mov_b32_e32 v115, v0
	v_mov_b32_e32 v116, v0
	v_mov_b32_e32 v117, v0
	v_mov_b32_e32 v118, v0
	v_mov_b32_e32 v119, v0
	v_mov_b32_e32 v120, v0
	v_mov_b32_e32 v121, v0
	v_mov_b32_e32 v72, v0
	v_mov_b32_e32 v73, v0
	v_mov_b32_e32 v74, v0
	v_mov_b32_e32 v75, v0
	v_mov_b32_e32 v76, v0
	v_mov_b32_e32 v77, v0
	v_mov_b32_e32 v78, v0
	v_mov_b32_e32 v79, v0
	v_mov_b32_e32 v88, v0
	v_mov_b32_e32 v89, v0
	v_mov_b32_e32 v90, v0
	v_mov_b32_e32 v91, v0
	v_mov_b32_e32 v92, v0
	v_mov_b32_e32 v93, v0
	v_mov_b32_e32 v94, v0
	v_mov_b32_e32 v95, v0
	v_mov_b32_e32 v106, v0
	v_mov_b32_e32 v107, v0
	v_mov_b32_e32 v108, v0
	v_mov_b32_e32 v109, v0
	v_mov_b32_e32 v110, v0
	v_mov_b32_e32 v111, v0
	v_mov_b32_e32 v112, v0
	v_mov_b32_e32 v113, v0
	v_mov_b32_e32 v122, v0
	v_mov_b32_e32 v123, v0
	v_mov_b32_e32 v124, v0
	v_mov_b32_e32 v125, v0
	v_mov_b32_e32 v126, v0
	v_mov_b32_e32 v127, v0
	v_mov_b32_e32 v128, v0
	v_mov_b32_e32 v129, v0
	v_readfirstlane_b32 s100, v226
	s_nop 3
	s_lshr_b32 s100, s100, 8
	s_cmp_eq_u32 s100, 0
	s_cbranch_scc1 .Lgp_5880
	s_setprio 1
.Lgp_5880:
.LBB0_105:
	s_add_u32 s50, s48, 0xfffe0080
	s_addc_u32 s51, s49, -1
	s_add_i32 s70, 0, 0x10000
	v_add_u32_e32 v96, s70, v221
	ds_read_b128 v[130:133], v96
	ds_read_b128 v[134:137], v96 offset:1024
	ds_read_b128 v[138:141], v96 offset:2048
	ds_read_b128 v[142:145], v96 offset:3072
	s_cmp_eq_u32 s69, 4
	s_cselect_b32 s53, s1, s51
	s_cselect_b32 s52, s39, s50
	s_cselect_b32 s51, s31, s68
	s_cselect_b32 s50, s47, s67
	v_lshl_add_u64 v[178:179], s[48:49], 0, v[204:205]
	s_add_i32 m0, s59, 0xc000
	ds_read_b128 v[146:149], v223
	ds_read_b128 v[150:153], v223 offset:1024
	ds_read_b128 v[154:157], v223 offset:2048
	ds_read_b128 v[158:161], v223 offset:3072
	ds_read_b128 v[162:165], v223 offset:4096
	ds_read_b128 v[166:169], v223 offset:5120
	ds_read_b128 v[170:173], v223 offset:6144
	ds_read_b128 v[174:177], v223 offset:7168
	global_load_lds_dwordx4 v[178:179], off
	v_lshl_add_u64 v[178:179], s[48:49], 0, v[208:209]
	s_add_i32 m0, s59, 0xe000
	s_nop 0
	global_load_lds_dwordx4 v[178:179], off
	s_waitcnt lgkmcnt(8)
	s_barrier
	s_waitcnt lgkmcnt(0)
	s_waitcnt lgkmcnt(0)
	v_mfma_f32_16x16x32_bf16 v[126:129], v[130:133], v[146:149], v[126:129]
	v_mfma_f32_16x16x32_bf16 v[122:125], v[138:141], v[146:149], v[122:125]
	v_mfma_f32_16x16x32_bf16 v[110:113], v[130:133], v[154:157], v[110:113]
	v_mfma_f32_16x16x32_bf16 v[106:109], v[138:141], v[154:157], v[106:109]
	v_mfma_f32_16x16x32_bf16 v[92:95], v[130:133], v[162:165], v[92:95]
	v_mfma_f32_16x16x32_bf16 v[88:91], v[138:141], v[162:165], v[88:91]
	v_mfma_f32_16x16x32_bf16 v[76:79], v[130:133], v[170:173], v[76:79]
	v_mfma_f32_16x16x32_bf16 v[72:75], v[138:141], v[170:173], v[72:75]
	v_mfma_f32_16x16x32_bf16 v[126:129], v[134:137], v[150:153], v[126:129]
	v_mfma_f32_16x16x32_bf16 v[122:125], v[142:145], v[150:153], v[122:125]
	v_mfma_f32_16x16x32_bf16 v[110:113], v[134:137], v[158:161], v[110:113]
	v_mfma_f32_16x16x32_bf16 v[106:109], v[142:145], v[158:161], v[106:109]
	v_mfma_f32_16x16x32_bf16 v[92:95], v[134:137], v[166:169], v[92:95]
	v_mfma_f32_16x16x32_bf16 v[88:91], v[142:145], v[166:169], v[88:91]
	v_mfma_f32_16x16x32_bf16 v[76:79], v[134:137], v[174:177], v[76:79]
	v_mfma_f32_16x16x32_bf16 v[72:75], v[142:145], v[174:177], v[72:75]
	s_barrier
; #define PG8_STAGE(bufoff, gbase, voff) do { _Pragma("unroll") for (int _i = 0; _i < 2; ++_i) \
;         __builtin_amdgcn_global_load_lds((const unsigned*)((const char*)(gbase) + (voff)[_i]), (PG8_LAS unsigned*)(lds + (bufoff) + ldsw + _i * 8192), 16, 0, 0); } while (0)
; #define PG8_LDA(dst, b, h) do { _Pragma("unroll") for (int m = 0; m < 4; ++m) _Pragma("unroll") for (int k = 0; k < 2; ++k) dst[m][k] = *(const PG8_LAS bf16x8*)(lds + PG8_SA(b, h) + aoff + m * 2048 + k * 1024); } while (0)
; #define PG8_LDB(dst, b, h) do { _Pragma("unroll") for (int n = 0; n < 2; ++n) _Pragma("unroll") for (int k = 0; k < 2; ++k) dst[n][k] = *(const PG8_LAS bf16x8*)(lds + PG8_SB(b, h) + boff + n * 2048 + k * 1024); } while (0)
; #define PG8_MMA(ai, bj, At, Bt) do { __builtin_amdgcn_s_setprio(1); _Pragma("unroll") for (int m = 0; m < 4; ++m) _Pragma("unroll") for (int n = 0; n < 2; ++n) _Pragma("unroll") for (int k = 0; k < 2; ++k) \
;         acc[ai][bj][m][n] = __builtin_amdgcn_mfma_f32_16x16x32_bf16(Bt[n][k], At[m][k], acc[ai][bj][m][n], 0, 0, 0); __builtin_amdgcn_s_setprio(0); } while (0)
; #define PG8_WAIT_V(n) asm volatile("s_waitcnt vmcnt(" #n ")" ::: "memory")
; #define PG8_WAIT_L(n) asm volatile("s_waitcnt lgkmcnt(" #n ")" ::: "memory")
; #define PG8_BAR __builtin_amdgcn_s_barrier()
; #define PG8_SCHED __builtin_amdgcn_sched_barrier(0)
; template <class Epi, class Sched>
; __device__ __forceinline__ void gemm_phase(PG8_LAS unsigned char* lds, const Gemm g, const Sched& S, const Epi& E) {
;     ...
;             PG8_LDB(B1, 0, 1); PG8_STAGE(PG8_SB(0, 0), b2, voffB);
;             PG8_BAR; PG8_WAIT_L(0); PG8_MMA(0, 1, At, B1); PG8_BAR;
;             PG8_LDA(At, 0, 1); PG8_STAGE(PG8_SA(0, 0), a2, voffA);
;             PG8_BAR; PG8_WAIT_L(0); PG8_MMA(1, 0, At, B0); PG8_BAR; PG8_SCHED;
;             PG8_STAGE(PG8_SB(0, 1), b2 + hstep, voffB);
;             PG8_WAIT_V(6); PG8_BAR; PG8_MMA(1, 1, At, B1); PG8_BAR;
;             PG8_LDB(B0, 1, 0); PG8_SCHED; PG8_LDA(At, 1, 0); PG8_STAGE(PG8_SA(0, 1), a2 + hstep, voffA);
;             PG8_WAIT_L(8); PG8_BAR; PG8_WAIT_L(0); PG8_MMA(0, 0, At, B0); PG8_BAR; PG8_SCHED;
	s_add_i32 s94, 0, 0x14000
	s_add_i32 s70, s70, s58
	v_add_u32_e32 v96, s94, v221
	v_lshl_add_u64 v[194:195], s[50:51], 0, v[198:199]
	s_mov_b32 m0, s70
	ds_read_b128 v[178:181], v96
	ds_read_b128 v[182:185], v96 offset:1024
	ds_read_b128 v[186:189], v96 offset:2048
	ds_read_b128 v[190:193], v96 offset:3072
	global_load_lds_dwordx4 v[194:195], off
	v_lshl_add_u64 v[210:211], s[50:51], 0, v[202:203]
	s_add_i32 m0, s70, 0x2000
	s_nop 0
	global_load_lds_dwordx4 v[210:211], off
	s_barrier
	s_waitcnt lgkmcnt(0)
	s_waitcnt lgkmcnt(0)
	v_mfma_f32_16x16x32_bf16 v[118:121], v[178:181], v[146:149], v[118:121]
	v_mfma_f32_16x16x32_bf16 v[114:117], v[186:189], v[146:149], v[114:117]
	v_mfma_f32_16x16x32_bf16 v[102:105], v[178:181], v[154:157], v[102:105]
	v_mfma_f32_16x16x32_bf16 v[98:101], v[186:189], v[154:157], v[98:101]
	v_mfma_f32_16x16x32_bf16 v[84:87], v[178:181], v[162:165], v[84:87]
	v_mfma_f32_16x16x32_bf16 v[80:83], v[186:189], v[162:165], v[80:83]
	v_mfma_f32_16x16x32_bf16 v[68:71], v[178:181], v[170:173], v[68:71]
	v_mfma_f32_16x16x32_bf16 v[64:67], v[186:189], v[170:173], v[64:67]
	v_mfma_f32_16x16x32_bf16 v[118:121], v[182:185], v[150:153], v[118:121]
	v_mfma_f32_16x16x32_bf16 v[114:117], v[190:193], v[150:153], v[114:117]
	v_mfma_f32_16x16x32_bf16 v[102:105], v[182:185], v[158:161], v[102:105]
	v_mfma_f32_16x16x32_bf16 v[98:101], v[190:193], v[158:161], v[98:101]
	v_mfma_f32_16x16x32_bf16 v[84:87], v[182:185], v[166:169], v[84:87]
	v_mfma_f32_16x16x32_bf16 v[80:83], v[190:193], v[166:169], v[80:83]
	v_mfma_f32_16x16x32_bf16 v[68:71], v[182:185], v[174:177], v[68:71]
	v_mfma_f32_16x16x32_bf16 v[64:67], v[190:193], v[174:177], v[64:67]
	s_mov_b32 m0, s59
	v_lshl_add_u64 v[212:213], s[52:53], 0, v[196:197]
	s_barrier
	ds_read_b128 v[146:149], v223 offset:16384
	ds_read_b128 v[150:153], v223 offset:17408
	ds_read_b128 v[154:157], v223 offset:18432
	ds_read_b128 v[158:161], v223 offset:19456
	ds_read_b128 v[162:165], v223 offset:20480
	ds_read_b128 v[166:169], v223 offset:21504
	ds_read_b128 v[170:173], v223 offset:22528
	ds_read_b128 v[174:177], v223 offset:23552
	global_load_lds_dwordx4 v[212:213], off
	v_lshl_add_u64 v[214:215], s[52:53], 0, v[200:201]
	s_mov_b32 m0, s60
	s_nop 0
	global_load_lds_dwordx4 v[214:215], off
	s_barrier
	s_waitcnt lgkmcnt(0)
	s_waitcnt lgkmcnt(0)
	v_mfma_f32_16x16x32_bf16 v[60:63], v[130:133], v[146:149], v[60:63]
	v_mfma_f32_16x16x32_bf16 v[56:59], v[138:141], v[146:149], v[56:59]
	v_mfma_f32_16x16x32_bf16 v[44:47], v[130:133], v[154:157], v[44:47]
	v_mfma_f32_16x16x32_bf16 v[40:43], v[138:141], v[154:157], v[40:43]
	v_mfma_f32_16x16x32_bf16 v[28:31], v[130:133], v[162:165], v[28:31]
	v_mfma_f32_16x16x32_bf16 v[24:27], v[138:141], v[162:165], v[24:27]
	v_mfma_f32_16x16x32_bf16 v[12:15], v[130:133], v[170:173], v[12:15]
	v_mfma_f32_16x16x32_bf16 v[8:11], v[138:141], v[170:173], v[8:11]
	v_mfma_f32_16x16x32_bf16 v[60:63], v[134:137], v[150:153], v[60:63]
	v_mfma_f32_16x16x32_bf16 v[56:59], v[142:145], v[150:153], v[56:59]
	v_mfma_f32_16x16x32_bf16 v[44:47], v[134:137], v[158:161], v[44:47]
	v_mfma_f32_16x16x32_bf16 v[40:43], v[142:145], v[158:161], v[40:43]
	v_mfma_f32_16x16x32_bf16 v[28:31], v[134:137], v[166:169], v[28:31]
	v_mfma_f32_16x16x32_bf16 v[24:27], v[142:145], v[166:169], v[24:27]
	v_mfma_f32_16x16x32_bf16 v[12:15], v[134:137], v[174:177], v[12:15]
	v_mfma_f32_16x16x32_bf16 v[8:11], v[142:145], v[174:177], v[8:11]
	s_barrier
	s_add_u32 s70, s50, 0x20000
	s_addc_u32 s71, s51, 0
	s_add_i32 s94, s94, s58
	v_lshl_add_u64 v[130:131], s[70:71], 0, v[198:199]
	s_mov_b32 m0, s94
	s_nop 0
	global_load_lds_dwordx4 v[130:131], off
	v_lshl_add_u64 v[130:131], s[70:71], 0, v[202:203]
	s_add_i32 m0, s94, 0x2000
	s_nop 0
	global_load_lds_dwordx4 v[130:131], off
	s_waitcnt vmcnt(6)
	s_barrier
	v_mfma_f32_16x16x32_bf16 v[52:55], v[178:181], v[146:149], v[52:55]
	v_mfma_f32_16x16x32_bf16 v[48:51], v[186:189], v[146:149], v[48:51]
	v_mfma_f32_16x16x32_bf16 v[36:39], v[178:181], v[154:157], v[36:39]
	v_mfma_f32_16x16x32_bf16 v[32:35], v[186:189], v[154:157], v[32:35]
	v_mfma_f32_16x16x32_bf16 v[20:23], v[178:181], v[162:165], v[20:23]
	v_mfma_f32_16x16x32_bf16 v[16:19], v[186:189], v[162:165], v[16:19]
	v_mfma_f32_16x16x32_bf16 v[4:7], v[178:181], v[170:173], v[4:7]
	v_mfma_f32_16x16x32_bf16 v[0:3], v[186:189], v[170:173], v[0:3]
	v_mfma_f32_16x16x32_bf16 v[52:55], v[182:185], v[150:153], v[52:55]
	v_mfma_f32_16x16x32_bf16 v[48:51], v[190:193], v[150:153], v[48:51]
	v_mfma_f32_16x16x32_bf16 v[36:39], v[182:185], v[158:161], v[36:39]
	v_mfma_f32_16x16x32_bf16 v[32:35], v[190:193], v[158:161], v[32:35]
	v_mfma_f32_16x16x32_bf16 v[20:23], v[182:185], v[166:169], v[20:23]
	v_mfma_f32_16x16x32_bf16 v[16:19], v[190:193], v[166:169], v[16:19]
	v_mfma_f32_16x16x32_bf16 v[4:7], v[182:185], v[174:177], v[4:7]
	v_mfma_f32_16x16x32_bf16 v[0:3], v[190:193], v[174:177], v[0:3]
	s_add_i32 s70, 0, 0x18000
	v_add_u32_e32 v96, s70, v221
	s_barrier
	ds_read_b128 v[130:133], v96
	ds_read_b128 v[134:137], v96 offset:1024
	ds_read_b128 v[138:141], v96 offset:2048
	ds_read_b128 v[142:145], v96 offset:3072
	s_add_u32 s52, s52, 0x20000
	s_addc_u32 s53, s53, 0
	s_mov_b32 m0, s61
	v_lshl_add_u64 v[178:179], s[52:53], 0, v[196:197]
	ds_read_b128 v[146:149], v223 offset:32768
	ds_read_b128 v[150:153], v223 offset:33792
	ds_read_b128 v[154:157], v223 offset:34816
	ds_read_b128 v[158:161], v223 offset:35840
	ds_read_b128 v[162:165], v223 offset:36864
	ds_read_b128 v[166:169], v223 offset:37888
	ds_read_b128 v[170:173], v223 offset:38912
	ds_read_b128 v[174:177], v223 offset:39936
	global_load_lds_dwordx4 v[178:179], off
	v_lshl_add_u64 v[178:179], s[52:53], 0, v[200:201]
	s_mov_b32 m0, s62
	s_nop 0
	global_load_lds_dwordx4 v[178:179], off
	s_waitcnt lgkmcnt(8)
	s_barrier
; #define PG8_STAGE(bufoff, gbase, voff) do { _Pragma("unroll") for (int _i = 0; _i < 2; ++_i) \
;         __builtin_amdgcn_global_load_lds((const unsigned*)((const char*)(gbase) + (voff)[_i]), (PG8_LAS unsigned*)(lds + (bufoff) + ldsw + _i * 8192), 16, 0, 0); } while (0)
; #define PG8_LDA(dst, b, h) do { _Pragma("unroll") for (int m = 0; m < 4; ++m) _Pragma("unroll") for (int k = 0; k < 2; ++k) dst[m][k] = *(const PG8_LAS bf16x8*)(lds + PG8_SA(b, h) + aoff + m * 2048 + k * 1024); } while (0)
; #define PG8_LDB(dst, b, h) do { _Pragma("unroll") for (int n = 0; n < 2; ++n) _Pragma("unroll") for (int k = 0; k < 2; ++k) dst[n][k] = *(const PG8_LAS bf16x8*)(lds + PG8_SB(b, h) + boff + n * 2048 + k * 1024); } while (0)
; #define PG8_MMA(ai, bj, At, Bt) do { __builtin_amdgcn_s_setprio(1); _Pragma("unroll") for (int m = 0; m < 4; ++m) _Pragma("unroll") for (int n = 0; n < 2; ++n) _Pragma("unroll") for (int k = 0; k < 2; ++k) \
;         acc[ai][bj][m][n] = __builtin_amdgcn_mfma_f32_16x16x32_bf16(Bt[n][k], At[m][k], acc[ai][bj][m][n], 0, 0, 0); __builtin_amdgcn_s_setprio(0); } while (0)
; #define PG8_WAIT_L(n) asm volatile("s_waitcnt lgkmcnt(" #n ")" ::: "memory")
; #define PG8_BAR __builtin_amdgcn_s_barrier()
; #define PG8_SCHED __builtin_amdgcn_sched_barrier(0)
; template <class Epi, class Sched>
; __device__ __forceinline__ void gemm_phase(PG8_LAS unsigned char* lds, const Gemm g, const Sched& S, const Epi& E) {
;     ...
;             PG8_WAIT_L(8); PG8_BAR; PG8_WAIT_L(0); PG8_MMA(0, 0, At, B0); PG8_BAR; PG8_SCHED;
;             PG8_LDB(B1, 1, 1); PG8_STAGE(PG8_SB(1, 0), b3, voffB);
;             PG8_BAR; PG8_WAIT_L(0); PG8_MMA(0, 1, At, B1); PG8_BAR;
;             PG8_LDA(At, 1, 1); PG8_STAGE(PG8_SA(1, 0), a3, voffA);
;             PG8_BAR; PG8_WAIT_L(0); PG8_MMA(1, 0, At, B0); PG8_BAR; PG8_SCHED;
	s_waitcnt lgkmcnt(0)
	s_waitcnt lgkmcnt(0)
	v_mfma_f32_16x16x32_bf16 v[126:129], v[130:133], v[146:149], v[126:129]
	v_mfma_f32_16x16x32_bf16 v[122:125], v[138:141], v[146:149], v[122:125]
	v_mfma_f32_16x16x32_bf16 v[110:113], v[130:133], v[154:157], v[110:113]
	v_mfma_f32_16x16x32_bf16 v[106:109], v[138:141], v[154:157], v[106:109]
	v_mfma_f32_16x16x32_bf16 v[92:95], v[130:133], v[162:165], v[92:95]
	v_mfma_f32_16x16x32_bf16 v[88:91], v[138:141], v[162:165], v[88:91]
	v_mfma_f32_16x16x32_bf16 v[76:79], v[130:133], v[170:173], v[76:79]
	v_mfma_f32_16x16x32_bf16 v[72:75], v[138:141], v[170:173], v[72:75]
	v_mfma_f32_16x16x32_bf16 v[126:129], v[134:137], v[150:153], v[126:129]
	v_mfma_f32_16x16x32_bf16 v[122:125], v[142:145], v[150:153], v[122:125]
	v_mfma_f32_16x16x32_bf16 v[110:113], v[134:137], v[158:161], v[110:113]
	v_mfma_f32_16x16x32_bf16 v[106:109], v[142:145], v[158:161], v[106:109]
	v_mfma_f32_16x16x32_bf16 v[92:95], v[134:137], v[166:169], v[92:95]
	v_mfma_f32_16x16x32_bf16 v[88:91], v[142:145], v[166:169], v[88:91]
	v_mfma_f32_16x16x32_bf16 v[76:79], v[134:137], v[174:177], v[76:79]
	v_mfma_f32_16x16x32_bf16 v[72:75], v[142:145], v[174:177], v[72:75]
	s_barrier
	s_add_i32 s52, 0, 0x1c000
	s_add_i32 s53, s70, s58
	v_add_u32_e32 v96, s52, v221
	v_lshl_add_u64 v[194:195], v[194:195], 0, s[2:3]
	s_mov_b32 m0, s53
	ds_read_b128 v[178:181], v96
	ds_read_b128 v[182:185], v96 offset:1024
	ds_read_b128 v[186:189], v96 offset:2048
	ds_read_b128 v[190:193], v96 offset:3072
	global_load_lds_dwordx4 v[194:195], off
	v_lshl_add_u64 v[194:195], v[210:211], 0, s[2:3]
	s_add_i32 m0, s53, 0x2000
	s_nop 0
	global_load_lds_dwordx4 v[194:195], off
	s_barrier
	s_waitcnt lgkmcnt(0)
	s_waitcnt lgkmcnt(0)
	v_mfma_f32_16x16x32_bf16 v[118:121], v[178:181], v[146:149], v[118:121]
	v_mfma_f32_16x16x32_bf16 v[114:117], v[186:189], v[146:149], v[114:117]
	v_mfma_f32_16x16x32_bf16 v[102:105], v[178:181], v[154:157], v[102:105]
	v_mfma_f32_16x16x32_bf16 v[98:101], v[186:189], v[154:157], v[98:101]
	v_mfma_f32_16x16x32_bf16 v[84:87], v[178:181], v[162:165], v[84:87]
	v_mfma_f32_16x16x32_bf16 v[80:83], v[186:189], v[162:165], v[80:83]
	v_mfma_f32_16x16x32_bf16 v[68:71], v[178:181], v[170:173], v[68:71]
	v_mfma_f32_16x16x32_bf16 v[64:67], v[186:189], v[170:173], v[64:67]
	v_mfma_f32_16x16x32_bf16 v[118:121], v[182:185], v[150:153], v[118:121]
	v_mfma_f32_16x16x32_bf16 v[114:117], v[190:193], v[150:153], v[114:117]
	v_mfma_f32_16x16x32_bf16 v[102:105], v[182:185], v[158:161], v[102:105]
	v_mfma_f32_16x16x32_bf16 v[98:101], v[190:193], v[158:161], v[98:101]
	v_mfma_f32_16x16x32_bf16 v[84:87], v[182:185], v[166:169], v[84:87]
	v_mfma_f32_16x16x32_bf16 v[80:83], v[190:193], v[166:169], v[80:83]
	v_mfma_f32_16x16x32_bf16 v[68:71], v[182:185], v[174:177], v[68:71]
	v_mfma_f32_16x16x32_bf16 v[64:67], v[190:193], v[174:177], v[64:67]
	s_mov_b32 m0, s63
	v_lshl_add_u64 v[194:195], v[212:213], 0, s[2:3]
	s_barrier
	ds_read_b128 v[146:149], v223 offset:49152
	ds_read_b128 v[150:153], v223 offset:50176
	ds_read_b128 v[154:157], v223 offset:51200
	ds_read_b128 v[158:161], v223 offset:52224
	ds_read_b128 v[162:165], v223 offset:53248
	ds_read_b128 v[166:169], v223 offset:54272
	ds_read_b128 v[170:173], v223 offset:55296
	ds_read_b128 v[174:177], v223 offset:56320
	global_load_lds_dwordx4 v[194:195], off
	v_lshl_add_u64 v[194:195], v[214:215], 0, s[2:3]
	s_mov_b32 m0, s64
	s_nop 0
	global_load_lds_dwordx4 v[194:195], off
	s_barrier
; #define PG8_STAGE(bufoff, gbase, voff) do { _Pragma("unroll") for (int _i = 0; _i < 2; ++_i) \
;         __builtin_amdgcn_global_load_lds((const unsigned*)((const char*)(gbase) + (voff)[_i]), (PG8_LAS unsigned*)(lds + (bufoff) + ldsw + _i * 8192), 16, 0, 0); } while (0)
; #define PG8_MMA(ai, bj, At, Bt) do { __builtin_amdgcn_s_setprio(1); _Pragma("unroll") for (int m = 0; m < 4; ++m) _Pragma("unroll") for (int n = 0; n < 2; ++n) _Pragma("unroll") for (int k = 0; k < 2; ++k) \
;         acc[ai][bj][m][n] = __builtin_amdgcn_mfma_f32_16x16x32_bf16(Bt[n][k], At[m][k], acc[ai][bj][m][n], 0, 0, 0); __builtin_amdgcn_s_setprio(0); } while (0)
; #define PG8_WAIT_V(n) asm volatile("s_waitcnt vmcnt(" #n ")" ::: "memory")
; #define PG8_WAIT_L(n) asm volatile("s_waitcnt lgkmcnt(" #n ")" ::: "memory")
; #define PG8_BAR __builtin_amdgcn_s_barrier()
; #define PG8_SCHED __builtin_amdgcn_sched_barrier(0)
; template <class Epi, class Sched>
; __device__ __forceinline__ void gemm_phase(PG8_LAS unsigned char* lds, const Gemm g, const Sched& S, const Epi& E) {
;     ...
;             PG8_BAR; PG8_WAIT_L(0); PG8_MMA(1, 0, At, B0); PG8_BAR; PG8_SCHED;
;             PG8_STAGE(PG8_SB(1, 1), b3 + hstep, voffB);
;             PG8_WAIT_V(6); PG8_BAR; PG8_MMA(1, 1, At, B1); PG8_BAR;
;         }
;   DEV void operator()(const f32x4 (&acc)[2][2][4][2], const pg8::Unit& u, int wr, int wc, int fr, int fq) const {
;     const int b = u.pn >> 2, pn = u.pn & 3, pm = u.pm - 136 * (b == 0 ? 11 : (b == 1 ? 12 : 6));
;     const bf16_t* G = (const bf16_t*)(ws + (b == 0 ? O_G1 : (b == 1 ? O_G2 : O_G3)));
;     bf16_t* M = (bf16_t*)(ws + O_M);
;     const int row0 = pm * 256 + wr * 64 + fr, col0 = pn * 256 + wc * 32 + 8 * fq;
; #pragma unroll
;     for (int ai = 0; ai < 2; ++ai) {
;       u32x4 gv[4][2], mv[4][2];
; #pragma unroll
;       for (int m = 0; m < 4; ++m)
; #pragma unroll
;         for (int bj = 0; bj < 2; ++bj) {
;           const size_t off = (size_t)(row0 + ai * 128 + m * 16) * DM + col0 + bj * 128;
;           gv[m][bj] = *(const u32x4*)(G + off);
;           mv[m][bj] = (u32x4){0u, 0u, 0u, 0u};
;           if (b > 0) mv[m][bj] = *(const u32x4*)(M + off);
	s_waitcnt lgkmcnt(0)
	s_waitcnt lgkmcnt(0)
	v_mfma_f32_16x16x32_bf16 v[60:63], v[130:133], v[146:149], v[60:63]
	v_mfma_f32_16x16x32_bf16 v[56:59], v[138:141], v[146:149], v[56:59]
	v_mfma_f32_16x16x32_bf16 v[44:47], v[130:133], v[154:157], v[44:47]
	v_mfma_f32_16x16x32_bf16 v[40:43], v[138:141], v[154:157], v[40:43]
	v_mfma_f32_16x16x32_bf16 v[28:31], v[130:133], v[162:165], v[28:31]
	v_mfma_f32_16x16x32_bf16 v[24:27], v[138:141], v[162:165], v[24:27]
	v_mfma_f32_16x16x32_bf16 v[12:15], v[130:133], v[170:173], v[12:15]
	v_mfma_f32_16x16x32_bf16 v[8:11], v[138:141], v[170:173], v[8:11]
	v_mfma_f32_16x16x32_bf16 v[60:63], v[134:137], v[150:153], v[60:63]
	v_mfma_f32_16x16x32_bf16 v[56:59], v[142:145], v[150:153], v[56:59]
	v_mfma_f32_16x16x32_bf16 v[44:47], v[134:137], v[158:161], v[44:47]
	v_mfma_f32_16x16x32_bf16 v[40:43], v[142:145], v[158:161], v[40:43]
	v_mfma_f32_16x16x32_bf16 v[28:31], v[134:137], v[166:169], v[28:31]
	v_mfma_f32_16x16x32_bf16 v[24:27], v[142:145], v[166:169], v[24:27]
	v_mfma_f32_16x16x32_bf16 v[12:15], v[134:137], v[174:177], v[12:15]
	v_mfma_f32_16x16x32_bf16 v[8:11], v[142:145], v[174:177], v[8:11]
	s_barrier
	s_add_u32 s50, s50, 0x20080
	s_addc_u32 s51, s51, 0
	s_add_i32 s52, s52, s58
	v_lshl_add_u64 v[130:131], s[50:51], 0, v[198:199]
	s_mov_b32 m0, s52
	s_nop 0
	global_load_lds_dwordx4 v[130:131], off
	v_lshl_add_u64 v[130:131], s[50:51], 0, v[202:203]
	s_add_i32 m0, s52, 0x2000
	s_nop 0
	global_load_lds_dwordx4 v[130:131], off
	s_waitcnt vmcnt(6)
	s_barrier
	v_mfma_f32_16x16x32_bf16 v[52:55], v[178:181], v[146:149], v[52:55]
	v_mfma_f32_16x16x32_bf16 v[48:51], v[186:189], v[146:149], v[48:51]
	v_mfma_f32_16x16x32_bf16 v[36:39], v[178:181], v[154:157], v[36:39]
	v_mfma_f32_16x16x32_bf16 v[32:35], v[186:189], v[154:157], v[32:35]
	v_mfma_f32_16x16x32_bf16 v[20:23], v[178:181], v[162:165], v[20:23]
	v_mfma_f32_16x16x32_bf16 v[16:19], v[186:189], v[162:165], v[16:19]
	v_mfma_f32_16x16x32_bf16 v[4:7], v[178:181], v[170:173], v[4:7]
	v_mfma_f32_16x16x32_bf16 v[0:3], v[186:189], v[170:173], v[0:3]
	v_mfma_f32_16x16x32_bf16 v[52:55], v[182:185], v[150:153], v[52:55]
	v_mfma_f32_16x16x32_bf16 v[48:51], v[190:193], v[150:153], v[48:51]
	v_mfma_f32_16x16x32_bf16 v[36:39], v[182:185], v[158:161], v[36:39]
	v_mfma_f32_16x16x32_bf16 v[32:35], v[190:193], v[158:161], v[32:35]
	v_mfma_f32_16x16x32_bf16 v[20:23], v[182:185], v[166:169], v[20:23]
	v_mfma_f32_16x16x32_bf16 v[16:19], v[190:193], v[166:169], v[16:19]
	v_mfma_f32_16x16x32_bf16 v[4:7], v[182:185], v[174:177], v[4:7]
	v_mfma_f32_16x16x32_bf16 v[0:3], v[190:193], v[174:177], v[0:3]
	s_add_i32 s69, s69, 2
	s_add_u32 s48, s48, 0x100
	s_addc_u32 s49, s49, 0
	s_add_u32 s67, s67, 0x100
	s_addc_u32 s68, s68, 0
	s_cmp_gt_u32 s69, 5
	s_barrier
	s_cbranch_scc0 .LBB0_105
	s_ashr_i32 s1, s0, 2
	s_cmp_eq_u32 s1, 1
	s_movk_i32 s31, 0xf9a0
	s_mov_b32 s39, 0xee00000
	s_cselect_b32 s31, s31, 0xfffffcd0
	s_cselect_b32 s39, s39, 0x13200000
	s_cmp_lt_u32 s0, 4
	s_cselect_b32 s31, 0xfffffa28, s31
	s_cselect_b32 s39, 0x6600000, s39
	s_add_i32 s31, s31, s46
	s_add_u32 s46, s74, s39
	s_addc_u32 s47, s75, 0
	v_lshl_add_u32 v212, s31, 8, v220
	s_lshl_b32 s0, s0, 8
	s_and_b32 s0, s0, 0x300
	v_ashrrev_i32_e32 v213, 31, v212
	v_or_b32_e32 v224, s0, v222
	v_lshlrev_b64 v[130:131], 10, v[212:213]
	v_or_b32_e32 v130, v130, v224
	v_lshl_add_u64 v[132:133], v[130:131], 1, s[46:47]
	global_load_dwordx4 v[188:191], v[132:133], off
	s_cmp_gt_i32 s1, 0
	s_cselect_b64 s[48:49], -1, 0
	s_cmp_lt_i32 s1, 1
	v_lshl_add_u64 v[130:131], v[130:131], 1, s[74:75]
	s_cbranch_scc1 .LBB0_108
	global_load_dwordx4 v[192:195], v[130:131], off
	s_branch .LBB0_109

; #define PG8_BAR __builtin_amdgcn_s_barrier()
; template <class Epi, class Sched>
; __device__ __forceinline__ void gemm_phase(PG8_LAS unsigned char* lds, const Gemm g, const Sched& S, const Epi& E) {
;     ...
;         const bool has_next = S.next(ui + 1, nxt);
;         const char* nA = has_next ? (const char*)g.A + (size_t)nxt.pm * tstep : cA; const char* nB = has_next ? (const char*)g.Bt + (size_t)nxt.pn * tstep : cB;
;         for (int t = 0; t < nt; t += 2) {
;             const bool last = (t == nt - 2);
;             const char* a1 = cA + (size_t)(t + 1) * kstep;
;             const char* a2 = last ? nA : cA + (size_t)(t + 2) * kstep; const char* b2 = last ? nB : cB + (size_t)(t + 2) * kstep;
;             const char* a3 = a2 + kstep; const char* b3 = b2 + kstep;
;             if (last && has_next) S.a_ready(nxt);
;             PG8_LDB(B0, 0, 0); PG8_SCHED; PG8_LDA(At, 0, 0); PG8_STAGE(PG8_SA(1, 1), a1 + hstep, voffA);
;             PG8_WAIT_L(8); PG8_BAR; PG8_WAIT_L(0); PG8_MMA(0, 0, At, B0); PG8_BAR; PG8_SCHED;
;             PG8_LDB(B1, 0, 1); PG8_STAGE(PG8_SB(0, 0), b2, voffB);
;             PG8_BAR; PG8_WAIT_L(0); PG8_MMA(0, 1, At, B1); PG8_BAR;
;             PG8_LDA(At, 0, 1); PG8_STAGE(PG8_SA(0, 0), a2, voffA);
;             PG8_BAR; PG8_WAIT_L(0); PG8_MMA(1, 0, At, B0); PG8_BAR; PG8_SCHED;
;             PG8_STAGE(PG8_SB(0, 1), b2 + hstep, voffB);
;             PG8_WAIT_V(6); PG8_BAR; PG8_MMA(1, 1, At, B1); PG8_BAR;
;             PG8_LDB(B0, 1, 0); PG8_SCHED; PG8_LDA(At, 1, 0); PG8_STAGE(PG8_SA(0, 1), a2 + hstep, voffA);
;             PG8_WAIT_L(8); PG8_BAR; PG8_WAIT_L(0); PG8_MMA(0, 0, At, B0); PG8_BAR; PG8_SCHED;
;             PG8_LDB(B1, 1, 1); PG8_STAGE(PG8_SB(1, 0), b3, voffB);
;             PG8_BAR; PG8_WAIT_L(0); PG8_MMA(0, 1, At, B1); PG8_BAR;
;             PG8_LDA(At, 1, 1); PG8_STAGE(PG8_SA(1, 0), a3, voffA);
;             PG8_BAR; PG8_WAIT_L(0); PG8_MMA(1, 0, At, B0); PG8_BAR; PG8_SCHED;
;             PG8_STAGE(PG8_SB(1, 1), b3 + hstep, voffB);
;             PG8_WAIT_V(6); PG8_BAR; PG8_MMA(1, 1, At, B1); PG8_BAR;
;         }
;         if constexpr (!Epi::AFTER_DRAIN) { E(acc, cur, wr, wc, fr, fq); S.done(cur); }
;         if (!has_next) break;
; #pragma unroll
;         for (int a = 0; a < 2; ++a)
; #pragma unroll
;             for (int b = 0; b < 2; ++b)
; #pragma unroll
;                 for (int m = 0; m < 4; ++m)
; #pragma unroll
.LBB0_151:
	v_mov_b64_e32 v[0:1], s[54:55]
	s_ashr_i32 s31, s30, 31
	v_cmp_lt_i64_e32 vcc, s[38:39], v[0:1]
	s_lshl_b64 s[38:39], s[30:31], 19
	s_add_u32 s38, s74, s38
	s_addc_u32 s39, s75, s39
	s_and_b64 s[40:41], vcc, exec
	s_cselect_b32 s31, s39, s47
	s_cselect_b32 s66, s38, s46
	s_ashr_i32 s1, s0, 31
	s_lshl_b64 s[40:41], s[0:1], 19
	v_readlane_b32 s42, v251, 5
	v_readlane_b32 s43, v251, 6
	s_add_u32 s40, s42, s40
	s_addc_u32 s41, s43, s41
	s_and_b64 s[50:51], vcc, exec
	s_cselect_b32 s1, s41, s49
	s_cselect_b32 s67, s40, s48
	s_add_u32 s46, s46, 0x40080
	s_addc_u32 s47, s47, 0
	s_add_u32 s68, s48, 0x100
	v_mov_b32_e32 v0, 0
	s_addc_u32 s69, s49, 0
	s_mov_b32 s70, -2
	v_mov_b32_e32 v1, v0
	v_mov_b32_e32 v2, v0
	v_mov_b32_e32 v3, v0
	v_mov_b32_e32 v4, v0
	v_mov_b32_e32 v5, v0
	v_mov_b32_e32 v6, v0
	v_mov_b32_e32 v7, v0
	v_mov_b32_e32 v16, v0
	v_mov_b32_e32 v17, v0
	v_mov_b32_e32 v18, v0
	v_mov_b32_e32 v19, v0
	v_mov_b32_e32 v20, v0
	v_mov_b32_e32 v21, v0
	v_mov_b32_e32 v22, v0
	v_mov_b32_e32 v23, v0
	v_mov_b32_e32 v32, v0
	v_mov_b32_e32 v33, v0
	v_mov_b32_e32 v34, v0
	v_mov_b32_e32 v35, v0
	v_mov_b32_e32 v36, v0
	v_mov_b32_e32 v37, v0
	v_mov_b32_e32 v38, v0
	v_mov_b32_e32 v39, v0
	v_mov_b32_e32 v48, v0
	v_mov_b32_e32 v49, v0
	v_mov_b32_e32 v50, v0
	v_mov_b32_e32 v51, v0
	v_mov_b32_e32 v52, v0
	v_mov_b32_e32 v53, v0
	v_mov_b32_e32 v54, v0
	v_mov_b32_e32 v55, v0
	v_mov_b32_e32 v8, v0
	v_mov_b32_e32 v9, v0
	v_mov_b32_e32 v10, v0
	v_mov_b32_e32 v11, v0
	v_mov_b32_e32 v12, v0
	v_mov_b32_e32 v13, v0
	v_mov_b32_e32 v14, v0
	v_mov_b32_e32 v15, v0
	v_mov_b32_e32 v24, v0
	v_mov_b32_e32 v25, v0
	v_mov_b32_e32 v26, v0
	v_mov_b32_e32 v27, v0
	v_mov_b32_e32 v28, v0
	v_mov_b32_e32 v29, v0
	v_mov_b32_e32 v30, v0
	v_mov_b32_e32 v31, v0
	v_mov_b32_e32 v40, v0
	v_mov_b32_e32 v41, v0
	v_mov_b32_e32 v42, v0
	v_mov_b32_e32 v43, v0
	v_mov_b32_e32 v44, v0
	v_mov_b32_e32 v45, v0
	v_mov_b32_e32 v46, v0
	v_mov_b32_e32 v47, v0
	v_mov_b32_e32 v56, v0
	v_mov_b32_e32 v57, v0
	v_mov_b32_e32 v58, v0
	v_mov_b32_e32 v59, v0
	v_mov_b32_e32 v60, v0
	v_mov_b32_e32 v61, v0
	v_mov_b32_e32 v62, v0
	v_mov_b32_e32 v63, v0
	v_mov_b32_e32 v64, v0
	v_mov_b32_e32 v65, v0
	v_mov_b32_e32 v66, v0
	v_mov_b32_e32 v67, v0
	v_mov_b32_e32 v68, v0
	v_mov_b32_e32 v69, v0
	v_mov_b32_e32 v70, v0
	v_mov_b32_e32 v71, v0
	v_mov_b32_e32 v80, v0
	v_mov_b32_e32 v81, v0
	v_mov_b32_e32 v82, v0
	v_mov_b32_e32 v83, v0
	v_mov_b32_e32 v84, v0
	v_mov_b32_e32 v85, v0
	v_mov_b32_e32 v86, v0
	v_mov_b32_e32 v87, v0
	v_mov_b32_e32 v98, v0
	v_mov_b32_e32 v99, v0
	v_mov_b32_e32 v100, v0
	v_mov_b32_e32 v101, v0
	v_mov_b32_e32 v102, v0
	v_mov_b32_e32 v103, v0
	v_mov_b32_e32 v104, v0
	v_mov_b32_e32 v105, v0
	v_mov_b32_e32 v114, v0
	v_mov_b32_e32 v115, v0
	v_mov_b32_e32 v116, v0
	v_mov_b32_e32 v117, v0
	v_mov_b32_e32 v118, v0
	v_mov_b32_e32 v119, v0
	v_mov_b32_e32 v120, v0
	v_mov_b32_e32 v121, v0
	v_mov_b32_e32 v72, v0
	v_mov_b32_e32 v73, v0
	v_mov_b32_e32 v74, v0
	v_mov_b32_e32 v75, v0
	v_mov_b32_e32 v76, v0
	v_mov_b32_e32 v77, v0
	v_mov_b32_e32 v78, v0
	v_mov_b32_e32 v79, v0
	v_mov_b32_e32 v88, v0
	v_mov_b32_e32 v89, v0
	v_mov_b32_e32 v90, v0
	v_mov_b32_e32 v91, v0
	v_mov_b32_e32 v92, v0
	v_mov_b32_e32 v93, v0
	v_mov_b32_e32 v94, v0
	v_mov_b32_e32 v95, v0
	v_mov_b32_e32 v106, v0
	v_mov_b32_e32 v107, v0
	v_mov_b32_e32 v108, v0
	v_mov_b32_e32 v109, v0
	v_mov_b32_e32 v110, v0
	v_mov_b32_e32 v111, v0
	v_mov_b32_e32 v112, v0
	v_mov_b32_e32 v113, v0
	v_mov_b32_e32 v122, v0
	v_mov_b32_e32 v123, v0
	v_mov_b32_e32 v124, v0
	v_mov_b32_e32 v125, v0
	v_mov_b32_e32 v126, v0
	v_mov_b32_e32 v127, v0
	v_mov_b32_e32 v128, v0
	v_mov_b32_e32 v129, v0
	v_readfirstlane_b32 s100, v226
	s_nop 3
	s_lshr_b32 s100, s100, 8
	s_cmp_eq_u32 s100, 0
	s_cbranch_scc1 .Lgp_7151
	s_setprio 1
.Lgp_7151:
.LBB0_152:
	s_add_u32 s48, s46, 0xfffc0080
	s_addc_u32 s49, s47, -1
	s_add_i32 s71, 0, 0x10000
	v_add_u32_e32 v96, s71, v147
	ds_read_b128 v[142:145], v96
	ds_read_b128 v[150:153], v96 offset:1024
	ds_read_b128 v[154:157], v96 offset:2048
	ds_read_b128 v[158:161], v96 offset:3072
	s_cmp_eq_u32 s70, 12
	s_cselect_b32 s51, s31, s49
	s_cselect_b32 s50, s66, s48
	s_cselect_b32 s49, s1, s69
	s_cselect_b32 s48, s67, s68
	v_lshl_add_u64 v[194:195], s[46:47], 0, v[138:139]
	s_add_i32 m0, s45, 0xc000
	ds_read_b128 v[162:165], v149
	ds_read_b128 v[166:169], v149 offset:1024
	ds_read_b128 v[170:173], v149 offset:2048
	ds_read_b128 v[174:177], v149 offset:3072
	ds_read_b128 v[178:181], v149 offset:4096
	ds_read_b128 v[182:185], v149 offset:5120
	ds_read_b128 v[186:189], v149 offset:6144
	ds_read_b128 v[190:193], v149 offset:7168
	global_load_lds_dwordx4 v[194:195], off
	v_lshl_add_u64 v[194:195], s[46:47], 0, v[140:141]
	s_add_i32 m0, s45, 0xe000
	s_nop 0
	global_load_lds_dwordx4 v[194:195], off
	s_waitcnt lgkmcnt(8)
	s_barrier
	s_waitcnt lgkmcnt(0)
	s_waitcnt lgkmcnt(0)
	v_mfma_f32_16x16x32_bf16 v[126:129], v[142:145], v[162:165], v[126:129]
	v_mfma_f32_16x16x32_bf16 v[122:125], v[154:157], v[162:165], v[122:125]
	v_mfma_f32_16x16x32_bf16 v[110:113], v[142:145], v[170:173], v[110:113]
	v_mfma_f32_16x16x32_bf16 v[106:109], v[154:157], v[170:173], v[106:109]
	v_mfma_f32_16x16x32_bf16 v[92:95], v[142:145], v[178:181], v[92:95]
	v_mfma_f32_16x16x32_bf16 v[88:91], v[154:157], v[178:181], v[88:91]
	v_mfma_f32_16x16x32_bf16 v[76:79], v[142:145], v[186:189], v[76:79]
	v_mfma_f32_16x16x32_bf16 v[72:75], v[154:157], v[186:189], v[72:75]
	v_mfma_f32_16x16x32_bf16 v[126:129], v[150:153], v[166:169], v[126:129]
	v_mfma_f32_16x16x32_bf16 v[122:125], v[158:161], v[166:169], v[122:125]
	v_mfma_f32_16x16x32_bf16 v[110:113], v[150:153], v[174:177], v[110:113]
	v_mfma_f32_16x16x32_bf16 v[106:109], v[158:161], v[174:177], v[106:109]
	v_mfma_f32_16x16x32_bf16 v[92:95], v[150:153], v[182:185], v[92:95]
	v_mfma_f32_16x16x32_bf16 v[88:91], v[158:161], v[182:185], v[88:91]
	v_mfma_f32_16x16x32_bf16 v[76:79], v[150:153], v[190:193], v[76:79]
	v_mfma_f32_16x16x32_bf16 v[72:75], v[158:161], v[190:193], v[72:75]
	s_barrier
; #define PG8_STAGE(bufoff, gbase, voff) do { _Pragma("unroll") for (int _i = 0; _i < 2; ++_i) \
;         __builtin_amdgcn_global_load_lds((const unsigned*)((const char*)(gbase) + (voff)[_i]), (PG8_LAS unsigned*)(lds + (bufoff) + ldsw + _i * 8192), 16, 0, 0); } while (0)
; #define PG8_LDA(dst, b, h) do { _Pragma("unroll") for (int m = 0; m < 4; ++m) _Pragma("unroll") for (int k = 0; k < 2; ++k) dst[m][k] = *(const PG8_LAS bf16x8*)(lds + PG8_SA(b, h) + aoff + m * 2048 + k * 1024); } while (0)
; #define PG8_LDB(dst, b, h) do { _Pragma("unroll") for (int n = 0; n < 2; ++n) _Pragma("unroll") for (int k = 0; k < 2; ++k) dst[n][k] = *(const PG8_LAS bf16x8*)(lds + PG8_SB(b, h) + boff + n * 2048 + k * 1024); } while (0)
; #define PG8_MMA(ai, bj, At, Bt) do { __builtin_amdgcn_s_setprio(1); _Pragma("unroll") for (int m = 0; m < 4; ++m) _Pragma("unroll") for (int n = 0; n < 2; ++n) _Pragma("unroll") for (int k = 0; k < 2; ++k) \
;         acc[ai][bj][m][n] = __builtin_amdgcn_mfma_f32_16x16x32_bf16(Bt[n][k], At[m][k], acc[ai][bj][m][n], 0, 0, 0); __builtin_amdgcn_s_setprio(0); } while (0)
; #define PG8_WAIT_V(n) asm volatile("s_waitcnt vmcnt(" #n ")" ::: "memory")
; #define PG8_WAIT_L(n) asm volatile("s_waitcnt lgkmcnt(" #n ")" ::: "memory")
; #define PG8_BAR __builtin_amdgcn_s_barrier()
; #define PG8_SCHED __builtin_amdgcn_sched_barrier(0)
; template <class Epi, class Sched>
; __device__ __forceinline__ void gemm_phase(PG8_LAS unsigned char* lds, const Gemm g, const Sched& S, const Epi& E) {
;     ...
;             PG8_LDB(B1, 0, 1); PG8_STAGE(PG8_SB(0, 0), b2, voffB);
;             PG8_BAR; PG8_WAIT_L(0); PG8_MMA(0, 1, At, B1); PG8_BAR;
;             PG8_LDA(At, 0, 1); PG8_STAGE(PG8_SA(0, 0), a2, voffA);
;             PG8_BAR; PG8_WAIT_L(0); PG8_MMA(1, 0, At, B0); PG8_BAR; PG8_SCHED;
;             PG8_STAGE(PG8_SB(0, 1), b2 + hstep, voffB);
;             PG8_WAIT_V(6); PG8_BAR; PG8_MMA(1, 1, At, B1); PG8_BAR;
;             PG8_LDB(B0, 1, 0); PG8_SCHED; PG8_LDA(At, 1, 0); PG8_STAGE(PG8_SA(0, 1), a2 + hstep, voffA);
;             PG8_WAIT_L(8); PG8_BAR; PG8_WAIT_L(0); PG8_MMA(0, 0, At, B0); PG8_BAR; PG8_SCHED;
	s_add_i32 s94, 0, 0x14000
	s_add_i32 s71, s71, s56
	v_add_u32_e32 v96, s94, v147
	v_lshl_add_u64 v[212:213], s[48:49], 0, v[134:135]
	s_mov_b32 m0, s71
	ds_read_b128 v[194:197], v96
	ds_read_b128 v[198:201], v96 offset:1024
	ds_read_b128 v[202:205], v96 offset:2048
	ds_read_b128 v[208:211], v96 offset:3072
	global_load_lds_dwordx4 v[212:213], off
	v_lshl_add_u64 v[214:215], s[48:49], 0, v[130:131]
	s_add_i32 m0, s71, 0x2000
	s_nop 0
	global_load_lds_dwordx4 v[214:215], off
	s_barrier
	s_waitcnt lgkmcnt(0)
	s_waitcnt lgkmcnt(0)
	v_mfma_f32_16x16x32_bf16 v[118:121], v[194:197], v[162:165], v[118:121]
	v_mfma_f32_16x16x32_bf16 v[114:117], v[202:205], v[162:165], v[114:117]
	v_mfma_f32_16x16x32_bf16 v[102:105], v[194:197], v[170:173], v[102:105]
	v_mfma_f32_16x16x32_bf16 v[98:101], v[202:205], v[170:173], v[98:101]
	v_mfma_f32_16x16x32_bf16 v[84:87], v[194:197], v[178:181], v[84:87]
	v_mfma_f32_16x16x32_bf16 v[80:83], v[202:205], v[178:181], v[80:83]
	v_mfma_f32_16x16x32_bf16 v[68:71], v[194:197], v[186:189], v[68:71]
	v_mfma_f32_16x16x32_bf16 v[64:67], v[202:205], v[186:189], v[64:67]
	v_mfma_f32_16x16x32_bf16 v[118:121], v[198:201], v[166:169], v[118:121]
	v_mfma_f32_16x16x32_bf16 v[114:117], v[208:211], v[166:169], v[114:117]
	v_mfma_f32_16x16x32_bf16 v[102:105], v[198:201], v[174:177], v[102:105]
	v_mfma_f32_16x16x32_bf16 v[98:101], v[208:211], v[174:177], v[98:101]
	v_mfma_f32_16x16x32_bf16 v[84:87], v[198:201], v[182:185], v[84:87]
	v_mfma_f32_16x16x32_bf16 v[80:83], v[208:211], v[182:185], v[80:83]
	v_mfma_f32_16x16x32_bf16 v[68:71], v[198:201], v[190:193], v[68:71]
	v_mfma_f32_16x16x32_bf16 v[64:67], v[208:211], v[190:193], v[64:67]
	s_mov_b32 m0, s45
	v_lshl_add_u64 v[216:217], s[50:51], 0, v[136:137]
	s_barrier
	ds_read_b128 v[162:165], v149 offset:16384
	ds_read_b128 v[166:169], v149 offset:17408
	ds_read_b128 v[170:173], v149 offset:18432
	ds_read_b128 v[174:177], v149 offset:19456
	ds_read_b128 v[178:181], v149 offset:20480
	ds_read_b128 v[182:185], v149 offset:21504
	ds_read_b128 v[186:189], v149 offset:22528
	ds_read_b128 v[190:193], v149 offset:23552
	global_load_lds_dwordx4 v[216:217], off
	v_lshl_add_u64 v[218:219], s[50:51], 0, v[132:133]
	s_mov_b32 m0, s59
	s_nop 0
	global_load_lds_dwordx4 v[218:219], off
	s_barrier
	s_waitcnt lgkmcnt(0)
	s_waitcnt lgkmcnt(0)
	v_mfma_f32_16x16x32_bf16 v[60:63], v[142:145], v[162:165], v[60:63]
	v_mfma_f32_16x16x32_bf16 v[56:59], v[154:157], v[162:165], v[56:59]
	v_mfma_f32_16x16x32_bf16 v[44:47], v[142:145], v[170:173], v[44:47]
	v_mfma_f32_16x16x32_bf16 v[40:43], v[154:157], v[170:173], v[40:43]
	v_mfma_f32_16x16x32_bf16 v[28:31], v[142:145], v[178:181], v[28:31]
	v_mfma_f32_16x16x32_bf16 v[24:27], v[154:157], v[178:181], v[24:27]
	v_mfma_f32_16x16x32_bf16 v[12:15], v[142:145], v[186:189], v[12:15]
	v_mfma_f32_16x16x32_bf16 v[8:11], v[154:157], v[186:189], v[8:11]
	v_mfma_f32_16x16x32_bf16 v[60:63], v[150:153], v[166:169], v[60:63]
	v_mfma_f32_16x16x32_bf16 v[56:59], v[158:161], v[166:169], v[56:59]
	v_mfma_f32_16x16x32_bf16 v[44:47], v[150:153], v[174:177], v[44:47]
	v_mfma_f32_16x16x32_bf16 v[40:43], v[158:161], v[174:177], v[40:43]
	v_mfma_f32_16x16x32_bf16 v[28:31], v[150:153], v[182:185], v[28:31]
	v_mfma_f32_16x16x32_bf16 v[24:27], v[158:161], v[182:185], v[24:27]
	v_mfma_f32_16x16x32_bf16 v[12:15], v[150:153], v[190:193], v[12:15]
	v_mfma_f32_16x16x32_bf16 v[8:11], v[158:161], v[190:193], v[8:11]
	s_barrier
	s_add_u32 vcc_lo, s48, 0x40000
	s_addc_u32 vcc_hi, s49, 0
	s_add_i32 s71, s94, s56
	v_lshl_add_u64 v[142:143], vcc, 0, v[134:135]
	s_mov_b32 m0, s71
	s_nop 0
	global_load_lds_dwordx4 v[142:143], off
	v_lshl_add_u64 v[142:143], vcc, 0, v[130:131]
	s_add_i32 m0, s71, 0x2000
	s_nop 0
	global_load_lds_dwordx4 v[142:143], off
	s_waitcnt vmcnt(6)
	s_barrier
	v_mfma_f32_16x16x32_bf16 v[52:55], v[194:197], v[162:165], v[52:55]
	v_mfma_f32_16x16x32_bf16 v[48:51], v[202:205], v[162:165], v[48:51]
	v_mfma_f32_16x16x32_bf16 v[36:39], v[194:197], v[170:173], v[36:39]
	v_mfma_f32_16x16x32_bf16 v[32:35], v[202:205], v[170:173], v[32:35]
	v_mfma_f32_16x16x32_bf16 v[20:23], v[194:197], v[178:181], v[20:23]
	v_mfma_f32_16x16x32_bf16 v[16:19], v[202:205], v[178:181], v[16:19]
	v_mfma_f32_16x16x32_bf16 v[4:7], v[194:197], v[186:189], v[4:7]
	v_mfma_f32_16x16x32_bf16 v[0:3], v[202:205], v[186:189], v[0:3]
	v_mfma_f32_16x16x32_bf16 v[52:55], v[198:201], v[166:169], v[52:55]
	v_mfma_f32_16x16x32_bf16 v[48:51], v[208:211], v[166:169], v[48:51]
	v_mfma_f32_16x16x32_bf16 v[36:39], v[198:201], v[174:177], v[36:39]
	v_mfma_f32_16x16x32_bf16 v[32:35], v[208:211], v[174:177], v[32:35]
	v_mfma_f32_16x16x32_bf16 v[20:23], v[198:201], v[182:185], v[20:23]
	v_mfma_f32_16x16x32_bf16 v[16:19], v[208:211], v[182:185], v[16:19]
	v_mfma_f32_16x16x32_bf16 v[4:7], v[198:201], v[190:193], v[4:7]
	v_mfma_f32_16x16x32_bf16 v[0:3], v[208:211], v[190:193], v[0:3]
	s_add_i32 s71, 0, 0x18000
	v_add_u32_e32 v96, s71, v147
	s_barrier
	ds_read_b128 v[142:145], v96
	ds_read_b128 v[150:153], v96 offset:1024
	ds_read_b128 v[154:157], v96 offset:2048
	ds_read_b128 v[158:161], v96 offset:3072
	s_add_u32 s50, s50, 0x40000
	s_addc_u32 s51, s51, 0
	s_mov_b32 m0, s60
	v_lshl_add_u64 v[194:195], s[50:51], 0, v[136:137]
	ds_read_b128 v[162:165], v149 offset:32768
	ds_read_b128 v[166:169], v149 offset:33792
	ds_read_b128 v[170:173], v149 offset:34816
	ds_read_b128 v[174:177], v149 offset:35840
	ds_read_b128 v[178:181], v149 offset:36864
	ds_read_b128 v[182:185], v149 offset:37888
	ds_read_b128 v[186:189], v149 offset:38912
	ds_read_b128 v[190:193], v149 offset:39936
	global_load_lds_dwordx4 v[194:195], off
	v_lshl_add_u64 v[194:195], s[50:51], 0, v[132:133]
	s_mov_b32 m0, s61
	s_nop 0
	global_load_lds_dwordx4 v[194:195], off
	s_waitcnt lgkmcnt(8)
	s_barrier
; #define PG8_STAGE(bufoff, gbase, voff) do { _Pragma("unroll") for (int _i = 0; _i < 2; ++_i) \
;         __builtin_amdgcn_global_load_lds((const unsigned*)((const char*)(gbase) + (voff)[_i]), (PG8_LAS unsigned*)(lds + (bufoff) + ldsw + _i * 8192), 16, 0, 0); } while (0)
; #define PG8_LDA(dst, b, h) do { _Pragma("unroll") for (int m = 0; m < 4; ++m) _Pragma("unroll") for (int k = 0; k < 2; ++k) dst[m][k] = *(const PG8_LAS bf16x8*)(lds + PG8_SA(b, h) + aoff + m * 2048 + k * 1024); } while (0)
; #define PG8_LDB(dst, b, h) do { _Pragma("unroll") for (int n = 0; n < 2; ++n) _Pragma("unroll") for (int k = 0; k < 2; ++k) dst[n][k] = *(const PG8_LAS bf16x8*)(lds + PG8_SB(b, h) + boff + n * 2048 + k * 1024); } while (0)
; #define PG8_MMA(ai, bj, At, Bt) do { __builtin_amdgcn_s_setprio(1); _Pragma("unroll") for (int m = 0; m < 4; ++m) _Pragma("unroll") for (int n = 0; n < 2; ++n) _Pragma("unroll") for (int k = 0; k < 2; ++k) \
;         acc[ai][bj][m][n] = __builtin_amdgcn_mfma_f32_16x16x32_bf16(Bt[n][k], At[m][k], acc[ai][bj][m][n], 0, 0, 0); __builtin_amdgcn_s_setprio(0); } while (0)
; #define PG8_WAIT_V(n) asm volatile("s_waitcnt vmcnt(" #n ")" ::: "memory")
; #define PG8_WAIT_L(n) asm volatile("s_waitcnt lgkmcnt(" #n ")" ::: "memory")
; #define PG8_BAR __builtin_amdgcn_s_barrier()
; #define PG8_SCHED __builtin_amdgcn_sched_barrier(0)
; template <class Epi, class Sched>
; __device__ __forceinline__ void gemm_phase(PG8_LAS unsigned char* lds, const Gemm g, const Sched& S, const Epi& E) {
;     ...
;             PG8_WAIT_L(8); PG8_BAR; PG8_WAIT_L(0); PG8_MMA(0, 0, At, B0); PG8_BAR; PG8_SCHED;
;             PG8_LDB(B1, 1, 1); PG8_STAGE(PG8_SB(1, 0), b3, voffB);
;             PG8_BAR; PG8_WAIT_L(0); PG8_MMA(0, 1, At, B1); PG8_BAR;
;             PG8_LDA(At, 1, 1); PG8_STAGE(PG8_SA(1, 0), a3, voffA);
;             PG8_BAR; PG8_WAIT_L(0); PG8_MMA(1, 0, At, B0); PG8_BAR; PG8_SCHED;
;             PG8_STAGE(PG8_SB(1, 1), b3 + hstep, voffB);
;             PG8_WAIT_V(6); PG8_BAR; PG8_MMA(1, 1, At, B1); PG8_BAR;
;         }
	s_waitcnt lgkmcnt(0)
	s_waitcnt lgkmcnt(0)
	v_mfma_f32_16x16x32_bf16 v[126:129], v[142:145], v[162:165], v[126:129]
	v_mfma_f32_16x16x32_bf16 v[122:125], v[154:157], v[162:165], v[122:125]
	v_mfma_f32_16x16x32_bf16 v[110:113], v[142:145], v[170:173], v[110:113]
	v_mfma_f32_16x16x32_bf16 v[106:109], v[154:157], v[170:173], v[106:109]
	v_mfma_f32_16x16x32_bf16 v[92:95], v[142:145], v[178:181], v[92:95]
	v_mfma_f32_16x16x32_bf16 v[88:91], v[154:157], v[178:181], v[88:91]
	v_mfma_f32_16x16x32_bf16 v[76:79], v[142:145], v[186:189], v[76:79]
	v_mfma_f32_16x16x32_bf16 v[72:75], v[154:157], v[186:189], v[72:75]
	v_mfma_f32_16x16x32_bf16 v[126:129], v[150:153], v[166:169], v[126:129]
	v_mfma_f32_16x16x32_bf16 v[122:125], v[158:161], v[166:169], v[122:125]
	v_mfma_f32_16x16x32_bf16 v[110:113], v[150:153], v[174:177], v[110:113]
	v_mfma_f32_16x16x32_bf16 v[106:109], v[158:161], v[174:177], v[106:109]
	v_mfma_f32_16x16x32_bf16 v[92:95], v[150:153], v[182:185], v[92:95]
	v_mfma_f32_16x16x32_bf16 v[88:91], v[158:161], v[182:185], v[88:91]
	v_mfma_f32_16x16x32_bf16 v[76:79], v[150:153], v[190:193], v[76:79]
	v_mfma_f32_16x16x32_bf16 v[72:75], v[158:161], v[190:193], v[72:75]
	s_barrier
	s_add_i32 s50, 0, 0x1c000
	s_add_i32 s51, s71, s56
	v_add_u32_e32 v96, s50, v147
	v_lshl_add_u64 v[212:213], v[212:213], 0, s[2:3]
	s_mov_b32 m0, s51
	ds_read_b128 v[194:197], v96
	ds_read_b128 v[198:201], v96 offset:1024
	ds_read_b128 v[202:205], v96 offset:2048
	ds_read_b128 v[208:211], v96 offset:3072
	global_load_lds_dwordx4 v[212:213], off
	v_lshl_add_u64 v[212:213], v[214:215], 0, s[2:3]
	s_add_i32 m0, s51, 0x2000
	s_nop 0
	global_load_lds_dwordx4 v[212:213], off
	s_barrier
	s_waitcnt lgkmcnt(0)
	s_waitcnt lgkmcnt(0)
	v_mfma_f32_16x16x32_bf16 v[118:121], v[194:197], v[162:165], v[118:121]
	v_mfma_f32_16x16x32_bf16 v[114:117], v[202:205], v[162:165], v[114:117]
	v_mfma_f32_16x16x32_bf16 v[102:105], v[194:197], v[170:173], v[102:105]
	v_mfma_f32_16x16x32_bf16 v[98:101], v[202:205], v[170:173], v[98:101]
	v_mfma_f32_16x16x32_bf16 v[84:87], v[194:197], v[178:181], v[84:87]
	v_mfma_f32_16x16x32_bf16 v[80:83], v[202:205], v[178:181], v[80:83]
	v_mfma_f32_16x16x32_bf16 v[68:71], v[194:197], v[186:189], v[68:71]
	v_mfma_f32_16x16x32_bf16 v[64:67], v[202:205], v[186:189], v[64:67]
	v_mfma_f32_16x16x32_bf16 v[118:121], v[198:201], v[166:169], v[118:121]
	v_mfma_f32_16x16x32_bf16 v[114:117], v[208:211], v[166:169], v[114:117]
	v_mfma_f32_16x16x32_bf16 v[102:105], v[198:201], v[174:177], v[102:105]
	v_mfma_f32_16x16x32_bf16 v[98:101], v[208:211], v[174:177], v[98:101]
	v_mfma_f32_16x16x32_bf16 v[84:87], v[198:201], v[182:185], v[84:87]
	v_mfma_f32_16x16x32_bf16 v[80:83], v[208:211], v[182:185], v[80:83]
	v_mfma_f32_16x16x32_bf16 v[68:71], v[198:201], v[190:193], v[68:71]
	v_mfma_f32_16x16x32_bf16 v[64:67], v[208:211], v[190:193], v[64:67]
	s_mov_b32 m0, s62
	v_lshl_add_u64 v[212:213], v[216:217], 0, s[2:3]
	s_barrier
	ds_read_b128 v[162:165], v149 offset:49152
	ds_read_b128 v[166:169], v149 offset:50176
	ds_read_b128 v[170:173], v149 offset:51200
	ds_read_b128 v[174:177], v149 offset:52224
	ds_read_b128 v[178:181], v149 offset:53248
	ds_read_b128 v[182:185], v149 offset:54272
	ds_read_b128 v[186:189], v149 offset:55296
	ds_read_b128 v[190:193], v149 offset:56320
	global_load_lds_dwordx4 v[212:213], off
	v_lshl_add_u64 v[212:213], v[218:219], 0, s[2:3]
	s_mov_b32 m0, s63
	s_nop 0
	global_load_lds_dwordx4 v[212:213], off
	s_barrier
	s_waitcnt lgkmcnt(0)
	s_waitcnt lgkmcnt(0)
	v_mfma_f32_16x16x32_bf16 v[60:63], v[142:145], v[162:165], v[60:63]
	v_mfma_f32_16x16x32_bf16 v[56:59], v[154:157], v[162:165], v[56:59]
	v_mfma_f32_16x16x32_bf16 v[44:47], v[142:145], v[170:173], v[44:47]
	v_mfma_f32_16x16x32_bf16 v[40:43], v[154:157], v[170:173], v[40:43]
	v_mfma_f32_16x16x32_bf16 v[28:31], v[142:145], v[178:181], v[28:31]
	v_mfma_f32_16x16x32_bf16 v[24:27], v[154:157], v[178:181], v[24:27]
	v_mfma_f32_16x16x32_bf16 v[12:15], v[142:145], v[186:189], v[12:15]
	v_mfma_f32_16x16x32_bf16 v[8:11], v[154:157], v[186:189], v[8:11]
	v_mfma_f32_16x16x32_bf16 v[60:63], v[150:153], v[166:169], v[60:63]
	v_mfma_f32_16x16x32_bf16 v[56:59], v[158:161], v[166:169], v[56:59]
	v_mfma_f32_16x16x32_bf16 v[44:47], v[150:153], v[174:177], v[44:47]
	v_mfma_f32_16x16x32_bf16 v[40:43], v[158:161], v[174:177], v[40:43]
	v_mfma_f32_16x16x32_bf16 v[28:31], v[150:153], v[182:185], v[28:31]
	v_mfma_f32_16x16x32_bf16 v[24:27], v[158:161], v[182:185], v[24:27]
	v_mfma_f32_16x16x32_bf16 v[12:15], v[150:153], v[190:193], v[12:15]
	v_mfma_f32_16x16x32_bf16 v[8:11], v[158:161], v[190:193], v[8:11]
	s_barrier
	s_add_u32 s48, s48, 0x40080
	s_addc_u32 s49, s49, 0
	s_add_i32 s50, s50, s56
	v_lshl_add_u64 v[142:143], s[48:49], 0, v[134:135]
	s_mov_b32 m0, s50
	s_nop 0
	global_load_lds_dwordx4 v[142:143], off
	v_lshl_add_u64 v[142:143], s[48:49], 0, v[130:131]
	s_add_i32 m0, s50, 0x2000
	s_nop 0
	global_load_lds_dwordx4 v[142:143], off
	s_waitcnt vmcnt(6)
	s_barrier
	v_mfma_f32_16x16x32_bf16 v[52:55], v[194:197], v[162:165], v[52:55]
	v_mfma_f32_16x16x32_bf16 v[48:51], v[202:205], v[162:165], v[48:51]
	v_mfma_f32_16x16x32_bf16 v[36:39], v[194:197], v[170:173], v[36:39]
	v_mfma_f32_16x16x32_bf16 v[32:35], v[202:205], v[170:173], v[32:35]
	v_mfma_f32_16x16x32_bf16 v[20:23], v[194:197], v[178:181], v[20:23]
	v_mfma_f32_16x16x32_bf16 v[16:19], v[202:205], v[178:181], v[16:19]
	v_mfma_f32_16x16x32_bf16 v[4:7], v[194:197], v[186:189], v[4:7]
	v_mfma_f32_16x16x32_bf16 v[0:3], v[202:205], v[186:189], v[0:3]
	v_mfma_f32_16x16x32_bf16 v[52:55], v[198:201], v[166:169], v[52:55]
	v_mfma_f32_16x16x32_bf16 v[48:51], v[208:211], v[166:169], v[48:51]
	v_mfma_f32_16x16x32_bf16 v[36:39], v[198:201], v[174:177], v[36:39]
	v_mfma_f32_16x16x32_bf16 v[32:35], v[208:211], v[174:177], v[32:35]
	v_mfma_f32_16x16x32_bf16 v[20:23], v[198:201], v[182:185], v[20:23]
	v_mfma_f32_16x16x32_bf16 v[16:19], v[208:211], v[182:185], v[16:19]
	v_mfma_f32_16x16x32_bf16 v[4:7], v[198:201], v[190:193], v[4:7]
	v_mfma_f32_16x16x32_bf16 v[0:3], v[208:211], v[190:193], v[0:3]
	s_add_i32 s70, s70, 2
	s_add_u32 s46, s46, 0x100
	s_addc_u32 s47, s47, 0
	s_add_u32 s68, s68, 0x100
	s_addc_u32 s69, s69, 0
	s_cmp_gt_u32 s70, 13
	s_barrier
; DEV float sigmoidf_(float x) { return __builtin_amdgcn_rcpf(1.f + __expf(-x)); }
;   DEV void operator()(const f32x4 (&acc)[2][2][4][2], const pg8::Unit& u, int wr, int wc, int fr, int fq) const {
;     const int b = u.pn >> 2, pn = u.pn & 3;
;     bf16_t* G = (bf16_t*)(ws + (b == 0 ? O_G1 : (b == 1 ? O_G2 : O_G3)));
;     const int row0 = u.pm * 256 + wr * 64 + fr, col0 = pn * 256 + wc * 32 + 8 * fq;
; #pragma unroll
;     for (int ai = 0; ai < 2; ++ai)
; #pragma unroll
;       for (int m = 0; m < 4; ++m) {
;         const int row = row0 + ai * 128 + m * 16;
; #pragma unroll
;         for (int bj = 0; bj < 2; ++bj) {
;           const f32x4 a0 = acc[ai][bj][m][0], a1 = acc[ai][bj][m][1];
;           u32x4 o;
;           o[0] = pk2(sigmoidf_(a0[0]), sigmoidf_(a0[1])); o[1] = pk2(sigmoidf_(a0[2]), sigmoidf_(a0[3]));
;           o[2] = pk2(sigmoidf_(a1[0]), sigmoidf_(a1[1])); o[3] = pk2(sigmoidf_(a1[2]), sigmoidf_(a1[3]));
;           *(u32x4*)(G + (size_t)row * DM + col0 + bj * 128) = o;
;         }
;       }
;   }
	s_cbranch_scc0 .LBB0_152
	s_and_b32 s1, s65, -4
	s_cmp_eq_u32 s1, 4
	s_mov_b32 s1, 0xee00000
	s_cselect_b32 s1, s1, 0x13200000
	s_cmp_gt_u32 s65, 3
	s_cselect_b32 s1, s1, 0x6600000
	s_add_u32 s46, s74, s1
	s_addc_u32 s47, s75, 0
	s_lshl_b32 s1, s65, 8
	s_and_b32 s1, s1, 0x300
	v_mul_f32_e32 v122, 0xbfb8aa3b, v122
	v_or_b32_e32 v96, s1, v148
	v_exp_f32_e32 v122, v122
	v_mul_f32_e32 v123, 0xbfb8aa3b, v123
	v_lshl_add_u32 v144, s44, 8, v146
	v_lshlrev_b32_e32 v96, 1, v96
	v_exp_f32_e32 v123, v123
	v_lshl_add_u64 v[142:143], s[46:47], 0, v[96:97]
	v_ashrrev_i32_e32 v145, 31, v144
	v_mul_f32_e32 v96, 0xbfb8aa3b, v126
	v_mul_f32_e32 v126, 0xbfb8aa3b, v127
	v_lshlrev_b64 v[150:151], 11, v[144:145]
	v_exp_f32_e32 v96, v96
	v_exp_f32_e32 v145, v126
	v_add_f32_e32 v122, 1.0, v122
	v_lshl_add_u64 v[126:127], v[142:143], 0, v[150:151]
	v_rcp_f32_e32 v150, v122
	v_add_f32_e32 v122, 1.0, v123
	v_mul_f32_e32 v123, 0xbfb8aa3b, v124
	v_exp_f32_e32 v123, v123
	v_mul_f32_e32 v124, 0xbfb8aa3b, v125
	v_mul_f32_e32 v114, 0xbfb8aa3b, v114
	v_add_f32_e32 v96, 1.0, v96
	v_add_f32_e32 v145, 1.0, v145
	v_mul_f32_e32 v128, 0xbfb8aa3b, v128
	v_mul_f32_e32 v129, 0xbfb8aa3b, v129
	v_exp_f32_e32 v124, v124
	v_exp_f32_e32 v114, v114
	v_mul_f32_e32 v115, 0xbfb8aa3b, v115
	v_rcp_f32_e32 v96, v96
	v_exp_f32_e32 v128, v128
	v_exp_f32_e32 v129, v129
	v_rcp_f32_e32 v145, v145
	v_exp_f32_e32 v115, v115
	v_rcp_f32_e32 v125, v122
	v_add_f32_e32 v122, 1.0, v123
	v_rcp_f32_e32 v151, v122
	v_add_f32_e32 v122, 1.0, v124
	v_add_f32_e32 v114, 1.0, v114
	v_add_f32_e32 v128, 1.0, v128
	v_add_f32_e32 v129, 1.0, v129
	v_rcp_f32_e32 v152, v122
	v_cvt_pk_bf16_f32 v122, v96, v145
	v_mul_f32_e32 v96, 0xbfb8aa3b, v118
	v_mul_f32_e32 v118, 0xbfb8aa3b, v119
	v_mul_f32_e32 v119, 0xbfb8aa3b, v120
	v_mul_f32_e32 v120, 0xbfb8aa3b, v121
	v_rcp_f32_e32 v121, v114
	v_add_f32_e32 v114, 1.0, v115
	v_mul_f32_e32 v115, 0xbfb8aa3b, v116
	v_rcp_f32_e32 v128, v128
	v_rcp_f32_e32 v129, v129
	v_exp_f32_e32 v115, v115
	v_mul_f32_e32 v116, 0xbfb8aa3b, v117
	v_exp_f32_e32 v96, v96
	v_exp_f32_e32 v118, v118
	v_exp_f32_e32 v119, v119
	v_exp_f32_e32 v120, v120
	v_exp_f32_e32 v116, v116
	v_cvt_pk_bf16_f32 v123, v128, v129
	v_cvt_pk_bf16_f32 v124, v150, v125
	v_cvt_pk_bf16_f32 v125, v151, v152
	v_rcp_f32_e32 v117, v114
	v_add_f32_e32 v114, 1.0, v115
	global_store_dwordx4 v[126:127], v[122:125], off
	v_add_f32_e32 v96, 1.0, v96
	v_add_f32_e32 v118, 1.0, v118
	v_add_f32_e32 v119, 1.0, v119
	v_add_f32_e32 v120, 1.0, v120
	v_rcp_f32_e32 v122, v114
	v_add_f32_e32 v114, 1.0, v116
	v_rcp_f32_e32 v96, v96
	v_rcp_f32_e32 v118, v118
	v_rcp_f32_e32 v119, v119
	v_rcp_f32_e32 v120, v120
	v_rcp_f32_e32 v123, v114
	v_mul_f32_e32 v106, 0xbfb8aa3b, v106
	v_exp_f32_e32 v106, v106
	v_mul_f32_e32 v107, 0xbfb8aa3b, v107
	v_cvt_pk_bf16_f32 v114, v96, v118
	v_cvt_pk_bf16_f32 v115, v119, v120
	v_cvt_pk_bf16_f32 v116, v121, v117
	v_cvt_pk_bf16_f32 v117, v122, v123
	v_exp_f32_e32 v107, v107
	global_store_dwordx4 v[126:127], v[114:117], off offset:256
	v_mul_f32_e32 v96, 0xbfb8aa3b, v110
	v_mul_f32_e32 v110, 0xbfb8aa3b, v111
	v_or_b32_e32 v114, 16, v144
	v_ashrrev_i32_e32 v115, 31, v114
	v_exp_f32_e32 v96, v96
	v_exp_f32_e32 v116, v110
	v_lshlrev_b64 v[114:115], 11, v[114:115]
	v_add_f32_e32 v106, 1.0, v106
	v_lshl_add_u64 v[110:111], v[142:143], 0, v[114:115]
	v_rcp_f32_e32 v115, v106
	v_add_f32_e32 v106, 1.0, v107
	v_mul_f32_e32 v107, 0xbfb8aa3b, v108
	v_exp_f32_e32 v107, v107
	v_mul_f32_e32 v108, 0xbfb8aa3b, v109
	v_mul_f32_e32 v98, 0xbfb8aa3b, v98
	v_add_f32_e32 v96, 1.0, v96
	v_add_f32_e32 v114, 1.0, v116
	v_mul_f32_e32 v112, 0xbfb8aa3b, v112
	v_mul_f32_e32 v113, 0xbfb8aa3b, v113
	v_exp_f32_e32 v108, v108
	v_exp_f32_e32 v98, v98
	v_mul_f32_e32 v99, 0xbfb8aa3b, v99
	v_rcp_f32_e32 v96, v96
	v_exp_f32_e32 v112, v112
	v_exp_f32_e32 v113, v113
	v_rcp_f32_e32 v114, v114
	v_exp_f32_e32 v99, v99
	v_rcp_f32_e32 v109, v106
	v_add_f32_e32 v106, 1.0, v107
	v_rcp_f32_e32 v116, v106
	v_add_f32_e32 v106, 1.0, v108
	v_add_f32_e32 v98, 1.0, v98
	v_add_f32_e32 v112, 1.0, v112
	v_add_f32_e32 v113, 1.0, v113
	v_rcp_f32_e32 v117, v106
	v_cvt_pk_bf16_f32 v106, v96, v114
	v_mul_f32_e32 v96, 0xbfb8aa3b, v102
	v_mul_f32_e32 v102, 0xbfb8aa3b, v103
	v_mul_f32_e32 v103, 0xbfb8aa3b, v104
	v_mul_f32_e32 v104, 0xbfb8aa3b, v105
	v_rcp_f32_e32 v105, v98
	v_add_f32_e32 v98, 1.0, v99
	v_mul_f32_e32 v99, 0xbfb8aa3b, v100
	v_rcp_f32_e32 v112, v112
	v_rcp_f32_e32 v113, v113
	v_exp_f32_e32 v99, v99
	v_mul_f32_e32 v100, 0xbfb8aa3b, v101
	v_exp_f32_e32 v96, v96
	v_exp_f32_e32 v102, v102
	v_exp_f32_e32 v103, v103
	v_exp_f32_e32 v104, v104
	v_exp_f32_e32 v100, v100
	v_cvt_pk_bf16_f32 v107, v112, v113
	v_cvt_pk_bf16_f32 v108, v115, v109
	v_cvt_pk_bf16_f32 v109, v116, v117
	v_rcp_f32_e32 v101, v98
	v_add_f32_e32 v98, 1.0, v99
	global_store_dwordx4 v[110:111], v[106:109], off
	v_add_f32_e32 v96, 1.0, v96
	v_add_f32_e32 v102, 1.0, v102
	v_add_f32_e32 v103, 1.0, v103
	v_add_f32_e32 v104, 1.0, v104
	v_rcp_f32_e32 v106, v98
	v_add_f32_e32 v98, 1.0, v100
	v_rcp_f32_e32 v96, v96
	v_rcp_f32_e32 v102, v102
	v_rcp_f32_e32 v103, v103
	v_rcp_f32_e32 v104, v104
	v_rcp_f32_e32 v107, v98
	v_mul_f32_e32 v88, 0xbfb8aa3b, v88
	v_exp_f32_e32 v88, v88
	v_mul_f32_e32 v89, 0xbfb8aa3b, v89
	v_cvt_pk_bf16_f32 v98, v96, v102
	v_cvt_pk_bf16_f32 v99, v103, v104
	v_cvt_pk_bf16_f32 v100, v105, v101
	v_cvt_pk_bf16_f32 v101, v106, v107
	v_exp_f32_e32 v89, v89
	global_store_dwordx4 v[110:111], v[98:101], off offset:256
	v_mul_f32_e32 v92, 0xbfb8aa3b, v92
	v_exp_f32_e32 v96, v92
	v_or_b32_e32 v98, 32, v144
	v_ashrrev_i32_e32 v99, 31, v98
	v_lshlrev_b64 v[98:99], 11, v[98:99]
	v_mul_f32_e32 v92, 0xbfb8aa3b, v93
; DEV float sigmoidf_(float x) { return __builtin_amdgcn_rcpf(1.f + __expf(-x)); }
;   DEV void operator()(const f32x4 (&acc)[2][2][4][2], const pg8::Unit& u, int wr, int wc, int fr, int fq) const {
;     ...
; #pragma unroll
;     for (int ai = 0; ai < 2; ++ai)
; #pragma unroll
;       for (int m = 0; m < 4; ++m) {
;         const int row = row0 + ai * 128 + m * 16;
; #pragma unroll
;         for (int bj = 0; bj < 2; ++bj) {
;           const f32x4 a0 = acc[ai][bj][m][0], a1 = acc[ai][bj][m][1];
;           u32x4 o;
;           o[0] = pk2(sigmoidf_(a0[0]), sigmoidf_(a0[1])); o[1] = pk2(sigmoidf_(a0[2]), sigmoidf_(a0[3]));
;           o[2] = pk2(sigmoidf_(a1[0]), sigmoidf_(a1[1])); o[3] = pk2(sigmoidf_(a1[2]), sigmoidf_(a1[3]));
;           *(u32x4*)(G + (size_t)row * DM + col0 + bj * 128) = o;
;         }
;       }
	v_add_f32_e32 v88, 1.0, v88
	v_exp_f32_e32 v100, v92
	v_lshl_add_u64 v[92:93], v[142:143], 0, v[98:99]
	v_rcp_f32_e32 v99, v88
	v_add_f32_e32 v88, 1.0, v89
	v_mul_f32_e32 v89, 0xbfb8aa3b, v90
	v_mul_f32_e32 v94, 0xbfb8aa3b, v94
	v_mul_f32_e32 v95, 0xbfb8aa3b, v95
	v_exp_f32_e32 v89, v89
	v_mul_f32_e32 v90, 0xbfb8aa3b, v91
	v_exp_f32_e32 v94, v94
	v_exp_f32_e32 v95, v95
	v_exp_f32_e32 v90, v90
	v_rcp_f32_e32 v91, v88
	v_add_f32_e32 v88, 1.0, v89
	v_add_f32_e32 v96, 1.0, v96
	v_add_f32_e32 v98, 1.0, v100
	v_add_f32_e32 v94, 1.0, v94
	v_add_f32_e32 v95, 1.0, v95
	v_rcp_f32_e32 v100, v88
	v_add_f32_e32 v88, 1.0, v90
	v_mul_f32_e32 v80, 0xbfb8aa3b, v80
	v_rcp_f32_e32 v96, v96
	v_rcp_f32_e32 v98, v98
	v_rcp_f32_e32 v94, v94
	v_rcp_f32_e32 v95, v95
	v_rcp_f32_e32 v101, v88
	v_exp_f32_e32 v80, v80
	v_mul_f32_e32 v81, 0xbfb8aa3b, v81
	v_exp_f32_e32 v81, v81
	v_cvt_pk_bf16_f32 v88, v96, v98
	v_cvt_pk_bf16_f32 v89, v94, v95
	v_cvt_pk_bf16_f32 v90, v99, v91
	v_cvt_pk_bf16_f32 v91, v100, v101
	v_add_f32_e32 v80, 1.0, v80
	global_store_dwordx4 v[92:93], v[88:91], off
	v_mul_f32_e32 v84, 0xbfb8aa3b, v84
	v_mul_f32_e32 v85, 0xbfb8aa3b, v85
	v_rcp_f32_e32 v88, v80
	v_add_f32_e32 v80, 1.0, v81
	v_mul_f32_e32 v81, 0xbfb8aa3b, v82
	v_mul_f32_e32 v86, 0xbfb8aa3b, v86
	v_mul_f32_e32 v87, 0xbfb8aa3b, v87
	v_exp_f32_e32 v81, v81
	v_mul_f32_e32 v82, 0xbfb8aa3b, v83
	v_exp_f32_e32 v84, v84
	v_exp_f32_e32 v85, v85
	v_exp_f32_e32 v86, v86
	v_exp_f32_e32 v87, v87
	v_exp_f32_e32 v82, v82
	v_rcp_f32_e32 v83, v80
	v_add_f32_e32 v80, 1.0, v81
	v_add_f32_e32 v84, 1.0, v84
	v_add_f32_e32 v85, 1.0, v85
	v_add_f32_e32 v86, 1.0, v86
	v_add_f32_e32 v87, 1.0, v87
	v_rcp_f32_e32 v89, v80
	v_add_f32_e32 v80, 1.0, v82
	v_rcp_f32_e32 v84, v84
	v_rcp_f32_e32 v85, v85
	v_rcp_f32_e32 v86, v86
	v_rcp_f32_e32 v87, v87
	v_rcp_f32_e32 v90, v80
	v_mul_f32_e32 v72, 0xbfb8aa3b, v72
	v_cvt_pk_bf16_f32 v80, v84, v85
	v_cvt_pk_bf16_f32 v81, v86, v87
	v_cvt_pk_bf16_f32 v82, v88, v83
	v_cvt_pk_bf16_f32 v83, v89, v90
	v_mul_f32_e32 v76, 0xbfb8aa3b, v76
	v_exp_f32_e32 v72, v72
	v_mul_f32_e32 v73, 0xbfb8aa3b, v73
	global_store_dwordx4 v[92:93], v[80:83], off offset:256
	v_exp_f32_e32 v73, v73
	v_add_f32_e32 v72, 1.0, v72
	v_exp_f32_e32 v82, v76
	v_or_b32_e32 v80, 48, v144
	v_ashrrev_i32_e32 v81, 31, v80
	v_lshlrev_b64 v[80:81], 11, v[80:81]
	v_mul_f32_e32 v76, 0xbfb8aa3b, v77
	v_exp_f32_e32 v83, v76
	v_lshl_add_u64 v[76:77], v[142:143], 0, v[80:81]
	v_add_f32_e32 v80, 1.0, v82
	v_rcp_f32_e32 v82, v72
	v_add_f32_e32 v72, 1.0, v73
	v_mul_f32_e32 v73, 0xbfb8aa3b, v74
	v_mul_f32_e32 v78, 0xbfb8aa3b, v78
	v_mul_f32_e32 v79, 0xbfb8aa3b, v79
	v_exp_f32_e32 v73, v73
	v_mul_f32_e32 v74, 0xbfb8aa3b, v75
	v_exp_f32_e32 v78, v78
	v_exp_f32_e32 v79, v79
	v_exp_f32_e32 v74, v74
	v_rcp_f32_e32 v75, v72
	v_add_f32_e32 v72, 1.0, v73
	v_add_f32_e32 v81, 1.0, v83
	v_add_f32_e32 v78, 1.0, v78
	v_add_f32_e32 v79, 1.0, v79
	v_rcp_f32_e32 v83, v72
	v_add_f32_e32 v72, 1.0, v74
	v_mul_f32_e32 v64, 0xbfb8aa3b, v64
	v_rcp_f32_e32 v80, v80
	v_rcp_f32_e32 v81, v81
	v_rcp_f32_e32 v78, v78
	v_rcp_f32_e32 v79, v79
	v_rcp_f32_e32 v84, v72
	v_exp_f32_e32 v64, v64
	v_mul_f32_e32 v65, 0xbfb8aa3b, v65
	v_exp_f32_e32 v65, v65
	v_cvt_pk_bf16_f32 v72, v80, v81
	v_cvt_pk_bf16_f32 v73, v78, v79
	v_cvt_pk_bf16_f32 v74, v82, v75
	v_cvt_pk_bf16_f32 v75, v83, v84
	v_add_f32_e32 v64, 1.0, v64
	global_store_dwordx4 v[76:77], v[72:75], off
	v_mul_f32_e32 v68, 0xbfb8aa3b, v68
	v_mul_f32_e32 v69, 0xbfb8aa3b, v69
	v_rcp_f32_e32 v72, v64
	v_add_f32_e32 v64, 1.0, v65
	v_mul_f32_e32 v65, 0xbfb8aa3b, v66
	v_mul_f32_e32 v70, 0xbfb8aa3b, v70
	v_mul_f32_e32 v71, 0xbfb8aa3b, v71
	v_exp_f32_e32 v65, v65
	v_mul_f32_e32 v66, 0xbfb8aa3b, v67
	v_exp_f32_e32 v68, v68
	v_exp_f32_e32 v69, v69
	v_exp_f32_e32 v70, v70
	v_exp_f32_e32 v71, v71
	v_exp_f32_e32 v66, v66
	v_rcp_f32_e32 v67, v64
	v_add_f32_e32 v64, 1.0, v65
	v_add_f32_e32 v68, 1.0, v68
	v_add_f32_e32 v69, 1.0, v69
	v_add_f32_e32 v70, 1.0, v70
	v_add_f32_e32 v71, 1.0, v71
	v_rcp_f32_e32 v73, v64
	v_add_f32_e32 v64, 1.0, v66
	v_mul_f32_e32 v56, 0xbfb8aa3b, v56
	v_rcp_f32_e32 v68, v68
	v_rcp_f32_e32 v69, v69
	v_rcp_f32_e32 v70, v70
	v_rcp_f32_e32 v71, v71
	v_rcp_f32_e32 v74, v64
	v_exp_f32_e32 v56, v56
	v_mul_f32_e32 v57, 0xbfb8aa3b, v57
	v_exp_f32_e32 v57, v57
	v_cvt_pk_bf16_f32 v64, v68, v69
	v_cvt_pk_bf16_f32 v65, v70, v71
	v_cvt_pk_bf16_f32 v66, v72, v67
	v_cvt_pk_bf16_f32 v67, v73, v74
	v_add_f32_e32 v56, 1.0, v56
	global_store_dwordx4 v[76:77], v[64:67], off offset:256
	v_mul_f32_e32 v60, 0xbfb8aa3b, v60
	v_mul_f32_e32 v62, 0xbfb8aa3b, v62
	v_mul_f32_e32 v63, 0xbfb8aa3b, v63
	v_rcp_f32_e32 v66, v56
	v_add_f32_e32 v56, 1.0, v57
	v_mul_f32_e32 v57, 0xbfb8aa3b, v58
	v_exp_f32_e32 v64, v60
	v_mul_f32_e32 v60, 0xbfb8aa3b, v61
	v_exp_f32_e32 v62, v62
	v_exp_f32_e32 v63, v63
	v_exp_f32_e32 v57, v57
	v_mul_f32_e32 v58, 0xbfb8aa3b, v59
	v_exp_f32_e32 v65, v60
	v_exp_f32_e32 v58, v58
	v_add_f32_e32 v62, 1.0, v62
	v_add_f32_e32 v63, 1.0, v63
	v_rcp_f32_e32 v59, v56
	v_add_f32_e32 v56, 1.0, v57
	v_add_f32_e32 v64, 1.0, v64
	v_add_f32_e32 v65, 1.0, v65
	v_rcp_f32_e32 v62, v62
	v_rcp_f32_e32 v63, v63
	v_rcp_f32_e32 v67, v56
	v_add_f32_e32 v56, 1.0, v58
	v_mul_f32_e32 v48, 0xbfb8aa3b, v48
	v_rcp_f32_e32 v64, v64
	v_rcp_f32_e32 v65, v65
	v_rcp_f32_e32 v68, v56
	v_exp_f32_e32 v48, v48
	v_mul_f32_e32 v49, 0xbfb8aa3b, v49
	v_exp_f32_e32 v49, v49
	s_mov_b32 s1, 0x40000
	v_cvt_pk_bf16_f32 v57, v62, v63
	v_add_co_u32_e32 v62, vcc, s1, v126
	v_cvt_pk_bf16_f32 v56, v64, v65
	v_cvt_pk_bf16_f32 v58, v66, v59
	v_cvt_pk_bf16_f32 v59, v67, v68
	v_addc_co_u32_e32 v63, vcc, 0, v127, vcc
	v_add_f32_e32 v48, 1.0, v48
; DEV float sigmoidf_(float x) { return __builtin_amdgcn_rcpf(1.f + __expf(-x)); }
;   DEV void operator()(const f32x4 (&acc)[2][2][4][2], const pg8::Unit& u, int wr, int wc, int fr, int fq) const {
;     ...
; #pragma unroll
;     for (int ai = 0; ai < 2; ++ai)
; #pragma unroll
;       for (int m = 0; m < 4; ++m) {
;         const int row = row0 + ai * 128 + m * 16;
; #pragma unroll
;         for (int bj = 0; bj < 2; ++bj) {
;           const f32x4 a0 = acc[ai][bj][m][0], a1 = acc[ai][bj][m][1];
;           u32x4 o;
;           o[0] = pk2(sigmoidf_(a0[0]), sigmoidf_(a0[1])); o[1] = pk2(sigmoidf_(a0[2]), sigmoidf_(a0[3]));
;           o[2] = pk2(sigmoidf_(a1[0]), sigmoidf_(a1[1])); o[3] = pk2(sigmoidf_(a1[2]), sigmoidf_(a1[3]));
;           *(u32x4*)(G + (size_t)row * DM + col0 + bj * 128) = o;
;         }
;       }
	global_store_dwordx4 v[62:63], v[56:59], off
	v_mul_f32_e32 v52, 0xbfb8aa3b, v52
	v_mul_f32_e32 v53, 0xbfb8aa3b, v53
	v_rcp_f32_e32 v56, v48
	v_add_f32_e32 v48, 1.0, v49
	v_mul_f32_e32 v49, 0xbfb8aa3b, v50
	v_mul_f32_e32 v54, 0xbfb8aa3b, v54
	v_mul_f32_e32 v55, 0xbfb8aa3b, v55
	v_exp_f32_e32 v49, v49
	v_mul_f32_e32 v50, 0xbfb8aa3b, v51
	v_exp_f32_e32 v52, v52
	v_exp_f32_e32 v53, v53
	v_exp_f32_e32 v54, v54
	v_exp_f32_e32 v55, v55
	v_exp_f32_e32 v50, v50
	v_rcp_f32_e32 v51, v48
	v_add_f32_e32 v48, 1.0, v49
	v_add_f32_e32 v52, 1.0, v52
	v_add_f32_e32 v53, 1.0, v53
	v_add_f32_e32 v54, 1.0, v54
	v_add_f32_e32 v55, 1.0, v55
	v_rcp_f32_e32 v57, v48
	v_add_f32_e32 v48, 1.0, v50
	v_mul_f32_e32 v40, 0xbfb8aa3b, v40
	v_rcp_f32_e32 v52, v52
	v_rcp_f32_e32 v53, v53
	v_rcp_f32_e32 v54, v54
	v_rcp_f32_e32 v55, v55
	v_rcp_f32_e32 v58, v48
	v_exp_f32_e32 v40, v40
	v_mul_f32_e32 v41, 0xbfb8aa3b, v41
	v_exp_f32_e32 v41, v41
	s_mov_b64 s[46:47], 0x40000
	v_lshl_add_u64 v[60:61], v[126:127], 0, s[46:47]
	v_cvt_pk_bf16_f32 v48, v52, v53
	v_cvt_pk_bf16_f32 v49, v54, v55
	v_cvt_pk_bf16_f32 v50, v56, v51
	v_cvt_pk_bf16_f32 v51, v57, v58
	v_add_f32_e32 v40, 1.0, v40
	global_store_dwordx4 v[60:61], v[48:51], off offset:256
	v_mul_f32_e32 v44, 0xbfb8aa3b, v44
	v_mul_f32_e32 v46, 0xbfb8aa3b, v46
	v_mul_f32_e32 v47, 0xbfb8aa3b, v47
	v_rcp_f32_e32 v50, v40
	v_add_f32_e32 v40, 1.0, v41
	v_mul_f32_e32 v41, 0xbfb8aa3b, v42
	v_exp_f32_e32 v48, v44
	v_mul_f32_e32 v44, 0xbfb8aa3b, v45
	v_exp_f32_e32 v46, v46
	v_exp_f32_e32 v47, v47
	v_exp_f32_e32 v41, v41
	v_mul_f32_e32 v42, 0xbfb8aa3b, v43
	v_exp_f32_e32 v49, v44
	v_exp_f32_e32 v42, v42
	v_add_f32_e32 v46, 1.0, v46
	v_add_f32_e32 v47, 1.0, v47
	v_rcp_f32_e32 v43, v40
	v_add_f32_e32 v40, 1.0, v41
	v_add_f32_e32 v48, 1.0, v48
	v_add_f32_e32 v49, 1.0, v49
	v_rcp_f32_e32 v46, v46
	v_rcp_f32_e32 v47, v47
	v_rcp_f32_e32 v51, v40
	v_add_f32_e32 v40, 1.0, v42
	v_mul_f32_e32 v32, 0xbfb8aa3b, v32
	v_rcp_f32_e32 v48, v48
	v_rcp_f32_e32 v49, v49
	v_rcp_f32_e32 v52, v40
	v_exp_f32_e32 v32, v32
	v_mul_f32_e32 v33, 0xbfb8aa3b, v33
	v_exp_f32_e32 v33, v33
	s_mov_b32 s1, 0x48000
	v_cvt_pk_bf16_f32 v41, v46, v47
	v_add_co_u32_e32 v46, vcc, s1, v126
	v_cvt_pk_bf16_f32 v40, v48, v49
	v_cvt_pk_bf16_f32 v42, v50, v43
	v_cvt_pk_bf16_f32 v43, v51, v52
	v_addc_co_u32_e32 v47, vcc, 0, v127, vcc
	v_add_f32_e32 v32, 1.0, v32
	global_store_dwordx4 v[46:47], v[40:43], off
	v_mul_f32_e32 v36, 0xbfb8aa3b, v36
	v_mul_f32_e32 v37, 0xbfb8aa3b, v37
	v_rcp_f32_e32 v40, v32
	v_add_f32_e32 v32, 1.0, v33
	v_mul_f32_e32 v33, 0xbfb8aa3b, v34
	v_mul_f32_e32 v38, 0xbfb8aa3b, v38
	v_mul_f32_e32 v39, 0xbfb8aa3b, v39
	v_exp_f32_e32 v33, v33
	v_mul_f32_e32 v34, 0xbfb8aa3b, v35
	v_exp_f32_e32 v36, v36
	v_exp_f32_e32 v37, v37
	v_exp_f32_e32 v38, v38
	v_exp_f32_e32 v39, v39
	v_exp_f32_e32 v34, v34
	v_rcp_f32_e32 v35, v32
	v_add_f32_e32 v32, 1.0, v33
	v_add_f32_e32 v36, 1.0, v36
	v_add_f32_e32 v37, 1.0, v37
	v_add_f32_e32 v38, 1.0, v38
	v_add_f32_e32 v39, 1.0, v39
	v_rcp_f32_e32 v41, v32
	v_add_f32_e32 v32, 1.0, v34
	v_mul_f32_e32 v24, 0xbfb8aa3b, v24
	v_rcp_f32_e32 v36, v36
	v_rcp_f32_e32 v37, v37
	v_rcp_f32_e32 v38, v38
	v_rcp_f32_e32 v39, v39
	v_rcp_f32_e32 v42, v32
	v_exp_f32_e32 v24, v24
	v_mul_f32_e32 v25, 0xbfb8aa3b, v25
	v_exp_f32_e32 v25, v25
	s_mov_b64 s[46:47], 0x48000
	v_lshl_add_u64 v[44:45], v[126:127], 0, s[46:47]
	v_cvt_pk_bf16_f32 v32, v36, v37
	v_cvt_pk_bf16_f32 v33, v38, v39
	v_cvt_pk_bf16_f32 v34, v40, v35
	v_cvt_pk_bf16_f32 v35, v41, v42
	v_add_f32_e32 v24, 1.0, v24
	global_store_dwordx4 v[44:45], v[32:35], off offset:256
	v_mul_f32_e32 v28, 0xbfb8aa3b, v28
	v_mul_f32_e32 v30, 0xbfb8aa3b, v30
	v_mul_f32_e32 v31, 0xbfb8aa3b, v31
	v_rcp_f32_e32 v34, v24
	v_add_f32_e32 v24, 1.0, v25
	v_mul_f32_e32 v25, 0xbfb8aa3b, v26
	v_exp_f32_e32 v32, v28
	v_mul_f32_e32 v28, 0xbfb8aa3b, v29
	v_exp_f32_e32 v30, v30
	v_exp_f32_e32 v31, v31
	v_exp_f32_e32 v25, v25
	v_mul_f32_e32 v26, 0xbfb8aa3b, v27
	v_exp_f32_e32 v33, v28
	v_exp_f32_e32 v26, v26
	v_add_f32_e32 v30, 1.0, v30
	v_add_f32_e32 v31, 1.0, v31
	v_rcp_f32_e32 v27, v24
	v_add_f32_e32 v24, 1.0, v25
	v_add_f32_e32 v32, 1.0, v32
	v_add_f32_e32 v33, 1.0, v33
; DEV float sigmoidf_(float x) { return __builtin_amdgcn_rcpf(1.f + __expf(-x)); }
; #define PG8_WAIT_V(n) asm volatile("s_waitcnt vmcnt(" #n ")" ::: "memory")
; #define PG8_BAR __builtin_amdgcn_s_barrier()
; template <class Epi, class Sched>
; __device__ __forceinline__ void gemm_phase(PG8_LAS unsigned char* lds, const Gemm g, const Sched& S, const Epi& E) {
;     ...
;         if (!has_next) break;
; #pragma unroll
;         for (int a = 0; a < 2; ++a)
; #pragma unroll
;             for (int b = 0; b < 2; ++b)
; #pragma unroll
;                 for (int m = 0; m < 4; ++m)
; #pragma unroll
;                     for (int n = 0; n < 2; ++n) acc[a][b][m][n] = (f32x4){0.f, 0.f, 0.f, 0.f};
;         cur = nxt; cA = nA; cB = nB; ++ui;
;     }
;     PG8_WAIT_V(0);
;     if (wr == 0) PG8_BAR;
;     PG8_BAR;
;   DEV void operator()(const f32x4 (&acc)[2][2][4][2], const pg8::Unit& u, int wr, int wc, int fr, int fq) const {
;     ...
; #pragma unroll
;     for (int ai = 0; ai < 2; ++ai)
; #pragma unroll
;       for (int m = 0; m < 4; ++m) {
;         const int row = row0 + ai * 128 + m * 16;
; #pragma unroll
;         for (int bj = 0; bj < 2; ++bj) {
;           const f32x4 a0 = acc[ai][bj][m][0], a1 = acc[ai][bj][m][1];
;           u32x4 o;
;           o[0] = pk2(sigmoidf_(a0[0]), sigmoidf_(a0[1])); o[1] = pk2(sigmoidf_(a0[2]), sigmoidf_(a0[3]));
;           o[2] = pk2(sigmoidf_(a1[0]), sigmoidf_(a1[1])); o[3] = pk2(sigmoidf_(a1[2]), sigmoidf_(a1[3]));
;           *(u32x4*)(G + (size_t)row * DM + col0 + bj * 128) = o;
;         }
;       }
;   }
	v_rcp_f32_e32 v30, v30
	v_rcp_f32_e32 v31, v31
	v_rcp_f32_e32 v35, v24
	v_add_f32_e32 v24, 1.0, v26
	v_mul_f32_e32 v16, 0xbfb8aa3b, v16
	v_rcp_f32_e32 v32, v32
	v_rcp_f32_e32 v33, v33
	v_rcp_f32_e32 v36, v24
	v_exp_f32_e32 v16, v16
	v_mul_f32_e32 v17, 0xbfb8aa3b, v17
	v_exp_f32_e32 v17, v17
	s_mov_b32 s1, 0x50000
	v_cvt_pk_bf16_f32 v25, v30, v31
	v_add_co_u32_e32 v30, vcc, s1, v126
	v_cvt_pk_bf16_f32 v24, v32, v33
	v_cvt_pk_bf16_f32 v26, v34, v27
	v_cvt_pk_bf16_f32 v27, v35, v36
	v_addc_co_u32_e32 v31, vcc, 0, v127, vcc
	v_add_f32_e32 v16, 1.0, v16
	global_store_dwordx4 v[30:31], v[24:27], off
	v_mul_f32_e32 v20, 0xbfb8aa3b, v20
	v_mul_f32_e32 v21, 0xbfb8aa3b, v21
	v_rcp_f32_e32 v24, v16
	v_add_f32_e32 v16, 1.0, v17
	v_mul_f32_e32 v17, 0xbfb8aa3b, v18
	v_mul_f32_e32 v22, 0xbfb8aa3b, v22
	v_mul_f32_e32 v23, 0xbfb8aa3b, v23
	v_exp_f32_e32 v17, v17
	v_mul_f32_e32 v18, 0xbfb8aa3b, v19
	v_exp_f32_e32 v20, v20
	v_exp_f32_e32 v21, v21
	v_exp_f32_e32 v22, v22
	v_exp_f32_e32 v23, v23
	v_exp_f32_e32 v18, v18
	v_rcp_f32_e32 v19, v16
	v_add_f32_e32 v16, 1.0, v17
	v_add_f32_e32 v20, 1.0, v20
	v_add_f32_e32 v21, 1.0, v21
	v_add_f32_e32 v22, 1.0, v22
	v_add_f32_e32 v23, 1.0, v23
	v_rcp_f32_e32 v25, v16
	v_add_f32_e32 v16, 1.0, v18
	v_mul_f32_e32 v8, 0xbfb8aa3b, v8
	v_rcp_f32_e32 v20, v20
	v_rcp_f32_e32 v21, v21
	v_rcp_f32_e32 v22, v22
	v_rcp_f32_e32 v23, v23
	v_rcp_f32_e32 v26, v16
	v_exp_f32_e32 v8, v8
	v_mul_f32_e32 v9, 0xbfb8aa3b, v9
	v_exp_f32_e32 v9, v9
	s_mov_b64 s[46:47], 0x50000
	v_lshl_add_u64 v[28:29], v[126:127], 0, s[46:47]
	v_cvt_pk_bf16_f32 v16, v20, v21
	v_cvt_pk_bf16_f32 v17, v22, v23
	v_cvt_pk_bf16_f32 v18, v24, v19
	v_cvt_pk_bf16_f32 v19, v25, v26
	v_add_f32_e32 v8, 1.0, v8
	global_store_dwordx4 v[28:29], v[16:19], off offset:256
	v_mul_f32_e32 v12, 0xbfb8aa3b, v12
	v_mul_f32_e32 v14, 0xbfb8aa3b, v14
	v_mul_f32_e32 v15, 0xbfb8aa3b, v15
	v_rcp_f32_e32 v18, v8
	v_add_f32_e32 v8, 1.0, v9
	v_mul_f32_e32 v9, 0xbfb8aa3b, v10
	v_exp_f32_e32 v16, v12
	v_mul_f32_e32 v12, 0xbfb8aa3b, v13
	v_exp_f32_e32 v14, v14
	v_exp_f32_e32 v15, v15
	v_exp_f32_e32 v9, v9
	v_mul_f32_e32 v10, 0xbfb8aa3b, v11
	v_exp_f32_e32 v17, v12
	v_exp_f32_e32 v10, v10
	v_add_f32_e32 v14, 1.0, v14
	v_add_f32_e32 v15, 1.0, v15
	v_rcp_f32_e32 v11, v8
	v_add_f32_e32 v8, 1.0, v9
	v_add_f32_e32 v16, 1.0, v16
	v_add_f32_e32 v17, 1.0, v17
	v_rcp_f32_e32 v14, v14
	v_rcp_f32_e32 v15, v15
	v_rcp_f32_e32 v19, v8
	v_add_f32_e32 v8, 1.0, v10
	v_mul_f32_e32 v0, 0xbfb8aa3b, v0
	v_rcp_f32_e32 v16, v16
	v_rcp_f32_e32 v17, v17
	v_rcp_f32_e32 v20, v8
	v_exp_f32_e32 v0, v0
	v_mul_f32_e32 v1, 0xbfb8aa3b, v1
	v_exp_f32_e32 v1, v1
	s_mov_b32 s1, 0x58000
	v_cvt_pk_bf16_f32 v9, v14, v15
	v_add_co_u32_e32 v14, vcc, s1, v126
	v_cvt_pk_bf16_f32 v8, v16, v17
	v_cvt_pk_bf16_f32 v10, v18, v11
	v_cvt_pk_bf16_f32 v11, v19, v20
	v_addc_co_u32_e32 v15, vcc, 0, v127, vcc
	v_add_f32_e32 v0, 1.0, v0
	global_store_dwordx4 v[14:15], v[8:11], off
	v_mul_f32_e32 v4, 0xbfb8aa3b, v4
	v_mul_f32_e32 v5, 0xbfb8aa3b, v5
	v_rcp_f32_e32 v8, v0
	v_add_f32_e32 v0, 1.0, v1
	v_mul_f32_e32 v1, 0xbfb8aa3b, v2
	v_mul_f32_e32 v6, 0xbfb8aa3b, v6
	v_mul_f32_e32 v7, 0xbfb8aa3b, v7
	v_exp_f32_e32 v1, v1
	v_mul_f32_e32 v2, 0xbfb8aa3b, v3
	v_exp_f32_e32 v4, v4
	v_exp_f32_e32 v5, v5
	v_exp_f32_e32 v6, v6
	v_exp_f32_e32 v7, v7
	v_exp_f32_e32 v2, v2
	v_rcp_f32_e32 v3, v0
	v_add_f32_e32 v0, 1.0, v1
	v_add_f32_e32 v4, 1.0, v4
	v_add_f32_e32 v5, 1.0, v5
	v_add_f32_e32 v6, 1.0, v6
	v_add_f32_e32 v7, 1.0, v7
	v_rcp_f32_e32 v9, v0
	v_add_f32_e32 v0, 1.0, v2
	v_rcp_f32_e32 v4, v4
	v_rcp_f32_e32 v5, v5
	v_rcp_f32_e32 v6, v6
	v_rcp_f32_e32 v7, v7
	v_rcp_f32_e32 v10, v0
	s_mov_b64 s[46:47], 0x58000
	v_lshl_add_u64 v[12:13], v[126:127], 0, s[46:47]
	v_cvt_pk_bf16_f32 v0, v4, v5
	v_cvt_pk_bf16_f32 v1, v6, v7
	v_cvt_pk_bf16_f32 v2, v8, v3
	v_cvt_pk_bf16_f32 v3, v9, v10
	s_and_b64 vcc, exec, s[36:37]
	s_mov_b32 s65, s0
	s_mov_b32 s44, s30
	s_mov_b64 s[48:49], s[40:41]
	s_mov_b64 s[46:47], s[38:39]
	global_store_dwordx4 v[12:13], v[0:3], off offset:256
	s_cbranch_vccz .LBB0_149
	s_waitcnt vmcnt(0)
	v_readlane_b32 s64, v255, 38
	s_cmpk_gt_u32 s53, 0xff
	v_readlane_b32 s65, v255, 39
	s_cbranch_scc1 .LBB0_156
	s_barrier

; #define PG8_STAGE(bufoff, gbase, voff) do { _Pragma("unroll") for (int _i = 0; _i < 2; ++_i) \
;         __builtin_amdgcn_global_load_lds((const unsigned*)((const char*)(gbase) + (voff)[_i]), (PG8_LAS unsigned*)(lds + (bufoff) + ldsw + _i * 8192), 16, 0, 0); } while (0)
; #define PG8_LDA(dst, b, h) do { _Pragma("unroll") for (int m = 0; m < 4; ++m) _Pragma("unroll") for (int k = 0; k < 2; ++k) dst[m][k] = *(const PG8_LAS bf16x8*)(lds + PG8_SA(b, h) + aoff + m * 2048 + k * 1024); } while (0)
; #define PG8_LDB(dst, b, h) do { _Pragma("unroll") for (int n = 0; n < 2; ++n) _Pragma("unroll") for (int k = 0; k < 2; ++k) dst[n][k] = *(const PG8_LAS bf16x8*)(lds + PG8_SB(b, h) + boff + n * 2048 + k * 1024); } while (0)
; #define PG8_MMA(ai, bj, At, Bt) do { __builtin_amdgcn_s_setprio(1); _Pragma("unroll") for (int m = 0; m < 4; ++m) _Pragma("unroll") for (int n = 0; n < 2; ++n) _Pragma("unroll") for (int k = 0; k < 2; ++k) \
;         acc[ai][bj][m][n] = __builtin_amdgcn_mfma_f32_16x16x32_bf16(Bt[n][k], At[m][k], acc[ai][bj][m][n], 0, 0, 0); __builtin_amdgcn_s_setprio(0); } while (0)
; #define PG8_WAIT_L(n) asm volatile("s_waitcnt lgkmcnt(" #n ")" ::: "memory")
; #define PG8_BAR __builtin_amdgcn_s_barrier()
; #define PG8_SCHED __builtin_amdgcn_sched_barrier(0)
; template <class Epi, class Sched>
; __device__ __forceinline__ void gemm_phase(PG8_LAS unsigned char* lds, const Gemm g, const Sched& S, const Epi& E) {
;     ...
;         for (int t = 0; t < nt; t += 2) {
;             const bool last = (t == nt - 2);
;             const char* a1 = cA + (size_t)(t + 1) * kstep;
;             const char* a2 = last ? nA : cA + (size_t)(t + 2) * kstep; const char* b2 = last ? nB : cB + (size_t)(t + 2) * kstep;
;             const char* a3 = a2 + kstep; const char* b3 = b2 + kstep;
;             if (last && has_next) S.a_ready(nxt);
;             PG8_LDB(B0, 0, 0); PG8_SCHED; PG8_LDA(At, 0, 0); PG8_STAGE(PG8_SA(1, 1), a1 + hstep, voffA);
;             PG8_WAIT_L(8); PG8_BAR; PG8_WAIT_L(0); PG8_MMA(0, 0, At, B0); PG8_BAR; PG8_SCHED;
;     ...
; #pragma unroll
;         for (int a = 0; a < 2; ++a)
; #pragma unroll
;             for (int b = 0; b < 2; ++b)
; #pragma unroll
;                 for (int m = 0; m < 4; ++m)
; #pragma unroll
;                     for (int n = 0; n < 2; ++n) acc[a][b][m][n] = (f32x4){0.f, 0.f, 0.f, 0.f};
;         cur = nxt; cA = nA; cB = nB; ++ui;
.LBB0_653:
	v_mov_b64_e32 v[0:1], 0x990
	s_ashr_i32 s43, s42, 31
	v_cmp_lt_i64_e32 vcc, s[44:45], v[0:1]
	s_lshl_b64 s[44:45], s[42:43], 19
	v_readlane_b32 s46, v253, 41
	v_readlane_b32 s47, v253, 42
	s_add_u32 s44, s46, s44
	s_addc_u32 s45, s47, s45
	s_and_b64 s[46:47], vcc, exec
	s_cselect_b32 s43, s45, s1
	s_cselect_b32 s57, s44, s0
	s_ashr_i32 s41, s40, 31
	s_lshl_b64 s[46:47], s[40:41], 19
	v_readlane_b32 s48, v255, 42
	v_readlane_b32 s49, v255, 43
	s_add_u32 s46, s48, s46
	s_addc_u32 s47, s49, s47
	s_and_b64 s[48:49], vcc, exec
	s_cselect_b32 s41, s47, s31
	s_cselect_b32 s58, s46, s30
	s_add_u32 s0, s0, 0x40080
	s_addc_u32 s1, s1, 0
	s_add_u32 s59, s30, 0x100
	v_mov_b32_e32 v0, 0
	s_addc_u32 s60, s31, 0
	s_mov_b32 s61, -2
	v_mov_b32_e32 v1, v0
	v_mov_b32_e32 v2, v0
	v_mov_b32_e32 v3, v0
	v_mov_b32_e32 v8, v0
	v_mov_b32_e32 v9, v0
	v_mov_b32_e32 v10, v0
	v_mov_b32_e32 v11, v0
	v_mov_b32_e32 v16, v0
	v_mov_b32_e32 v17, v0
	v_mov_b32_e32 v18, v0
	v_mov_b32_e32 v19, v0
	v_mov_b32_e32 v24, v0
	v_mov_b32_e32 v25, v0
	v_mov_b32_e32 v26, v0
	v_mov_b32_e32 v27, v0
	v_mov_b32_e32 v32, v0
	v_mov_b32_e32 v33, v0
	v_mov_b32_e32 v34, v0
	v_mov_b32_e32 v35, v0
	v_mov_b32_e32 v40, v0
	v_mov_b32_e32 v41, v0
	v_mov_b32_e32 v42, v0
	v_mov_b32_e32 v43, v0
	v_mov_b32_e32 v48, v0
	v_mov_b32_e32 v49, v0
	v_mov_b32_e32 v50, v0
	v_mov_b32_e32 v51, v0
	v_mov_b32_e32 v56, v0
	v_mov_b32_e32 v57, v0
	v_mov_b32_e32 v58, v0
	v_mov_b32_e32 v59, v0
	v_mov_b32_e32 v4, v0
	v_mov_b32_e32 v5, v0
	v_mov_b32_e32 v6, v0
	v_mov_b32_e32 v7, v0
	v_mov_b32_e32 v12, v0
	v_mov_b32_e32 v13, v0
	v_mov_b32_e32 v14, v0
	v_mov_b32_e32 v15, v0
	v_mov_b32_e32 v20, v0
	v_mov_b32_e32 v21, v0
	v_mov_b32_e32 v22, v0
	v_mov_b32_e32 v23, v0
	v_mov_b32_e32 v28, v0
	v_mov_b32_e32 v29, v0
	v_mov_b32_e32 v30, v0
	v_mov_b32_e32 v31, v0
	v_mov_b32_e32 v36, v0
	v_mov_b32_e32 v37, v0
	v_mov_b32_e32 v38, v0
	v_mov_b32_e32 v39, v0
	v_mov_b32_e32 v44, v0
	v_mov_b32_e32 v45, v0
	v_mov_b32_e32 v46, v0
	v_mov_b32_e32 v47, v0
	v_mov_b32_e32 v52, v0
	v_mov_b32_e32 v53, v0
	v_mov_b32_e32 v54, v0
	v_mov_b32_e32 v55, v0
	v_mov_b32_e32 v60, v0
	v_mov_b32_e32 v61, v0
	v_mov_b32_e32 v62, v0
	v_mov_b32_e32 v63, v0
	v_mov_b32_e32 v64, v0
	v_mov_b32_e32 v65, v0
	v_mov_b32_e32 v66, v0
	v_mov_b32_e32 v67, v0
	v_mov_b32_e32 v72, v0
	v_mov_b32_e32 v73, v0
	v_mov_b32_e32 v74, v0
	v_mov_b32_e32 v75, v0
	v_mov_b32_e32 v80, v0
	v_mov_b32_e32 v81, v0
	v_mov_b32_e32 v82, v0
	v_mov_b32_e32 v83, v0
	v_mov_b32_e32 v88, v0
	v_mov_b32_e32 v89, v0
	v_mov_b32_e32 v90, v0
	v_mov_b32_e32 v91, v0
	v_mov_b32_e32 v98, v0
	v_mov_b32_e32 v99, v0
	v_mov_b32_e32 v100, v0
	v_mov_b32_e32 v101, v0
	v_mov_b32_e32 v106, v0
	v_mov_b32_e32 v107, v0
	v_mov_b32_e32 v108, v0
	v_mov_b32_e32 v109, v0
	v_mov_b32_e32 v114, v0
	v_mov_b32_e32 v115, v0
	v_mov_b32_e32 v116, v0
	v_mov_b32_e32 v117, v0
	v_mov_b32_e32 v122, v0
	v_mov_b32_e32 v123, v0
	v_mov_b32_e32 v124, v0
	v_mov_b32_e32 v125, v0
	v_mov_b32_e32 v68, v0
	v_mov_b32_e32 v69, v0
	v_mov_b32_e32 v70, v0
	v_mov_b32_e32 v71, v0
	v_mov_b32_e32 v76, v0
	v_mov_b32_e32 v77, v0
	v_mov_b32_e32 v78, v0
	v_mov_b32_e32 v79, v0
	v_mov_b32_e32 v84, v0
	v_mov_b32_e32 v85, v0
	v_mov_b32_e32 v86, v0
	v_mov_b32_e32 v87, v0
	v_mov_b32_e32 v92, v0
	v_mov_b32_e32 v93, v0
	v_mov_b32_e32 v94, v0
	v_mov_b32_e32 v95, v0
	v_mov_b32_e32 v102, v0
	v_mov_b32_e32 v103, v0
	v_mov_b32_e32 v104, v0
	v_mov_b32_e32 v105, v0
	v_mov_b32_e32 v110, v0
	v_mov_b32_e32 v111, v0
	v_mov_b32_e32 v112, v0
	v_mov_b32_e32 v113, v0
	v_mov_b32_e32 v118, v0
	v_mov_b32_e32 v119, v0
	v_mov_b32_e32 v120, v0
	v_mov_b32_e32 v121, v0
	v_mov_b32_e32 v126, v0
	v_mov_b32_e32 v127, v0
	v_mov_b32_e32 v128, v0
	v_mov_b32_e32 v129, v0
	v_readfirstlane_b32 s100, v226
	s_nop 3
	s_lshr_b32 s100, s100, 8
	s_cmp_eq_u32 s100, 0
	s_cbranch_scc1 .Lgp_21593
	s_setprio 1
.Lgp_21593:
.LBB0_654:
	s_add_u32 s30, s0, 0xfffc0080
	s_addc_u32 s31, s1, -1
	s_add_i32 s62, 0, 0x10000
	v_add_u32_e32 v96, s62, v162
	ds_read_b128 v[144:147], v96
	ds_read_b128 v[148:151], v96 offset:1024
	ds_read_b128 v[152:155], v96 offset:2048
	ds_read_b128 v[156:159], v96 offset:3072
	s_cmp_eq_u32 s61, 12
	s_cselect_b32 s49, s43, s31
	s_cselect_b32 s48, s57, s30
	s_cselect_b32 s31, s41, s60
	s_cselect_b32 s30, s58, s59
	v_lshl_add_u64 v[160:161], s[0:1], 0, v[140:141]
	s_add_i32 m0, s52, 0xc000
	ds_read_b128 v[170:173], v168
	ds_read_b128 v[174:177], v168 offset:1024
	ds_read_b128 v[178:181], v168 offset:2048
	ds_read_b128 v[182:185], v168 offset:3072
	ds_read_b128 v[186:189], v168 offset:4096
	ds_read_b128 v[190:193], v168 offset:5120
	ds_read_b128 v[194:197], v168 offset:6144
	ds_read_b128 v[198:201], v168 offset:7168
	global_load_lds_dwordx4 v[160:161], off
	v_lshl_add_u64 v[160:161], s[0:1], 0, v[142:143]
	s_add_i32 m0, s52, 0xe000
	s_nop 0
	global_load_lds_dwordx4 v[160:161], off
	s_waitcnt lgkmcnt(8)
	s_barrier
	s_waitcnt lgkmcnt(0)
	s_waitcnt lgkmcnt(0)
	v_mfma_f32_16x16x32_bf16 v[126:129], v[144:147], v[170:173], v[126:129]
	v_mfma_f32_16x16x32_bf16 v[118:121], v[152:155], v[170:173], v[118:121]
	v_mfma_f32_16x16x32_bf16 v[110:113], v[144:147], v[178:181], v[110:113]
	v_mfma_f32_16x16x32_bf16 v[102:105], v[152:155], v[178:181], v[102:105]
	v_mfma_f32_16x16x32_bf16 v[92:95], v[144:147], v[186:189], v[92:95]
	v_mfma_f32_16x16x32_bf16 v[84:87], v[152:155], v[186:189], v[84:87]
	v_mfma_f32_16x16x32_bf16 v[76:79], v[144:147], v[194:197], v[76:79]
	v_mfma_f32_16x16x32_bf16 v[68:71], v[152:155], v[194:197], v[68:71]
	v_mfma_f32_16x16x32_bf16 v[126:129], v[148:151], v[174:177], v[126:129]
	v_mfma_f32_16x16x32_bf16 v[118:121], v[156:159], v[174:177], v[118:121]
	v_mfma_f32_16x16x32_bf16 v[110:113], v[148:151], v[182:185], v[110:113]
	v_mfma_f32_16x16x32_bf16 v[102:105], v[156:159], v[182:185], v[102:105]
	v_mfma_f32_16x16x32_bf16 v[92:95], v[148:151], v[190:193], v[92:95]
	v_mfma_f32_16x16x32_bf16 v[84:87], v[156:159], v[190:193], v[84:87]
	v_mfma_f32_16x16x32_bf16 v[76:79], v[148:151], v[198:201], v[76:79]
	v_mfma_f32_16x16x32_bf16 v[68:71], v[156:159], v[198:201], v[68:71]
	s_barrier
; #define PG8_STAGE(bufoff, gbase, voff) do { _Pragma("unroll") for (int _i = 0; _i < 2; ++_i) \
;         __builtin_amdgcn_global_load_lds((const unsigned*)((const char*)(gbase) + (voff)[_i]), (PG8_LAS unsigned*)(lds + (bufoff) + ldsw + _i * 8192), 16, 0, 0); } while (0)
; #define PG8_LDA(dst, b, h) do { _Pragma("unroll") for (int m = 0; m < 4; ++m) _Pragma("unroll") for (int k = 0; k < 2; ++k) dst[m][k] = *(const PG8_LAS bf16x8*)(lds + PG8_SA(b, h) + aoff + m * 2048 + k * 1024); } while (0)
; #define PG8_LDB(dst, b, h) do { _Pragma("unroll") for (int n = 0; n < 2; ++n) _Pragma("unroll") for (int k = 0; k < 2; ++k) dst[n][k] = *(const PG8_LAS bf16x8*)(lds + PG8_SB(b, h) + boff + n * 2048 + k * 1024); } while (0)
; #define PG8_MMA(ai, bj, At, Bt) do { __builtin_amdgcn_s_setprio(1); _Pragma("unroll") for (int m = 0; m < 4; ++m) _Pragma("unroll") for (int n = 0; n < 2; ++n) _Pragma("unroll") for (int k = 0; k < 2; ++k) \
;         acc[ai][bj][m][n] = __builtin_amdgcn_mfma_f32_16x16x32_bf16(Bt[n][k], At[m][k], acc[ai][bj][m][n], 0, 0, 0); __builtin_amdgcn_s_setprio(0); } while (0)
; #define PG8_WAIT_V(n) asm volatile("s_waitcnt vmcnt(" #n ")" ::: "memory")
; #define PG8_WAIT_L(n) asm volatile("s_waitcnt lgkmcnt(" #n ")" ::: "memory")
; #define PG8_BAR __builtin_amdgcn_s_barrier()
; #define PG8_SCHED __builtin_amdgcn_sched_barrier(0)
; template <class Epi, class Sched>
; __device__ __forceinline__ void gemm_phase(PG8_LAS unsigned char* lds, const Gemm g, const Sched& S, const Epi& E) {
;     ...
;             PG8_LDB(B1, 0, 1); PG8_STAGE(PG8_SB(0, 0), b2, voffB);
;             PG8_BAR; PG8_WAIT_L(0); PG8_MMA(0, 1, At, B1); PG8_BAR;
;             PG8_LDA(At, 0, 1); PG8_STAGE(PG8_SA(0, 0), a2, voffA);
;             PG8_BAR; PG8_WAIT_L(0); PG8_MMA(1, 0, At, B0); PG8_BAR; PG8_SCHED;
;             PG8_STAGE(PG8_SB(0, 1), b2 + hstep, voffB);
;             PG8_WAIT_V(6); PG8_BAR; PG8_MMA(1, 1, At, B1); PG8_BAR;
;             PG8_LDB(B0, 1, 0); PG8_SCHED; PG8_LDA(At, 1, 0); PG8_STAGE(PG8_SA(0, 1), a2 + hstep, voffA);
	s_add_i32 s64, 0, 0x14000
	s_add_i32 s62, s62, s51
	v_add_u32_e32 v96, s64, v162
	v_lshl_add_u64 v[160:161], s[30:31], 0, v[134:135]
	s_mov_b32 m0, s62
	ds_read_b128 v[202:205], v96
	ds_read_b128 v[208:211], v96 offset:1024
	ds_read_b128 v[212:215], v96 offset:2048
	ds_read_b128 v[216:219], v96 offset:3072
	global_load_lds_dwordx4 v[160:161], off
	v_lshl_add_u64 v[220:221], s[30:31], 0, v[130:131]
	s_add_i32 m0, s62, 0x2000
	s_nop 0
	global_load_lds_dwordx4 v[220:221], off
	s_barrier
	s_waitcnt lgkmcnt(0)
	s_waitcnt lgkmcnt(0)
	v_mfma_f32_16x16x32_bf16 v[122:125], v[202:205], v[170:173], v[122:125]
	v_mfma_f32_16x16x32_bf16 v[114:117], v[212:215], v[170:173], v[114:117]
	v_mfma_f32_16x16x32_bf16 v[106:109], v[202:205], v[178:181], v[106:109]
	v_mfma_f32_16x16x32_bf16 v[98:101], v[212:215], v[178:181], v[98:101]
	v_mfma_f32_16x16x32_bf16 v[88:91], v[202:205], v[186:189], v[88:91]
	v_mfma_f32_16x16x32_bf16 v[80:83], v[212:215], v[186:189], v[80:83]
	v_mfma_f32_16x16x32_bf16 v[72:75], v[202:205], v[194:197], v[72:75]
	v_mfma_f32_16x16x32_bf16 v[64:67], v[212:215], v[194:197], v[64:67]
	v_mfma_f32_16x16x32_bf16 v[122:125], v[208:211], v[174:177], v[122:125]
	v_mfma_f32_16x16x32_bf16 v[114:117], v[216:219], v[174:177], v[114:117]
	v_mfma_f32_16x16x32_bf16 v[106:109], v[208:211], v[182:185], v[106:109]
	v_mfma_f32_16x16x32_bf16 v[98:101], v[216:219], v[182:185], v[98:101]
	v_mfma_f32_16x16x32_bf16 v[88:91], v[208:211], v[190:193], v[88:91]
	v_mfma_f32_16x16x32_bf16 v[80:83], v[216:219], v[190:193], v[80:83]
	v_mfma_f32_16x16x32_bf16 v[72:75], v[208:211], v[198:201], v[72:75]
	v_mfma_f32_16x16x32_bf16 v[64:67], v[216:219], v[198:201], v[64:67]
	s_mov_b32 m0, s52
	v_lshl_add_u64 v[222:223], s[48:49], 0, v[136:137]
	s_barrier
	ds_read_b128 v[170:173], v168 offset:16384
	ds_read_b128 v[174:177], v168 offset:17408
	ds_read_b128 v[178:181], v168 offset:18432
	ds_read_b128 v[182:185], v168 offset:19456
	ds_read_b128 v[186:189], v168 offset:20480
	ds_read_b128 v[190:193], v168 offset:21504
	ds_read_b128 v[194:197], v168 offset:22528
	ds_read_b128 v[198:201], v168 offset:23552
	global_load_lds_dwordx4 v[222:223], off
	v_lshl_add_u64 v[224:225], s[48:49], 0, v[132:133]
	s_mov_b32 m0, s53
	s_nop 0
	global_load_lds_dwordx4 v[224:225], off
	s_barrier
	s_waitcnt lgkmcnt(0)
	s_waitcnt lgkmcnt(0)
	v_mfma_f32_16x16x32_bf16 v[60:63], v[144:147], v[170:173], v[60:63]
	v_mfma_f32_16x16x32_bf16 v[52:55], v[152:155], v[170:173], v[52:55]
	v_mfma_f32_16x16x32_bf16 v[44:47], v[144:147], v[178:181], v[44:47]
	v_mfma_f32_16x16x32_bf16 v[36:39], v[152:155], v[178:181], v[36:39]
	v_mfma_f32_16x16x32_bf16 v[28:31], v[144:147], v[186:189], v[28:31]
	v_mfma_f32_16x16x32_bf16 v[20:23], v[152:155], v[186:189], v[20:23]
	v_mfma_f32_16x16x32_bf16 v[12:15], v[144:147], v[194:197], v[12:15]
	v_mfma_f32_16x16x32_bf16 v[4:7], v[152:155], v[194:197], v[4:7]
	v_mfma_f32_16x16x32_bf16 v[60:63], v[148:151], v[174:177], v[60:63]
	v_mfma_f32_16x16x32_bf16 v[52:55], v[156:159], v[174:177], v[52:55]
	v_mfma_f32_16x16x32_bf16 v[44:47], v[148:151], v[182:185], v[44:47]
	v_mfma_f32_16x16x32_bf16 v[36:39], v[156:159], v[182:185], v[36:39]
	v_mfma_f32_16x16x32_bf16 v[28:31], v[148:151], v[190:193], v[28:31]
	v_mfma_f32_16x16x32_bf16 v[20:23], v[156:159], v[190:193], v[20:23]
	v_mfma_f32_16x16x32_bf16 v[12:15], v[148:151], v[198:201], v[12:15]
	v_mfma_f32_16x16x32_bf16 v[4:7], v[156:159], v[198:201], v[4:7]
	s_barrier
	s_add_u32 s62, s30, 0x40000
	s_addc_u32 s63, s31, 0
	s_add_i32 s64, s64, s51
	v_lshl_add_u64 v[144:145], s[62:63], 0, v[134:135]
	s_mov_b32 m0, s64
	s_nop 0
	global_load_lds_dwordx4 v[144:145], off
	v_lshl_add_u64 v[144:145], s[62:63], 0, v[130:131]
	s_add_i32 m0, s64, 0x2000
	s_nop 0
	global_load_lds_dwordx4 v[144:145], off
	s_waitcnt vmcnt(6)
	s_barrier
	v_mfma_f32_16x16x32_bf16 v[56:59], v[202:205], v[170:173], v[56:59]
	v_mfma_f32_16x16x32_bf16 v[48:51], v[212:215], v[170:173], v[48:51]
	v_mfma_f32_16x16x32_bf16 v[40:43], v[202:205], v[178:181], v[40:43]
	v_mfma_f32_16x16x32_bf16 v[32:35], v[212:215], v[178:181], v[32:35]
	v_mfma_f32_16x16x32_bf16 v[24:27], v[202:205], v[186:189], v[24:27]
	v_mfma_f32_16x16x32_bf16 v[16:19], v[212:215], v[186:189], v[16:19]
	v_mfma_f32_16x16x32_bf16 v[8:11], v[202:205], v[194:197], v[8:11]
	v_mfma_f32_16x16x32_bf16 v[0:3], v[212:215], v[194:197], v[0:3]
	v_mfma_f32_16x16x32_bf16 v[56:59], v[208:211], v[174:177], v[56:59]
	v_mfma_f32_16x16x32_bf16 v[48:51], v[216:219], v[174:177], v[48:51]
	v_mfma_f32_16x16x32_bf16 v[40:43], v[208:211], v[182:185], v[40:43]
	v_mfma_f32_16x16x32_bf16 v[32:35], v[216:219], v[182:185], v[32:35]
	v_mfma_f32_16x16x32_bf16 v[24:27], v[208:211], v[190:193], v[24:27]
	v_mfma_f32_16x16x32_bf16 v[16:19], v[216:219], v[190:193], v[16:19]
	v_mfma_f32_16x16x32_bf16 v[8:11], v[208:211], v[198:201], v[8:11]
	v_mfma_f32_16x16x32_bf16 v[0:3], v[216:219], v[198:201], v[0:3]
	s_add_i32 s62, 0, 0x18000
	v_add_u32_e32 v96, s62, v162
	s_barrier
	ds_read_b128 v[144:147], v96
	ds_read_b128 v[148:151], v96 offset:1024
	ds_read_b128 v[152:155], v96 offset:2048
	ds_read_b128 v[156:159], v96 offset:3072
	s_add_u32 s48, s48, 0x40000
	s_addc_u32 s49, s49, 0
	s_mov_b32 m0, s54
	v_lshl_add_u64 v[202:203], s[48:49], 0, v[136:137]
	ds_read_b128 v[170:173], v168 offset:32768
	ds_read_b128 v[174:177], v168 offset:33792
	ds_read_b128 v[178:181], v168 offset:34816
	ds_read_b128 v[182:185], v168 offset:35840
	ds_read_b128 v[186:189], v168 offset:36864
	ds_read_b128 v[190:193], v168 offset:37888
	ds_read_b128 v[194:197], v168 offset:38912
	ds_read_b128 v[198:201], v168 offset:39936
	global_load_lds_dwordx4 v[202:203], off
	v_lshl_add_u64 v[202:203], s[48:49], 0, v[132:133]
	s_mov_b32 m0, s96
	s_nop 0
	global_load_lds_dwordx4 v[202:203], off
	s_waitcnt lgkmcnt(8)
	s_barrier
; #define PG8_STAGE(bufoff, gbase, voff) do { _Pragma("unroll") for (int _i = 0; _i < 2; ++_i) \
;         __builtin_amdgcn_global_load_lds((const unsigned*)((const char*)(gbase) + (voff)[_i]), (PG8_LAS unsigned*)(lds + (bufoff) + ldsw + _i * 8192), 16, 0, 0); } while (0)
; #define PG8_LDA(dst, b, h) do { _Pragma("unroll") for (int m = 0; m < 4; ++m) _Pragma("unroll") for (int k = 0; k < 2; ++k) dst[m][k] = *(const PG8_LAS bf16x8*)(lds + PG8_SA(b, h) + aoff + m * 2048 + k * 1024); } while (0)
; #define PG8_LDB(dst, b, h) do { _Pragma("unroll") for (int n = 0; n < 2; ++n) _Pragma("unroll") for (int k = 0; k < 2; ++k) dst[n][k] = *(const PG8_LAS bf16x8*)(lds + PG8_SB(b, h) + boff + n * 2048 + k * 1024); } while (0)
; #define PG8_MMA(ai, bj, At, Bt) do { __builtin_amdgcn_s_setprio(1); _Pragma("unroll") for (int m = 0; m < 4; ++m) _Pragma("unroll") for (int n = 0; n < 2; ++n) _Pragma("unroll") for (int k = 0; k < 2; ++k) \
;         acc[ai][bj][m][n] = __builtin_amdgcn_mfma_f32_16x16x32_bf16(Bt[n][k], At[m][k], acc[ai][bj][m][n], 0, 0, 0); __builtin_amdgcn_s_setprio(0); } while (0)
; #define PG8_WAIT_L(n) asm volatile("s_waitcnt lgkmcnt(" #n ")" ::: "memory")
; #define PG8_BAR __builtin_amdgcn_s_barrier()
; #define PG8_SCHED __builtin_amdgcn_sched_barrier(0)
; template <class Epi, class Sched>
; __device__ __forceinline__ void gemm_phase(PG8_LAS unsigned char* lds, const Gemm g, const Sched& S, const Epi& E) {
;     ...
;             PG8_WAIT_L(8); PG8_BAR; PG8_WAIT_L(0); PG8_MMA(0, 0, At, B0); PG8_BAR; PG8_SCHED;
;             PG8_LDB(B1, 1, 1); PG8_STAGE(PG8_SB(1, 0), b3, voffB);
;             PG8_BAR; PG8_WAIT_L(0); PG8_MMA(0, 1, At, B1); PG8_BAR;
;             PG8_LDA(At, 1, 1); PG8_STAGE(PG8_SA(1, 0), a3, voffA);
	s_waitcnt lgkmcnt(0)
	s_waitcnt lgkmcnt(0)
	v_mfma_f32_16x16x32_bf16 v[126:129], v[144:147], v[170:173], v[126:129]
	v_mfma_f32_16x16x32_bf16 v[118:121], v[152:155], v[170:173], v[118:121]
	v_mfma_f32_16x16x32_bf16 v[110:113], v[144:147], v[178:181], v[110:113]
	v_mfma_f32_16x16x32_bf16 v[102:105], v[152:155], v[178:181], v[102:105]
	v_mfma_f32_16x16x32_bf16 v[92:95], v[144:147], v[186:189], v[92:95]
	v_mfma_f32_16x16x32_bf16 v[84:87], v[152:155], v[186:189], v[84:87]
	v_mfma_f32_16x16x32_bf16 v[76:79], v[144:147], v[194:197], v[76:79]
	v_mfma_f32_16x16x32_bf16 v[68:71], v[152:155], v[194:197], v[68:71]
	v_mfma_f32_16x16x32_bf16 v[126:129], v[148:151], v[174:177], v[126:129]
	v_mfma_f32_16x16x32_bf16 v[118:121], v[156:159], v[174:177], v[118:121]
	v_mfma_f32_16x16x32_bf16 v[110:113], v[148:151], v[182:185], v[110:113]
	v_mfma_f32_16x16x32_bf16 v[102:105], v[156:159], v[182:185], v[102:105]
	v_mfma_f32_16x16x32_bf16 v[92:95], v[148:151], v[190:193], v[92:95]
	v_mfma_f32_16x16x32_bf16 v[84:87], v[156:159], v[190:193], v[84:87]
	v_mfma_f32_16x16x32_bf16 v[76:79], v[148:151], v[198:201], v[76:79]
	v_mfma_f32_16x16x32_bf16 v[68:71], v[156:159], v[198:201], v[68:71]
	s_barrier
	s_add_i32 s48, 0, 0x1c000
	s_add_i32 s49, s62, s51
	v_add_u32_e32 v96, s48, v162
	v_lshl_add_u64 v[160:161], v[160:161], 0, s[2:3]
	s_mov_b32 m0, s49
	ds_read_b128 v[202:205], v96
	ds_read_b128 v[208:211], v96 offset:1024
	ds_read_b128 v[212:215], v96 offset:2048
	ds_read_b128 v[216:219], v96 offset:3072
	global_load_lds_dwordx4 v[160:161], off
	v_lshl_add_u64 v[160:161], v[220:221], 0, s[2:3]
	s_add_i32 m0, s49, 0x2000
	s_nop 0
	global_load_lds_dwordx4 v[160:161], off
	s_barrier
	s_waitcnt lgkmcnt(0)
	s_waitcnt lgkmcnt(0)
	v_mfma_f32_16x16x32_bf16 v[122:125], v[202:205], v[170:173], v[122:125]
	v_mfma_f32_16x16x32_bf16 v[114:117], v[212:215], v[170:173], v[114:117]
	v_mfma_f32_16x16x32_bf16 v[106:109], v[202:205], v[178:181], v[106:109]
	v_mfma_f32_16x16x32_bf16 v[98:101], v[212:215], v[178:181], v[98:101]
	v_mfma_f32_16x16x32_bf16 v[88:91], v[202:205], v[186:189], v[88:91]
	v_mfma_f32_16x16x32_bf16 v[80:83], v[212:215], v[186:189], v[80:83]
	v_mfma_f32_16x16x32_bf16 v[72:75], v[202:205], v[194:197], v[72:75]
	v_mfma_f32_16x16x32_bf16 v[64:67], v[212:215], v[194:197], v[64:67]
	v_mfma_f32_16x16x32_bf16 v[122:125], v[208:211], v[174:177], v[122:125]
	v_mfma_f32_16x16x32_bf16 v[114:117], v[216:219], v[174:177], v[114:117]
	v_mfma_f32_16x16x32_bf16 v[106:109], v[208:211], v[182:185], v[106:109]
	v_mfma_f32_16x16x32_bf16 v[98:101], v[216:219], v[182:185], v[98:101]
	v_mfma_f32_16x16x32_bf16 v[88:91], v[208:211], v[190:193], v[88:91]
	v_mfma_f32_16x16x32_bf16 v[80:83], v[216:219], v[190:193], v[80:83]
	v_mfma_f32_16x16x32_bf16 v[72:75], v[208:211], v[198:201], v[72:75]
	v_mfma_f32_16x16x32_bf16 v[64:67], v[216:219], v[198:201], v[64:67]
	s_mov_b32 m0, s97
	v_lshl_add_u64 v[160:161], v[222:223], 0, s[2:3]
	s_barrier
	ds_read_b128 v[170:173], v168 offset:49152
	ds_read_b128 v[174:177], v168 offset:50176
	ds_read_b128 v[178:181], v168 offset:51200
	ds_read_b128 v[182:185], v168 offset:52224
	ds_read_b128 v[186:189], v168 offset:53248
	ds_read_b128 v[190:193], v168 offset:54272
	ds_read_b128 v[194:197], v168 offset:55296
	ds_read_b128 v[198:201], v168 offset:56320
	global_load_lds_dwordx4 v[160:161], off
	v_lshl_add_u64 v[160:161], v[224:225], 0, s[2:3]
	s_mov_b32 m0, s50
	s_nop 0
	global_load_lds_dwordx4 v[160:161], off
	s_barrier
; #define PG8_STAGE(bufoff, gbase, voff) do { _Pragma("unroll") for (int _i = 0; _i < 2; ++_i) \
;         __builtin_amdgcn_global_load_lds((const unsigned*)((const char*)(gbase) + (voff)[_i]), (PG8_LAS unsigned*)(lds + (bufoff) + ldsw + _i * 8192), 16, 0, 0); } while (0)
; #define PG8_MMA(ai, bj, At, Bt) do { __builtin_amdgcn_s_setprio(1); _Pragma("unroll") for (int m = 0; m < 4; ++m) _Pragma("unroll") for (int n = 0; n < 2; ++n) _Pragma("unroll") for (int k = 0; k < 2; ++k) \
;         acc[ai][bj][m][n] = __builtin_amdgcn_mfma_f32_16x16x32_bf16(Bt[n][k], At[m][k], acc[ai][bj][m][n], 0, 0, 0); __builtin_amdgcn_s_setprio(0); } while (0)
; #define PG8_WAIT_V(n) asm volatile("s_waitcnt vmcnt(" #n ")" ::: "memory")
; #define PG8_WAIT_L(n) asm volatile("s_waitcnt lgkmcnt(" #n ")" ::: "memory")
; #define PG8_BAR __builtin_amdgcn_s_barrier()
; #define PG8_SCHED __builtin_amdgcn_sched_barrier(0)
; template <class Epi, class Sched>
; __device__ __forceinline__ void gemm_phase(PG8_LAS unsigned char* lds, const Gemm g, const Sched& S, const Epi& E) {
;     ...
;             PG8_BAR; PG8_WAIT_L(0); PG8_MMA(1, 0, At, B0); PG8_BAR; PG8_SCHED;
;             PG8_STAGE(PG8_SB(1, 1), b3 + hstep, voffB);
;             PG8_WAIT_V(6); PG8_BAR; PG8_MMA(1, 1, At, B1); PG8_BAR;
;         }
;   DEV void operator()(const f32x4 (&acc)[2][2][4][2], const pg8::Unit& u, int wr, int wc, int fr, int fq) const {
;     ...
;     } else {
; #pragma unroll
;       for (int ai = 0; ai < 2; ++ai)
; #pragma unroll
;         for (int m = 0; m < 4; ++m) {
;           const int row = row0 + ai * 128 + m * 16;
; #pragma unroll
;           for (int bj = 0; bj < 2; ++bj) {
;             const int c = (pn - 10) * 256 + bj * 128 + cl;
;             if (c < 1920) {
;               u32x4 o;
;               o[0] = pk2(acc[ai][bj][m][0][0], acc[ai][bj][m][0][1]); o[1] = pk2(acc[ai][bj][m][0][2], acc[ai][bj][m][0][3]);
;               o[2] = pk2(acc[ai][bj][m][1][0], acc[ai][bj][m][1][1]); o[3] = pk2(acc[ai][bj][m][1][2], acc[ai][bj][m][1][3]);
;               *(u32x4*)(ZRW + (size_t)row * 1920 + c) = o;
	s_waitcnt lgkmcnt(0)
	s_waitcnt lgkmcnt(0)
	v_mfma_f32_16x16x32_bf16 v[60:63], v[144:147], v[170:173], v[60:63]
	v_mfma_f32_16x16x32_bf16 v[52:55], v[152:155], v[170:173], v[52:55]
	v_mfma_f32_16x16x32_bf16 v[44:47], v[144:147], v[178:181], v[44:47]
	v_mfma_f32_16x16x32_bf16 v[36:39], v[152:155], v[178:181], v[36:39]
	v_mfma_f32_16x16x32_bf16 v[28:31], v[144:147], v[186:189], v[28:31]
	v_mfma_f32_16x16x32_bf16 v[20:23], v[152:155], v[186:189], v[20:23]
	v_mfma_f32_16x16x32_bf16 v[12:15], v[144:147], v[194:197], v[12:15]
	v_mfma_f32_16x16x32_bf16 v[4:7], v[152:155], v[194:197], v[4:7]
	v_mfma_f32_16x16x32_bf16 v[60:63], v[148:151], v[174:177], v[60:63]
	v_mfma_f32_16x16x32_bf16 v[52:55], v[156:159], v[174:177], v[52:55]
	v_mfma_f32_16x16x32_bf16 v[44:47], v[148:151], v[182:185], v[44:47]
	v_mfma_f32_16x16x32_bf16 v[36:39], v[156:159], v[182:185], v[36:39]
	v_mfma_f32_16x16x32_bf16 v[28:31], v[148:151], v[190:193], v[28:31]
	v_mfma_f32_16x16x32_bf16 v[20:23], v[156:159], v[190:193], v[20:23]
	v_mfma_f32_16x16x32_bf16 v[12:15], v[148:151], v[198:201], v[12:15]
	v_mfma_f32_16x16x32_bf16 v[4:7], v[156:159], v[198:201], v[4:7]
	s_barrier
	s_add_u32 s30, s30, 0x40080
	s_addc_u32 s31, s31, 0
	s_add_i32 s48, s48, s51
	v_lshl_add_u64 v[144:145], s[30:31], 0, v[134:135]
	s_mov_b32 m0, s48
	s_nop 0
	global_load_lds_dwordx4 v[144:145], off
	v_lshl_add_u64 v[144:145], s[30:31], 0, v[130:131]
	s_add_i32 m0, s48, 0x2000
	s_nop 0
	global_load_lds_dwordx4 v[144:145], off
	s_waitcnt vmcnt(6)
	s_barrier
	v_mfma_f32_16x16x32_bf16 v[56:59], v[202:205], v[170:173], v[56:59]
	v_mfma_f32_16x16x32_bf16 v[48:51], v[212:215], v[170:173], v[48:51]
	v_mfma_f32_16x16x32_bf16 v[40:43], v[202:205], v[178:181], v[40:43]
	v_mfma_f32_16x16x32_bf16 v[32:35], v[212:215], v[178:181], v[32:35]
	v_mfma_f32_16x16x32_bf16 v[24:27], v[202:205], v[186:189], v[24:27]
	v_mfma_f32_16x16x32_bf16 v[16:19], v[212:215], v[186:189], v[16:19]
	v_mfma_f32_16x16x32_bf16 v[8:11], v[202:205], v[194:197], v[8:11]
	v_mfma_f32_16x16x32_bf16 v[0:3], v[212:215], v[194:197], v[0:3]
	v_mfma_f32_16x16x32_bf16 v[56:59], v[208:211], v[174:177], v[56:59]
	v_mfma_f32_16x16x32_bf16 v[48:51], v[216:219], v[174:177], v[48:51]
	v_mfma_f32_16x16x32_bf16 v[40:43], v[208:211], v[182:185], v[40:43]
	v_mfma_f32_16x16x32_bf16 v[32:35], v[216:219], v[182:185], v[32:35]
	v_mfma_f32_16x16x32_bf16 v[24:27], v[208:211], v[190:193], v[24:27]
	v_mfma_f32_16x16x32_bf16 v[16:19], v[216:219], v[190:193], v[16:19]
	v_mfma_f32_16x16x32_bf16 v[8:11], v[208:211], v[198:201], v[8:11]
	v_mfma_f32_16x16x32_bf16 v[0:3], v[216:219], v[198:201], v[0:3]
	s_add_i32 s61, s61, 2
	s_add_u32 s0, s0, 0x100
	s_addc_u32 s1, s1, 0
	s_add_u32 s59, s59, 0x100
	s_addc_u32 s60, s60, 0
	s_cmp_gt_u32 s61, 13
	s_barrier
	s_cbranch_scc0 .LBB0_654
	s_lshl_b32 s41, s56, 8
	s_add_i32 s41, s41, s79
	v_readlane_b32 s60, v255, 32
	v_readlane_b32 s64, v255, 38
	v_or_b32_e32 v144, s41, v139
	s_cmp_gt_i32 s37, 3
	s_mov_b64 s[0:1], -1
	v_readlane_b32 s61, v255, 33
	v_readlane_b32 s65, v255, 39
	s_movk_i32 s56, 0x2000
	s_cbranch_scc0 .LBB0_729
	s_cmp_gt_u32 s37, 7
	s_cbranch_scc0 .LBB0_694
	s_lshl_b32 s43, s37, 8
	s_cmp_lt_u32 s37, 10
	s_cbranch_scc1 .LBB0_691
	s_movk_i32 s0, 0xf00
	v_mad_i64_i32 v[146:147], s[0:1], v144, s0, 0
	v_add_u32_e32 v96, s43, v163
	s_movk_i32 s0, 0x780
	v_cmp_gt_i32_e32 vcc, s0, v96
	v_readlane_b32 s0, v251, 49
	v_readlane_b32 s1, v251, 50
	s_nop 1
	v_lshl_add_u64 v[146:147], s[0:1], 0, v[146:147]
	s_and_saveexec_b64 s[0:1], vcc
	s_cbranch_execz .LBB0_660
	v_cvt_pk_bf16_f32 v148, v126, v127
	v_cvt_pk_bf16_f32 v149, v128, v129
	v_cvt_pk_bf16_f32 v150, v118, v119
	v_cvt_pk_bf16_f32 v151, v120, v121
	v_lshl_add_u64 v[152:153], v[96:97], 1, v[146:147]
	global_store_dwordx4 v[152:153], v[148:151], off

; __global__ void __launch_bounds__(512) fwd_megakernel(Params p, int ph_lo, int ph_hi) {
;     ...
;   for (int ph = ph_lo; ph < ph_hi; ++ph) {
;     if (ph == 0) {
;       cvt_phase(p, 0, smem);
;       mod_phase(p, smem);
;     } else if (ph == N_PHASES - 1) {
;       final_phase(p);
;     } else {
;       const int l = (ph - 1) / 12, sp = (ph - 1) % 12;
;       const int nrows = (l == 1) ? T_LAT : T_ALL;
;       switch (sp) {
;         case 0:
;           if (l > 0) cvt_phase(p, l, smem);
;           norm_phase(p, l, 0, (bf16_t*)(p.ws + O_H0), l == 0);
;           break;
;         case 1: gemm_in_phase(p, smem); break;
;         case 2: branch_phase(p, l, smem); break;
;         case 3:
;           lora64_phase(p, l, smem);
;           lora_phase(p, l, smem, true);
;           break;
;         case 4: scan_phase(p, l, smem); break;
;         case 5:
;           post_phase(p, l, nrows);
;           norm_phase(p, l, 0, (bf16_t*)(p.ws + O_HM), l == 0, nrows);
;           break;
;         case 6: gate_phase(p, nrows, smem); break;
;         case 7: merge_phase(p, nrows, smem); break;
;         case 8: resid_gemm_phase(p, l, (const bf16_t*)(p.ws + O_M), 1024, (const bf16_t*)(p.ws + O_WB + W_WOUT), 2048, nrows, smem, l == 0); break;
;         case 9: norm_phase(p, l, 1, (bf16_t*)(p.ws + O_HM), false, nrows); break;
;         case 10: mlp1_phase(p, nrows, smem); break;
;         case 11: resid_gemm_phase(p, l, (const bf16_t*)(p.ws + O_HID), 4096, (const bf16_t*)(p.ws + O_WB + W_W2), 5120, nrows, smem); break;
;       }
;     }
;     if (ph + 1 < ph_hi) xcd_barrier(xb);
;   }
.LBB0_790:
	s_setprio 0
	s_add_i32 s58, s58, 1
	s_cmp_ge_i32 s58, s59
	s_mov_b64 s[0:1], -1
	s_cbranch_scc0 .LBB0_791
	s_getpc_b64 s[98:99]
